# all per-phase s_setprio flips removed; one static s_setprio 1 for waves 4-7 at kernel entry
# baseline (speedup 1.0000x reference)
; #define LAS __attribute__((address_space(3)))
; __device__ __forceinline__ ArgsP get_args() { ArgsP p = (ArgsP)__builtin_amdgcn_kernarg_segment_ptr(); asm volatile("" : "+s"(p)); return p; }
; __device__ __forceinline__ int get_tid() { int t = __builtin_amdgcn_workitem_id_x(); asm volatile("" : "+v"(t)); return t; }
; __device__ __forceinline__ unsigned xb_add(unsigned* p, unsigned v) { return __hip_atomic_fetch_add(p, v, __ATOMIC_RELAXED, __HIP_MEMORY_SCOPE_AGENT); }
; __device__ __forceinline__ unsigned xb_xcc_id() { return (unsigned)__builtin_amdgcn_s_getreg((3 << 11) | 20) & 0xFu; }
; __global__ void __launch_bounds__(512, 2) mega(Args a_unused) {
;     extern __shared__ __attribute__((aligned(16))) unsigned char lds_raw[];
;     LAS unsigned char* lds = (LAS unsigned char*)lds_raw;
;     ...
;     { volatile LAS unsigned* st_ = (volatile LAS unsigned*)(lds + 151 * 1024); unsigned* bar_ = (unsigned*)(get_args()->ws + WS_CTL) + CW_BAR; const unsigned xid_ = xb_xcc_id();
;       if (get_tid() == 0) { st_[0] = 0u; st_[1] = 0u; (void)xb_add(bar_ + XB_XCNT(xid_), 1u); } __syncthreads(); }
_Z4mega4Args:
	v_readfirstlane_b32 s98, v0
	s_nop 3
	s_and_b32 s98, s98, 0x3ff
	s_cmp_ge_u32 s98, 0x100
	s_cbranch_scc0 .Lmy_noprio
	s_setprio 1
.Lmy_noprio:
	v_and_b32_e32 v206, 0x3ff, v0
	s_mov_b64 s[4:5], s[0:1]
	v_mov_b32_e32 v1, v206
	s_mov_b32 s8, s2
	s_getreg_b32 s9, hwreg(HW_REG_XCC_ID, 0, 4)
	s_nop 0
	v_cmp_eq_u32_e32 vcc, 0, v1
	s_and_saveexec_b64 s[2:3], vcc
	s_cbranch_execz .LBB0_3
	s_add_i32 s10, 0, 0x25c00
	v_mov_b32_e32 v1, 0
	v_mov_b32_e32 v2, s10
	s_add_i32 s10, 0, 0x25c04
	s_mov_b64 s[6:7], exec
	ds_write_b32 v2, v1
	v_mov_b32_e32 v2, s10
	ds_write_b32 v2, v1
	v_mbcnt_lo_u32_b32 v1, s6, 0
	v_mbcnt_hi_u32_b32 v1, s7, v1
	v_cmp_eq_u32_e32 vcc, 0, v1
	s_and_b64 s[10:11], exec, vcc
	s_mov_b64 exec, s[10:11]
	s_cbranch_execz .LBB0_3
	s_load_dwordx2 s[4:5], s[4:5], 0xd0
	s_lshl_b32 s9, s9, 8
	s_and_b32 s9, s9, 0xf00
	v_mov_b32_e32 v1, 0x4000
	s_waitcnt lgkmcnt(0)
	s_add_u32 s4, s4, s9
	s_addc_u32 s5, s5, 0
	s_bcnt1_i32_b64 s6, s[6:7]
	v_mov_b32_e32 v2, s6
	global_atomic_add v1, v2, s[4:5] offset:1024

; #define PG8_STAGE(bufoff, gbase, voff) do { _Pragma("unroll") for (int _i = 0; _i < 2; ++_i) \
;         __builtin_amdgcn_global_load_lds((const unsigned*)((const char*)(gbase) + (voff)[_i]), (LAS unsigned*)(lds + (bufoff) + ldsw + _i * 8192), 16, 0, 0); } while (0)
; #define PG8_LDA(dst, b, h) do { _Pragma("unroll") for (int m = 0; m < 4; ++m) _Pragma("unroll") for (int k = 0; k < 2; ++k) dst[m][k] = *(const LAS bf16x8*)(lds + PG8_SA(b, h) + aoff + m * 2048 + k * 1024); } while (0)
; #define PG8_LDB(dst, b, h) do { _Pragma("unroll") for (int n = 0; n < 2; ++n) _Pragma("unroll") for (int k = 0; k < 2; ++k) dst[n][k] = *(const LAS bf16x8*)(lds + PG8_SB(b, h) + boff + n * 2048 + k * 1024); } while (0)
; #define PG8_WAIT_V(n) asm volatile("s_waitcnt vmcnt(" #n ")" ::: "memory")
; #define PG8_WAIT_L(n) asm volatile("s_waitcnt lgkmcnt(" #n ")" ::: "memory")
; template <class Epi, bool HAS_MID>
; __device__ __forceinline__ void gemm_phase(LAS unsigned char* lds, const Gemm g, const Sched& S, const Epi& E) {
;     ...
;         for (int t = 0; t < nt; t += 2) {
;             const bool last = (t == nt - 2);
;             const char* a1 = PG8_APT(t + 1);
;             const char* a2 = last ? nA : PG8_APT(t + 2); const char* b2 = last ? nB : cB + (size_t)(t + 2) * kstep;
;             const char* a3 = a2 + kstep; const char* b3 = b2 + kstep;
;             PG8_LDB(B0, 0, 0); PG8_LDB(B1, 0, 1); PG8_SCHED; PG8_LDA(At, 0, 0); PG8_STAGE(PG8_SA(1, 1), a1 + hstepA, voffA);
;             PG8_WAIT_V(8); PG8_WAIT_L(0); PG8_BAR; PG8_MMA(0, 0, At, B0); PG8_MMA(0, 1, At, B1); PG8_BAR; PG8_SCHED;
;             PG8_LDA(At, 0, 1); PG8_STAGE(PG8_SB(0, 0), b2, voffB); PG8_STAGE(PG8_SB(0, 1), b2 + hstepB, voffB); PG8_STAGE(PG8_SA(0, 0), a2, voffA);
;             PG8_WAIT_V(8); PG8_WAIT_L(0); PG8_BAR; PG8_MMA(1, 0, At, B0); PG8_MMA(1, 1, At, B1); PG8_BAR; PG8_SCHED;
;             PG8_LDB(B0, 1, 0); PG8_LDB(B1, 1, 1); PG8_SCHED; PG8_LDA(At, 1, 0); PG8_STAGE(PG8_SA(0, 1), a2 + hstepA, voffA);
;             PG8_WAIT_V(8); PG8_WAIT_L(0); PG8_BAR; PG8_MMA(0, 0, At, B0); PG8_MMA(0, 1, At, B1); PG8_BAR; PG8_SCHED;
;             PG8_LDA(At, 1, 1); PG8_STAGE(PG8_SB(1, 0), b3, voffB); PG8_STAGE(PG8_SB(1, 1), b3 + hstepB, voffB); PG8_STAGE(PG8_SA(1, 0), a3, voffA);
;             PG8_WAIT_V(8); PG8_WAIT_L(0); PG8_BAR; PG8_MMA(1, 0, At, B0); PG8_MMA(1, 1, At, B1); PG8_BAR; PG8_SCHED;
.LBB0_709:
	s_add_u32 s64, s80, 0xfff80080
	s_addc_u32 s65, s81, -1
	s_add_i32 s30, 0, 0x10000
	s_cmp_eq_u32 vcc_hi, 28
	s_cselect_b32 s85, s7, s65
	s_cselect_b32 s84, s10, s64
	v_add_u32_e32 v140, s30, v144
	s_cselect_b32 s83, s71, vcc_lo
	s_cselect_b32 s82, s73, s79
	s_add_i32 s36, 0, 0x14000
	ds_read_b128 v[148:151], v140
	ds_read_b128 v[152:155], v140 offset:1024
	ds_read_b128 v[156:159], v140 offset:2048
	ds_read_b128 v[164:167], v140 offset:3072
	v_add_u32_e32 v140, s36, v144
	ds_read_b128 v[168:171], v140
	ds_read_b128 v[172:175], v140 offset:1024
	ds_read_b128 v[176:179], v140 offset:2048
	ds_read_b128 v[180:183], v140 offset:3072
	v_lshl_add_u64 v[140:141], s[80:81], 0, v[138:139]
	s_add_i32 m0, s52, 0xc000
	ds_read_b128 v[184:187], v146
	ds_read_b128 v[188:191], v146 offset:1024
	ds_read_b128 v[192:195], v146 offset:2048
	ds_read_b128 v[196:199], v146 offset:3072
	ds_read_b128 v[200:203], v146 offset:4096
	ds_read_b128 v[216:219], v146 offset:5120
	ds_read_b128 v[220:223], v146 offset:6144
	ds_read_b128 v[224:227], v146 offset:7168
	global_load_lds_dwordx4 v[140:141], off
	v_lshl_add_u64 v[140:141], s[80:81], 0, v[136:137]
	s_add_i32 m0, s52, 0xe000
	s_nop 0
	global_load_lds_dwordx4 v[140:141], off
	s_waitcnt vmcnt(8)
	s_waitcnt lgkmcnt(0)
	s_barrier
	s_waitcnt lgkmcnt(0)
	v_mfma_f32_16x16x32_bf16 v[124:127], v[148:151], v[184:187], v[124:127]
	v_mfma_f32_16x16x32_bf16 v[120:123], v[156:159], v[184:187], v[120:123]
	v_mfma_f32_16x16x32_bf16 v[108:111], v[148:151], v[192:195], v[108:111]
	v_mfma_f32_16x16x32_bf16 v[104:107], v[156:159], v[192:195], v[104:107]
	v_mfma_f32_16x16x32_bf16 v[92:95], v[148:151], v[200:203], v[92:95]
	v_mfma_f32_16x16x32_bf16 v[88:91], v[156:159], v[200:203], v[88:91]
	v_mfma_f32_16x16x32_bf16 v[76:79], v[148:151], v[220:223], v[76:79]
	v_mfma_f32_16x16x32_bf16 v[72:75], v[156:159], v[220:223], v[72:75]
	v_mfma_f32_16x16x32_bf16 v[124:127], v[152:155], v[188:191], v[124:127]
	v_mfma_f32_16x16x32_bf16 v[120:123], v[164:167], v[188:191], v[120:123]
	v_mfma_f32_16x16x32_bf16 v[108:111], v[152:155], v[196:199], v[108:111]
	v_mfma_f32_16x16x32_bf16 v[104:107], v[164:167], v[196:199], v[104:107]
	v_mfma_f32_16x16x32_bf16 v[92:95], v[152:155], v[216:219], v[92:95]
	v_mfma_f32_16x16x32_bf16 v[88:91], v[164:167], v[216:219], v[88:91]
	v_mfma_f32_16x16x32_bf16 v[76:79], v[152:155], v[224:227], v[76:79]
	v_mfma_f32_16x16x32_bf16 v[72:75], v[164:167], v[224:227], v[72:75]
	v_mfma_f32_16x16x32_bf16 v[116:119], v[168:171], v[184:187], v[116:119]
	v_mfma_f32_16x16x32_bf16 v[112:115], v[176:179], v[184:187], v[112:115]
	v_mfma_f32_16x16x32_bf16 v[100:103], v[168:171], v[192:195], v[100:103]
	v_mfma_f32_16x16x32_bf16 v[96:99], v[176:179], v[192:195], v[96:99]
	v_mfma_f32_16x16x32_bf16 v[84:87], v[168:171], v[200:203], v[84:87]
	v_mfma_f32_16x16x32_bf16 v[80:83], v[176:179], v[200:203], v[80:83]
	v_mfma_f32_16x16x32_bf16 v[68:71], v[168:171], v[220:223], v[68:71]
	v_mfma_f32_16x16x32_bf16 v[64:67], v[176:179], v[220:223], v[64:67]
	v_mfma_f32_16x16x32_bf16 v[116:119], v[172:175], v[188:191], v[116:119]
	v_mfma_f32_16x16x32_bf16 v[112:115], v[180:183], v[188:191], v[112:115]
	v_mfma_f32_16x16x32_bf16 v[100:103], v[172:175], v[196:199], v[100:103]
	v_mfma_f32_16x16x32_bf16 v[96:99], v[180:183], v[196:199], v[96:99]
	v_mfma_f32_16x16x32_bf16 v[84:87], v[172:175], v[216:219], v[84:87]
	v_mfma_f32_16x16x32_bf16 v[80:83], v[180:183], v[216:219], v[80:83]
	v_mfma_f32_16x16x32_bf16 v[68:71], v[172:175], v[224:227], v[68:71]
	v_mfma_f32_16x16x32_bf16 v[64:67], v[180:183], v[224:227], v[64:67]
	s_barrier
	s_add_i32 s30, s30, s51
	v_lshl_add_u64 v[140:141], s[82:83], 0, v[160:161]
	s_mov_b32 m0, s30
	ds_read_b128 v[184:187], v146 offset:16384
	ds_read_b128 v[188:191], v146 offset:17408
	ds_read_b128 v[192:195], v146 offset:18432
	ds_read_b128 v[196:199], v146 offset:19456
	ds_read_b128 v[200:203], v146 offset:20480
	ds_read_b128 v[216:219], v146 offset:21504
	ds_read_b128 v[220:223], v146 offset:22528
	ds_read_b128 v[224:227], v146 offset:23552
	global_load_lds_dwordx4 v[140:141], off
	s_add_i32 m0, s30, 0x2000
	s_add_u32 s64, s82, 0x80000
	v_lshl_add_u64 v[204:205], s[82:83], 0, v[132:133]
	s_addc_u32 s65, s83, 0
	s_add_i32 s30, s36, s51
	global_load_lds_dwordx4 v[204:205], off
	v_lshl_add_u64 v[208:209], s[64:65], 0, v[160:161]
	s_mov_b32 m0, s30
	v_lshl_add_u64 v[210:211], s[84:85], 0, v[130:131]
	global_load_lds_dwordx4 v[208:209], off
	v_lshl_add_u64 v[208:209], s[64:65], 0, v[132:133]
	s_add_i32 m0, s30, 0x2000
	s_nop 0
	global_load_lds_dwordx4 v[208:209], off
	v_lshl_add_u64 v[208:209], s[84:85], 0, v[128:129]
	s_mov_b32 m0, s52
	s_nop 0
	global_load_lds_dwordx4 v[208:209], off
	s_mov_b32 m0, s57
	s_nop 0
	global_load_lds_dwordx4 v[210:211], off
	s_waitcnt vmcnt(8)
	s_waitcnt lgkmcnt(0)
	s_barrier
; #define PG8_STAGE(bufoff, gbase, voff) do { _Pragma("unroll") for (int _i = 0; _i < 2; ++_i) \
;         __builtin_amdgcn_global_load_lds((const unsigned*)((const char*)(gbase) + (voff)[_i]), (LAS unsigned*)(lds + (bufoff) + ldsw + _i * 8192), 16, 0, 0); } while (0)
; #define PG8_LDA(dst, b, h) do { _Pragma("unroll") for (int m = 0; m < 4; ++m) _Pragma("unroll") for (int k = 0; k < 2; ++k) dst[m][k] = *(const LAS bf16x8*)(lds + PG8_SA(b, h) + aoff + m * 2048 + k * 1024); } while (0)
; #define PG8_LDB(dst, b, h) do { _Pragma("unroll") for (int n = 0; n < 2; ++n) _Pragma("unroll") for (int k = 0; k < 2; ++k) dst[n][k] = *(const LAS bf16x8*)(lds + PG8_SB(b, h) + boff + n * 2048 + k * 1024); } while (0)
; #define PG8_MMA(ai, bj, At, Bt) do { __builtin_amdgcn_s_setprio(1); _Pragma("unroll") for (int m = 0; m < 4; ++m) _Pragma("unroll") for (int n = 0; n < 2; ++n) _Pragma("unroll") for (int k = 0; k < 2; ++k) \
;         acc[ai][bj][m][n] = __builtin_amdgcn_mfma_f32_16x16x32_bf16(Bt[n][k], At[m][k], acc[ai][bj][m][n], 0, 0, 0); __builtin_amdgcn_s_setprio(0); } while (0)
; #define PG8_WAIT_V(n) asm volatile("s_waitcnt vmcnt(" #n ")" ::: "memory")
; #define PG8_WAIT_L(n) asm volatile("s_waitcnt lgkmcnt(" #n ")" ::: "memory")
; #define PG8_BAR __builtin_amdgcn_s_barrier()
; #define PG8_SCHED __builtin_amdgcn_sched_barrier(0)
; template <class Epi, bool HAS_MID>
; __device__ __forceinline__ void gemm_phase(LAS unsigned char* lds, const Gemm g, const Sched& S, const Epi& E) {
;     ...
;             PG8_WAIT_V(8); PG8_WAIT_L(0); PG8_BAR; PG8_MMA(1, 0, At, B0); PG8_MMA(1, 1, At, B1); PG8_BAR; PG8_SCHED;
;             PG8_LDB(B0, 1, 0); PG8_LDB(B1, 1, 1); PG8_SCHED; PG8_LDA(At, 1, 0); PG8_STAGE(PG8_SA(0, 1), a2 + hstepA, voffA);
;             PG8_WAIT_V(8); PG8_WAIT_L(0); PG8_BAR; PG8_MMA(0, 0, At, B0); PG8_MMA(0, 1, At, B1); PG8_BAR; PG8_SCHED;
;             PG8_LDA(At, 1, 1); PG8_STAGE(PG8_SB(1, 0), b3, voffB); PG8_STAGE(PG8_SB(1, 1), b3 + hstepB, voffB); PG8_STAGE(PG8_SA(1, 0), a3, voffA);
	s_waitcnt lgkmcnt(0)
	v_mfma_f32_16x16x32_bf16 v[60:63], v[148:151], v[184:187], v[60:63]
	v_mfma_f32_16x16x32_bf16 v[56:59], v[156:159], v[184:187], v[56:59]
	v_mfma_f32_16x16x32_bf16 v[44:47], v[148:151], v[192:195], v[44:47]
	v_mfma_f32_16x16x32_bf16 v[40:43], v[156:159], v[192:195], v[40:43]
	v_mfma_f32_16x16x32_bf16 v[28:31], v[148:151], v[200:203], v[28:31]
	v_mfma_f32_16x16x32_bf16 v[24:27], v[156:159], v[200:203], v[24:27]
	v_mfma_f32_16x16x32_bf16 v[12:15], v[148:151], v[220:223], v[12:15]
	v_mfma_f32_16x16x32_bf16 v[8:11], v[156:159], v[220:223], v[8:11]
	v_mfma_f32_16x16x32_bf16 v[60:63], v[152:155], v[188:191], v[60:63]
	v_mfma_f32_16x16x32_bf16 v[56:59], v[164:167], v[188:191], v[56:59]
	v_mfma_f32_16x16x32_bf16 v[44:47], v[152:155], v[196:199], v[44:47]
	v_mfma_f32_16x16x32_bf16 v[40:43], v[164:167], v[196:199], v[40:43]
	v_mfma_f32_16x16x32_bf16 v[28:31], v[152:155], v[216:219], v[28:31]
	v_mfma_f32_16x16x32_bf16 v[24:27], v[164:167], v[216:219], v[24:27]
	v_mfma_f32_16x16x32_bf16 v[12:15], v[152:155], v[224:227], v[12:15]
	v_mfma_f32_16x16x32_bf16 v[8:11], v[164:167], v[224:227], v[8:11]
	v_mfma_f32_16x16x32_bf16 v[52:55], v[168:171], v[184:187], v[52:55]
	v_mfma_f32_16x16x32_bf16 v[48:51], v[176:179], v[184:187], v[48:51]
	v_mfma_f32_16x16x32_bf16 v[36:39], v[168:171], v[192:195], v[36:39]
	v_mfma_f32_16x16x32_bf16 v[32:35], v[176:179], v[192:195], v[32:35]
	v_mfma_f32_16x16x32_bf16 v[20:23], v[168:171], v[200:203], v[20:23]
	v_mfma_f32_16x16x32_bf16 v[16:19], v[176:179], v[200:203], v[16:19]
	v_mfma_f32_16x16x32_bf16 v[4:7], v[168:171], v[220:223], v[4:7]
	v_mfma_f32_16x16x32_bf16 v[0:3], v[176:179], v[220:223], v[0:3]
	v_mfma_f32_16x16x32_bf16 v[52:55], v[172:175], v[188:191], v[52:55]
	v_mfma_f32_16x16x32_bf16 v[48:51], v[180:183], v[188:191], v[48:51]
	v_mfma_f32_16x16x32_bf16 v[36:39], v[172:175], v[196:199], v[36:39]
	v_mfma_f32_16x16x32_bf16 v[32:35], v[180:183], v[196:199], v[32:35]
	v_mfma_f32_16x16x32_bf16 v[20:23], v[172:175], v[216:219], v[20:23]
	v_mfma_f32_16x16x32_bf16 v[16:19], v[180:183], v[216:219], v[16:19]
	v_mfma_f32_16x16x32_bf16 v[4:7], v[172:175], v[224:227], v[4:7]
	v_mfma_f32_16x16x32_bf16 v[0:3], v[180:183], v[224:227], v[0:3]
	s_barrier
	s_add_i32 s30, 0, 0x18000
	v_add_u32_e32 v147, s30, v144
	s_add_i32 s36, 0, 0x1c000
	ds_read_b128 v[148:151], v147
	ds_read_b128 v[152:155], v147 offset:1024
	ds_read_b128 v[156:159], v147 offset:2048
	ds_read_b128 v[164:167], v147 offset:3072
	v_add_u32_e32 v147, s36, v144
	ds_read_b128 v[168:171], v147
	ds_read_b128 v[172:175], v147 offset:1024
	ds_read_b128 v[176:179], v147 offset:2048
	ds_read_b128 v[180:183], v147 offset:3072
	s_add_u32 s64, s84, 0x80000
	s_addc_u32 s65, s85, 0
	s_mov_b32 m0, s59
	v_lshl_add_u64 v[228:229], s[64:65], 0, v[128:129]
	ds_read_b128 v[184:187], v146 offset:32768
	ds_read_b128 v[188:191], v146 offset:33792
	ds_read_b128 v[192:195], v146 offset:34816
	ds_read_b128 v[196:199], v146 offset:35840
	ds_read_b128 v[200:203], v146 offset:36864
	ds_read_b128 v[216:219], v146 offset:37888
	ds_read_b128 v[220:223], v146 offset:38912
	ds_read_b128 v[224:227], v146 offset:39936
	global_load_lds_dwordx4 v[228:229], off
	v_lshl_add_u64 v[228:229], s[64:65], 0, v[130:131]
	s_mov_b32 m0, s60
	s_nop 0
	global_load_lds_dwordx4 v[228:229], off
	s_waitcnt vmcnt(8)
	s_waitcnt lgkmcnt(0)
	s_barrier
	s_waitcnt lgkmcnt(0)
	v_mfma_f32_16x16x32_bf16 v[124:127], v[148:151], v[184:187], v[124:127]
	v_mfma_f32_16x16x32_bf16 v[120:123], v[156:159], v[184:187], v[120:123]
	v_mfma_f32_16x16x32_bf16 v[108:111], v[148:151], v[192:195], v[108:111]
	v_mfma_f32_16x16x32_bf16 v[104:107], v[156:159], v[192:195], v[104:107]
	v_mfma_f32_16x16x32_bf16 v[92:95], v[148:151], v[200:203], v[92:95]
	v_mfma_f32_16x16x32_bf16 v[88:91], v[156:159], v[200:203], v[88:91]
	v_mfma_f32_16x16x32_bf16 v[76:79], v[148:151], v[220:223], v[76:79]
	v_mfma_f32_16x16x32_bf16 v[72:75], v[156:159], v[220:223], v[72:75]
	v_mfma_f32_16x16x32_bf16 v[124:127], v[152:155], v[188:191], v[124:127]
	v_mfma_f32_16x16x32_bf16 v[120:123], v[164:167], v[188:191], v[120:123]
	v_mfma_f32_16x16x32_bf16 v[108:111], v[152:155], v[196:199], v[108:111]
	v_mfma_f32_16x16x32_bf16 v[104:107], v[164:167], v[196:199], v[104:107]
	v_mfma_f32_16x16x32_bf16 v[92:95], v[152:155], v[216:219], v[92:95]
	v_mfma_f32_16x16x32_bf16 v[88:91], v[164:167], v[216:219], v[88:91]
	v_mfma_f32_16x16x32_bf16 v[76:79], v[152:155], v[224:227], v[76:79]
	v_mfma_f32_16x16x32_bf16 v[72:75], v[164:167], v[224:227], v[72:75]
	v_mfma_f32_16x16x32_bf16 v[116:119], v[168:171], v[184:187], v[116:119]
	v_mfma_f32_16x16x32_bf16 v[112:115], v[176:179], v[184:187], v[112:115]
	v_mfma_f32_16x16x32_bf16 v[100:103], v[168:171], v[192:195], v[100:103]
	v_mfma_f32_16x16x32_bf16 v[96:99], v[176:179], v[192:195], v[96:99]
	v_mfma_f32_16x16x32_bf16 v[84:87], v[168:171], v[200:203], v[84:87]
	v_mfma_f32_16x16x32_bf16 v[80:83], v[176:179], v[200:203], v[80:83]
	v_mfma_f32_16x16x32_bf16 v[68:71], v[168:171], v[220:223], v[68:71]
	v_mfma_f32_16x16x32_bf16 v[64:67], v[176:179], v[220:223], v[64:67]
	v_mfma_f32_16x16x32_bf16 v[116:119], v[172:175], v[188:191], v[116:119]
	v_mfma_f32_16x16x32_bf16 v[112:115], v[180:183], v[188:191], v[112:115]
	v_mfma_f32_16x16x32_bf16 v[100:103], v[172:175], v[196:199], v[100:103]
	v_mfma_f32_16x16x32_bf16 v[96:99], v[180:183], v[196:199], v[96:99]
	v_mfma_f32_16x16x32_bf16 v[84:87], v[172:175], v[216:219], v[84:87]
	v_mfma_f32_16x16x32_bf16 v[80:83], v[180:183], v[216:219], v[80:83]
	v_mfma_f32_16x16x32_bf16 v[68:71], v[172:175], v[224:227], v[68:71]
	v_mfma_f32_16x16x32_bf16 v[64:67], v[180:183], v[224:227], v[64:67]
	s_barrier
; #define PG8_STAGE(bufoff, gbase, voff) do { _Pragma("unroll") for (int _i = 0; _i < 2; ++_i) \
;         __builtin_amdgcn_global_load_lds((const unsigned*)((const char*)(gbase) + (voff)[_i]), (LAS unsigned*)(lds + (bufoff) + ldsw + _i * 8192), 16, 0, 0); } while (0)
; #define PG8_LDA(dst, b, h) do { _Pragma("unroll") for (int m = 0; m < 4; ++m) _Pragma("unroll") for (int k = 0; k < 2; ++k) dst[m][k] = *(const LAS bf16x8*)(lds + PG8_SA(b, h) + aoff + m * 2048 + k * 1024); } while (0)
; #define PG8_MMA(ai, bj, At, Bt) do { __builtin_amdgcn_s_setprio(1); _Pragma("unroll") for (int m = 0; m < 4; ++m) _Pragma("unroll") for (int n = 0; n < 2; ++n) _Pragma("unroll") for (int k = 0; k < 2; ++k) \
;         acc[ai][bj][m][n] = __builtin_amdgcn_mfma_f32_16x16x32_bf16(Bt[n][k], At[m][k], acc[ai][bj][m][n], 0, 0, 0); __builtin_amdgcn_s_setprio(0); } while (0)
; #define PG8_WAIT_V(n) asm volatile("s_waitcnt vmcnt(" #n ")" ::: "memory")
; #define PG8_WAIT_L(n) asm volatile("s_waitcnt lgkmcnt(" #n ")" ::: "memory")
; #define PG8_BAR __builtin_amdgcn_s_barrier()
; #define PG8_SCHED __builtin_amdgcn_sched_barrier(0)
; template <class Epi, bool HAS_MID>
; __device__ __forceinline__ void gemm_phase(LAS unsigned char* lds, const Gemm g, const Sched& S, const Epi& E) {
;     ...
;             PG8_LDA(At, 1, 1); PG8_STAGE(PG8_SB(1, 0), b3, voffB); PG8_STAGE(PG8_SB(1, 1), b3 + hstepB, voffB); PG8_STAGE(PG8_SA(1, 0), a3, voffA);
;             PG8_WAIT_V(8); PG8_WAIT_L(0); PG8_BAR; PG8_MMA(1, 0, At, B0); PG8_MMA(1, 1, At, B1); PG8_BAR; PG8_SCHED;
;         }
;         if (wr == 0) PG8_BAR;
	s_add_i32 s30, s30, s51
	v_lshl_add_u64 v[140:141], v[140:141], 0, s[38:39]
	s_mov_b32 m0, s30
	ds_read_b128 v[184:187], v146 offset:49152
	ds_read_b128 v[188:191], v146 offset:50176
	ds_read_b128 v[192:195], v146 offset:51200
	ds_read_b128 v[196:199], v146 offset:52224
	ds_read_b128 v[200:203], v146 offset:53248
	ds_read_b128 v[216:219], v146 offset:54272
	ds_read_b128 v[220:223], v146 offset:55296
	ds_read_b128 v[224:227], v146 offset:56320
	global_load_lds_dwordx4 v[140:141], off
	s_add_i32 m0, s30, 0x2000
	s_add_u32 s64, s82, 0x80080
	v_lshl_add_u64 v[140:141], v[204:205], 0, s[38:39]
	s_addc_u32 s65, s83, 0
	s_add_i32 s30, s36, s51
	global_load_lds_dwordx4 v[140:141], off
	v_lshl_add_u64 v[140:141], s[64:65], 0, v[160:161]
	s_mov_b32 m0, s30
	s_nop 0
	global_load_lds_dwordx4 v[140:141], off
	v_lshl_add_u64 v[140:141], s[64:65], 0, v[132:133]
	s_add_i32 m0, s30, 0x2000
	s_nop 0
	global_load_lds_dwordx4 v[140:141], off
	v_lshl_add_u64 v[140:141], v[208:209], 0, s[38:39]
	s_mov_b32 m0, s61
	s_nop 0
	global_load_lds_dwordx4 v[140:141], off
	v_lshl_add_u64 v[140:141], v[210:211], 0, s[38:39]
	s_mov_b32 m0, s86
	s_nop 0
	global_load_lds_dwordx4 v[140:141], off
	s_waitcnt vmcnt(8)
	s_waitcnt lgkmcnt(0)
	s_barrier
	s_waitcnt lgkmcnt(0)
	v_mfma_f32_16x16x32_bf16 v[60:63], v[148:151], v[184:187], v[60:63]
	v_mfma_f32_16x16x32_bf16 v[56:59], v[156:159], v[184:187], v[56:59]
	v_mfma_f32_16x16x32_bf16 v[44:47], v[148:151], v[192:195], v[44:47]
	v_mfma_f32_16x16x32_bf16 v[40:43], v[156:159], v[192:195], v[40:43]
	v_mfma_f32_16x16x32_bf16 v[28:31], v[148:151], v[200:203], v[28:31]
	v_mfma_f32_16x16x32_bf16 v[24:27], v[156:159], v[200:203], v[24:27]
	v_mfma_f32_16x16x32_bf16 v[12:15], v[148:151], v[220:223], v[12:15]
	v_mfma_f32_16x16x32_bf16 v[8:11], v[156:159], v[220:223], v[8:11]
	v_mfma_f32_16x16x32_bf16 v[60:63], v[152:155], v[188:191], v[60:63]
	v_mfma_f32_16x16x32_bf16 v[56:59], v[164:167], v[188:191], v[56:59]
	v_mfma_f32_16x16x32_bf16 v[44:47], v[152:155], v[196:199], v[44:47]
	v_mfma_f32_16x16x32_bf16 v[40:43], v[164:167], v[196:199], v[40:43]
	v_mfma_f32_16x16x32_bf16 v[28:31], v[152:155], v[216:219], v[28:31]
	v_mfma_f32_16x16x32_bf16 v[24:27], v[164:167], v[216:219], v[24:27]
	v_mfma_f32_16x16x32_bf16 v[12:15], v[152:155], v[224:227], v[12:15]
	v_mfma_f32_16x16x32_bf16 v[8:11], v[164:167], v[224:227], v[8:11]
	v_mfma_f32_16x16x32_bf16 v[52:55], v[168:171], v[184:187], v[52:55]
	v_mfma_f32_16x16x32_bf16 v[48:51], v[176:179], v[184:187], v[48:51]
	v_mfma_f32_16x16x32_bf16 v[36:39], v[168:171], v[192:195], v[36:39]
	v_mfma_f32_16x16x32_bf16 v[32:35], v[176:179], v[192:195], v[32:35]
	v_mfma_f32_16x16x32_bf16 v[20:23], v[168:171], v[200:203], v[20:23]
	v_mfma_f32_16x16x32_bf16 v[16:19], v[176:179], v[200:203], v[16:19]
	v_mfma_f32_16x16x32_bf16 v[4:7], v[168:171], v[220:223], v[4:7]
	v_mfma_f32_16x16x32_bf16 v[0:3], v[176:179], v[220:223], v[0:3]
	v_mfma_f32_16x16x32_bf16 v[52:55], v[172:175], v[188:191], v[52:55]
	v_mfma_f32_16x16x32_bf16 v[48:51], v[180:183], v[188:191], v[48:51]
	v_mfma_f32_16x16x32_bf16 v[36:39], v[172:175], v[196:199], v[36:39]
	v_mfma_f32_16x16x32_bf16 v[32:35], v[180:183], v[196:199], v[32:35]
	v_mfma_f32_16x16x32_bf16 v[20:23], v[172:175], v[216:219], v[20:23]
	v_mfma_f32_16x16x32_bf16 v[16:19], v[180:183], v[216:219], v[16:19]
	v_mfma_f32_16x16x32_bf16 v[4:7], v[172:175], v[224:227], v[4:7]
	v_mfma_f32_16x16x32_bf16 v[0:3], v[180:183], v[224:227], v[0:3]
	s_barrier
	s_add_i32 vcc_hi, vcc_hi, 2
	s_add_u32 s79, s79, 0x100
	s_addc_u32 vcc_lo, vcc_lo, 0
	s_add_u32 s80, s80, 0x100
	s_addc_u32 s81, s81, 0
	s_cmp_gt_u32 vcc_hi, 29
	s_cbranch_scc0 .LBB0_709
	s_and_b64 vcc, exec, s[26:27]
	s_cbranch_vccz .LBB0_713
	s_barrier
	v_lshl_add_u32 v147, s78, 8, v143
	s_cmp_gt_i32 s6, 43
	s_mov_b64 s[78:79], -1
	s_cbranch_scc1 .LBB0_714

; #define PG8_STAGE(bufoff, gbase, voff) do { _Pragma("unroll") for (int _i = 0; _i < 2; ++_i) \
;         __builtin_amdgcn_global_load_lds((const unsigned*)((const char*)(gbase) + (voff)[_i]), (LAS unsigned*)(lds + (bufoff) + ldsw + _i * 8192), 16, 0, 0); } while (0)
; #define PG8_LDA(dst, b, h) do { _Pragma("unroll") for (int m = 0; m < 4; ++m) _Pragma("unroll") for (int k = 0; k < 2; ++k) dst[m][k] = *(const LAS bf16x8*)(lds + PG8_SA(b, h) + aoff + m * 2048 + k * 1024); } while (0)
; #define PG8_LDB(dst, b, h) do { _Pragma("unroll") for (int n = 0; n < 2; ++n) _Pragma("unroll") for (int k = 0; k < 2; ++k) dst[n][k] = *(const LAS bf16x8*)(lds + PG8_SB(b, h) + boff + n * 2048 + k * 1024); } while (0)
; #define PG8_WAIT_V(n) asm volatile("s_waitcnt vmcnt(" #n ")" ::: "memory")
; #define PG8_WAIT_L(n) asm volatile("s_waitcnt lgkmcnt(" #n ")" ::: "memory")
; template <class Epi, bool HAS_MID>
; __device__ __forceinline__ void gemm_phase(LAS unsigned char* lds, const Gemm g, const Sched& S, const Epi& E) {
;     ...
;         for (int t = 0; t < nt; t += 2) {
;             const bool last = (t == nt - 2);
;             const char* a1 = PG8_APT(t + 1);
;             const char* a2 = last ? nA : PG8_APT(t + 2); const char* b2 = last ? nB : cB + (size_t)(t + 2) * kstep;
;             const char* a3 = a2 + kstep; const char* b3 = b2 + kstep;
;             PG8_LDB(B0, 0, 0); PG8_LDB(B1, 0, 1); PG8_SCHED; PG8_LDA(At, 0, 0); PG8_STAGE(PG8_SA(1, 1), a1 + hstepA, voffA);
;             PG8_WAIT_V(8); PG8_WAIT_L(0); PG8_BAR; PG8_MMA(0, 0, At, B0); PG8_MMA(0, 1, At, B1); PG8_BAR; PG8_SCHED;
;             PG8_LDA(At, 0, 1); PG8_STAGE(PG8_SB(0, 0), b2, voffB); PG8_STAGE(PG8_SB(0, 1), b2 + hstepB, voffB); PG8_STAGE(PG8_SA(0, 0), a2, voffA);
;             PG8_WAIT_V(8); PG8_WAIT_L(0); PG8_BAR; PG8_MMA(1, 0, At, B0); PG8_MMA(1, 1, At, B1); PG8_BAR; PG8_SCHED;
;             PG8_LDB(B0, 1, 0); PG8_LDB(B1, 1, 1); PG8_SCHED; PG8_LDA(At, 1, 0); PG8_STAGE(PG8_SA(0, 1), a2 + hstepA, voffA);
;             PG8_WAIT_V(8); PG8_WAIT_L(0); PG8_BAR; PG8_MMA(0, 0, At, B0); PG8_MMA(0, 1, At, B1); PG8_BAR; PG8_SCHED;
;             PG8_LDA(At, 1, 1); PG8_STAGE(PG8_SB(1, 0), b3, voffB); PG8_STAGE(PG8_SB(1, 1), b3 + hstepB, voffB); PG8_STAGE(PG8_SA(1, 0), a3, voffA);
;             PG8_WAIT_V(8); PG8_WAIT_L(0); PG8_BAR; PG8_MMA(1, 0, At, B0); PG8_MMA(1, 1, At, B1); PG8_BAR; PG8_SCHED;
.LBB0_1175:
	s_add_u32 s4, s70, 0x100
	s_addc_u32 s5, s71, 0
	s_add_i32 s30, 0, 0x10000
	s_cmp_eq_u32 s43, 4
	s_cselect_b32 s75, s27, s5
	s_cselect_b32 s74, s26, s4
	s_cselect_b32 s73, s7, s42
	s_cselect_b32 s72, s25, s40
	s_add_i32 s36, 0, 0x14000
	v_add_u32_e32 v156, s30, v149
	v_add_u32_e32 v160, s36, v149
	ds_read_b128 v[140:143], v156
	ds_read_b128 v[144:147], v156 offset:1024
	ds_read_b128 v[152:155], v156 offset:2048
	ds_read_b128 v[156:159], v156 offset:3072
	ds_read_b128 v[164:167], v160
	ds_read_b128 v[168:171], v160 offset:1024
	ds_read_b128 v[172:175], v160 offset:2048
	ds_read_b128 v[176:179], v160 offset:3072
	v_lshl_add_u64 v[204:205], s[70:71], 0, v[138:139]
	s_add_i32 m0, s77, 0xc000
	ds_read_b128 v[180:183], v151
	ds_read_b128 v[184:187], v151 offset:1024
	ds_read_b128 v[188:191], v151 offset:2048
	ds_read_b128 v[192:195], v151 offset:3072
	ds_read_b128 v[196:199], v151 offset:4096
	ds_read_b128 v[200:203], v151 offset:5120
	ds_read_b128 v[216:219], v151 offset:6144
	ds_read_b128 v[220:223], v151 offset:7168
	global_load_lds_dwordx4 v[204:205], off
	v_lshl_add_u64 v[204:205], s[70:71], 0, v[136:137]
	s_add_i32 m0, s77, 0xe000
	s_nop 0
	global_load_lds_dwordx4 v[204:205], off
	s_waitcnt vmcnt(8)
	s_waitcnt lgkmcnt(0)
	s_barrier
	s_waitcnt lgkmcnt(0)
	v_mfma_f32_16x16x32_bf16 v[124:127], v[140:143], v[180:183], v[124:127]
	v_mfma_f32_16x16x32_bf16 v[120:123], v[152:155], v[180:183], v[120:123]
	v_mfma_f32_16x16x32_bf16 v[108:111], v[140:143], v[188:191], v[108:111]
	v_mfma_f32_16x16x32_bf16 v[104:107], v[152:155], v[188:191], v[104:107]
	v_mfma_f32_16x16x32_bf16 v[92:95], v[140:143], v[196:199], v[92:95]
	v_mfma_f32_16x16x32_bf16 v[88:91], v[152:155], v[196:199], v[88:91]
	v_mfma_f32_16x16x32_bf16 v[76:79], v[140:143], v[216:219], v[76:79]
	v_mfma_f32_16x16x32_bf16 v[72:75], v[152:155], v[216:219], v[72:75]
	v_mfma_f32_16x16x32_bf16 v[124:127], v[144:147], v[184:187], v[124:127]
	v_mfma_f32_16x16x32_bf16 v[120:123], v[156:159], v[184:187], v[120:123]
	v_mfma_f32_16x16x32_bf16 v[108:111], v[144:147], v[192:195], v[108:111]
	v_mfma_f32_16x16x32_bf16 v[104:107], v[156:159], v[192:195], v[104:107]
	v_mfma_f32_16x16x32_bf16 v[92:95], v[144:147], v[200:203], v[92:95]
	v_mfma_f32_16x16x32_bf16 v[88:91], v[156:159], v[200:203], v[88:91]
	v_mfma_f32_16x16x32_bf16 v[76:79], v[144:147], v[220:223], v[76:79]
	v_mfma_f32_16x16x32_bf16 v[72:75], v[156:159], v[220:223], v[72:75]
	v_mfma_f32_16x16x32_bf16 v[116:119], v[164:167], v[180:183], v[116:119]
	v_mfma_f32_16x16x32_bf16 v[112:115], v[172:175], v[180:183], v[112:115]
	v_mfma_f32_16x16x32_bf16 v[100:103], v[164:167], v[188:191], v[100:103]
	v_mfma_f32_16x16x32_bf16 v[96:99], v[172:175], v[188:191], v[96:99]
	v_mfma_f32_16x16x32_bf16 v[84:87], v[164:167], v[196:199], v[84:87]
	v_mfma_f32_16x16x32_bf16 v[80:83], v[172:175], v[196:199], v[80:83]
	v_mfma_f32_16x16x32_bf16 v[68:71], v[164:167], v[216:219], v[68:71]
	v_mfma_f32_16x16x32_bf16 v[64:67], v[172:175], v[216:219], v[64:67]
	v_mfma_f32_16x16x32_bf16 v[116:119], v[168:171], v[184:187], v[116:119]
	v_mfma_f32_16x16x32_bf16 v[112:115], v[176:179], v[184:187], v[112:115]
	v_mfma_f32_16x16x32_bf16 v[100:103], v[168:171], v[192:195], v[100:103]
	v_mfma_f32_16x16x32_bf16 v[96:99], v[176:179], v[192:195], v[96:99]
	v_mfma_f32_16x16x32_bf16 v[84:87], v[168:171], v[200:203], v[84:87]
	v_mfma_f32_16x16x32_bf16 v[80:83], v[176:179], v[200:203], v[80:83]
	v_mfma_f32_16x16x32_bf16 v[68:71], v[168:171], v[220:223], v[68:71]
	v_mfma_f32_16x16x32_bf16 v[64:67], v[176:179], v[220:223], v[64:67]
	s_barrier
	s_add_i32 s30, s30, s76
	v_lshl_add_u64 v[204:205], s[72:73], 0, v[130:131]
	s_mov_b32 m0, s30
	ds_read_b128 v[180:183], v151 offset:16384
	ds_read_b128 v[184:187], v151 offset:17408
	ds_read_b128 v[188:191], v151 offset:18432
	ds_read_b128 v[192:195], v151 offset:19456
	ds_read_b128 v[196:199], v151 offset:20480
	ds_read_b128 v[200:203], v151 offset:21504
	ds_read_b128 v[216:219], v151 offset:22528
	ds_read_b128 v[220:223], v151 offset:23552
	global_load_lds_dwordx4 v[204:205], off
	s_add_i32 m0, s30, 0x2000
	s_add_u32 s64, s72, 0x20000
	v_lshl_add_u64 v[208:209], s[72:73], 0, v[134:135]
	s_addc_u32 s65, s73, 0
	s_add_i32 s30, s36, s76
	global_load_lds_dwordx4 v[208:209], off
	v_lshl_add_u64 v[210:211], s[64:65], 0, v[130:131]
	s_mov_b32 m0, s30
	v_lshl_add_u64 v[224:225], s[74:75], 0, v[132:133]
	global_load_lds_dwordx4 v[210:211], off
	v_lshl_add_u64 v[210:211], s[64:65], 0, v[134:135]
	s_add_i32 m0, s30, 0x2000
	s_nop 0
	global_load_lds_dwordx4 v[210:211], off
	v_lshl_add_u64 v[210:211], s[74:75], 0, v[128:129]
	s_mov_b32 m0, s77
	s_nop 0
	global_load_lds_dwordx4 v[210:211], off
	s_mov_b32 m0, s78
	s_nop 0
	global_load_lds_dwordx4 v[224:225], off
	s_waitcnt vmcnt(8)
	s_waitcnt lgkmcnt(0)
	s_barrier
; #define PG8_STAGE(bufoff, gbase, voff) do { _Pragma("unroll") for (int _i = 0; _i < 2; ++_i) \
;         __builtin_amdgcn_global_load_lds((const unsigned*)((const char*)(gbase) + (voff)[_i]), (LAS unsigned*)(lds + (bufoff) + ldsw + _i * 8192), 16, 0, 0); } while (0)
; #define PG8_LDA(dst, b, h) do { _Pragma("unroll") for (int m = 0; m < 4; ++m) _Pragma("unroll") for (int k = 0; k < 2; ++k) dst[m][k] = *(const LAS bf16x8*)(lds + PG8_SA(b, h) + aoff + m * 2048 + k * 1024); } while (0)
; #define PG8_LDB(dst, b, h) do { _Pragma("unroll") for (int n = 0; n < 2; ++n) _Pragma("unroll") for (int k = 0; k < 2; ++k) dst[n][k] = *(const LAS bf16x8*)(lds + PG8_SB(b, h) + boff + n * 2048 + k * 1024); } while (0)
; #define PG8_MMA(ai, bj, At, Bt) do { __builtin_amdgcn_s_setprio(1); _Pragma("unroll") for (int m = 0; m < 4; ++m) _Pragma("unroll") for (int n = 0; n < 2; ++n) _Pragma("unroll") for (int k = 0; k < 2; ++k) \
;         acc[ai][bj][m][n] = __builtin_amdgcn_mfma_f32_16x16x32_bf16(Bt[n][k], At[m][k], acc[ai][bj][m][n], 0, 0, 0); __builtin_amdgcn_s_setprio(0); } while (0)
; #define PG8_WAIT_V(n) asm volatile("s_waitcnt vmcnt(" #n ")" ::: "memory")
; #define PG8_WAIT_L(n) asm volatile("s_waitcnt lgkmcnt(" #n ")" ::: "memory")
; #define PG8_BAR __builtin_amdgcn_s_barrier()
; #define PG8_SCHED __builtin_amdgcn_sched_barrier(0)
; template <class Epi, bool HAS_MID>
; __device__ __forceinline__ void gemm_phase(LAS unsigned char* lds, const Gemm g, const Sched& S, const Epi& E) {
;     ...
;             PG8_WAIT_V(8); PG8_WAIT_L(0); PG8_BAR; PG8_MMA(1, 0, At, B0); PG8_MMA(1, 1, At, B1); PG8_BAR; PG8_SCHED;
;             PG8_LDB(B0, 1, 0); PG8_LDB(B1, 1, 1); PG8_SCHED; PG8_LDA(At, 1, 0); PG8_STAGE(PG8_SA(0, 1), a2 + hstepA, voffA);
;             PG8_WAIT_V(8); PG8_WAIT_L(0); PG8_BAR; PG8_MMA(0, 0, At, B0); PG8_MMA(0, 1, At, B1); PG8_BAR; PG8_SCHED;
;             PG8_LDA(At, 1, 1); PG8_STAGE(PG8_SB(1, 0), b3, voffB); PG8_STAGE(PG8_SB(1, 1), b3 + hstepB, voffB); PG8_STAGE(PG8_SA(1, 0), a3, voffA);
	s_waitcnt lgkmcnt(0)
	v_mfma_f32_16x16x32_bf16 v[60:63], v[140:143], v[180:183], v[60:63]
	v_mfma_f32_16x16x32_bf16 v[56:59], v[152:155], v[180:183], v[56:59]
	v_mfma_f32_16x16x32_bf16 v[44:47], v[140:143], v[188:191], v[44:47]
	v_mfma_f32_16x16x32_bf16 v[40:43], v[152:155], v[188:191], v[40:43]
	v_mfma_f32_16x16x32_bf16 v[28:31], v[140:143], v[196:199], v[28:31]
	v_mfma_f32_16x16x32_bf16 v[24:27], v[152:155], v[196:199], v[24:27]
	v_mfma_f32_16x16x32_bf16 v[12:15], v[140:143], v[216:219], v[12:15]
	v_mfma_f32_16x16x32_bf16 v[8:11], v[152:155], v[216:219], v[8:11]
	v_mfma_f32_16x16x32_bf16 v[60:63], v[144:147], v[184:187], v[60:63]
	v_mfma_f32_16x16x32_bf16 v[56:59], v[156:159], v[184:187], v[56:59]
	v_mfma_f32_16x16x32_bf16 v[44:47], v[144:147], v[192:195], v[44:47]
	v_mfma_f32_16x16x32_bf16 v[40:43], v[156:159], v[192:195], v[40:43]
	v_mfma_f32_16x16x32_bf16 v[28:31], v[144:147], v[200:203], v[28:31]
	v_mfma_f32_16x16x32_bf16 v[24:27], v[156:159], v[200:203], v[24:27]
	v_mfma_f32_16x16x32_bf16 v[12:15], v[144:147], v[220:223], v[12:15]
	v_mfma_f32_16x16x32_bf16 v[8:11], v[156:159], v[220:223], v[8:11]
	v_mfma_f32_16x16x32_bf16 v[52:55], v[164:167], v[180:183], v[52:55]
	v_mfma_f32_16x16x32_bf16 v[48:51], v[172:175], v[180:183], v[48:51]
	v_mfma_f32_16x16x32_bf16 v[36:39], v[164:167], v[188:191], v[36:39]
	v_mfma_f32_16x16x32_bf16 v[32:35], v[172:175], v[188:191], v[32:35]
	v_mfma_f32_16x16x32_bf16 v[20:23], v[164:167], v[196:199], v[20:23]
	v_mfma_f32_16x16x32_bf16 v[16:19], v[172:175], v[196:199], v[16:19]
	v_mfma_f32_16x16x32_bf16 v[4:7], v[164:167], v[216:219], v[4:7]
	v_mfma_f32_16x16x32_bf16 v[0:3], v[172:175], v[216:219], v[0:3]
	v_mfma_f32_16x16x32_bf16 v[52:55], v[168:171], v[184:187], v[52:55]
	v_mfma_f32_16x16x32_bf16 v[48:51], v[176:179], v[184:187], v[48:51]
	v_mfma_f32_16x16x32_bf16 v[36:39], v[168:171], v[192:195], v[36:39]
	v_mfma_f32_16x16x32_bf16 v[32:35], v[176:179], v[192:195], v[32:35]
	v_mfma_f32_16x16x32_bf16 v[20:23], v[168:171], v[200:203], v[20:23]
	v_mfma_f32_16x16x32_bf16 v[16:19], v[176:179], v[200:203], v[16:19]
	v_mfma_f32_16x16x32_bf16 v[4:7], v[168:171], v[220:223], v[4:7]
	v_mfma_f32_16x16x32_bf16 v[0:3], v[176:179], v[220:223], v[0:3]
	s_barrier
	s_add_i32 s30, 0, 0x18000
	s_add_i32 s36, 0, 0x1c000
	v_add_u32_e32 v156, s30, v149
	v_add_u32_e32 v160, s36, v149
	ds_read_b128 v[140:143], v156
	ds_read_b128 v[144:147], v156 offset:1024
	ds_read_b128 v[152:155], v156 offset:2048
	ds_read_b128 v[156:159], v156 offset:3072
	ds_read_b128 v[164:167], v160
	ds_read_b128 v[168:171], v160 offset:1024
	ds_read_b128 v[172:175], v160 offset:2048
	ds_read_b128 v[176:179], v160 offset:3072
	s_add_u32 s64, s74, 0x2c0000
	s_addc_u32 s65, s75, 0
	s_mov_b32 m0, s79
	v_lshl_add_u64 v[226:227], s[64:65], 0, v[128:129]
	ds_read_b128 v[180:183], v151 offset:32768
	ds_read_b128 v[184:187], v151 offset:33792
	ds_read_b128 v[188:191], v151 offset:34816
	ds_read_b128 v[192:195], v151 offset:35840
	ds_read_b128 v[196:199], v151 offset:36864
	ds_read_b128 v[200:203], v151 offset:37888
	ds_read_b128 v[216:219], v151 offset:38912
	ds_read_b128 v[220:223], v151 offset:39936
	global_load_lds_dwordx4 v[226:227], off
	v_lshl_add_u64 v[226:227], s[64:65], 0, v[132:133]
	s_mov_b32 m0, s80
	s_nop 0
	global_load_lds_dwordx4 v[226:227], off
	s_waitcnt vmcnt(8)
	s_waitcnt lgkmcnt(0)
	s_barrier
	s_waitcnt lgkmcnt(0)
	v_mfma_f32_16x16x32_bf16 v[124:127], v[140:143], v[180:183], v[124:127]
	v_mfma_f32_16x16x32_bf16 v[120:123], v[152:155], v[180:183], v[120:123]
	v_mfma_f32_16x16x32_bf16 v[108:111], v[140:143], v[188:191], v[108:111]
	v_mfma_f32_16x16x32_bf16 v[104:107], v[152:155], v[188:191], v[104:107]
	v_mfma_f32_16x16x32_bf16 v[92:95], v[140:143], v[196:199], v[92:95]
	v_mfma_f32_16x16x32_bf16 v[88:91], v[152:155], v[196:199], v[88:91]
	v_mfma_f32_16x16x32_bf16 v[76:79], v[140:143], v[216:219], v[76:79]
	v_mfma_f32_16x16x32_bf16 v[72:75], v[152:155], v[216:219], v[72:75]
	v_mfma_f32_16x16x32_bf16 v[124:127], v[144:147], v[184:187], v[124:127]
	v_mfma_f32_16x16x32_bf16 v[120:123], v[156:159], v[184:187], v[120:123]
	v_mfma_f32_16x16x32_bf16 v[108:111], v[144:147], v[192:195], v[108:111]
	v_mfma_f32_16x16x32_bf16 v[104:107], v[156:159], v[192:195], v[104:107]
	v_mfma_f32_16x16x32_bf16 v[92:95], v[144:147], v[200:203], v[92:95]
	v_mfma_f32_16x16x32_bf16 v[88:91], v[156:159], v[200:203], v[88:91]
	v_mfma_f32_16x16x32_bf16 v[76:79], v[144:147], v[220:223], v[76:79]
	v_mfma_f32_16x16x32_bf16 v[72:75], v[156:159], v[220:223], v[72:75]
	v_mfma_f32_16x16x32_bf16 v[116:119], v[164:167], v[180:183], v[116:119]
	v_mfma_f32_16x16x32_bf16 v[112:115], v[172:175], v[180:183], v[112:115]
	v_mfma_f32_16x16x32_bf16 v[100:103], v[164:167], v[188:191], v[100:103]
	v_mfma_f32_16x16x32_bf16 v[96:99], v[172:175], v[188:191], v[96:99]
	v_mfma_f32_16x16x32_bf16 v[84:87], v[164:167], v[196:199], v[84:87]
	v_mfma_f32_16x16x32_bf16 v[80:83], v[172:175], v[196:199], v[80:83]
	v_mfma_f32_16x16x32_bf16 v[68:71], v[164:167], v[216:219], v[68:71]
	v_mfma_f32_16x16x32_bf16 v[64:67], v[172:175], v[216:219], v[64:67]
	v_mfma_f32_16x16x32_bf16 v[116:119], v[168:171], v[184:187], v[116:119]
	v_mfma_f32_16x16x32_bf16 v[112:115], v[176:179], v[184:187], v[112:115]
	v_mfma_f32_16x16x32_bf16 v[100:103], v[168:171], v[192:195], v[100:103]
	v_mfma_f32_16x16x32_bf16 v[96:99], v[176:179], v[192:195], v[96:99]
	v_mfma_f32_16x16x32_bf16 v[84:87], v[168:171], v[200:203], v[84:87]
	v_mfma_f32_16x16x32_bf16 v[80:83], v[176:179], v[200:203], v[80:83]
	v_mfma_f32_16x16x32_bf16 v[68:71], v[168:171], v[220:223], v[68:71]
	v_mfma_f32_16x16x32_bf16 v[64:67], v[176:179], v[220:223], v[64:67]
	s_barrier
; #define PG8_STAGE(bufoff, gbase, voff) do { _Pragma("unroll") for (int _i = 0; _i < 2; ++_i) \
;         __builtin_amdgcn_global_load_lds((const unsigned*)((const char*)(gbase) + (voff)[_i]), (LAS unsigned*)(lds + (bufoff) + ldsw + _i * 8192), 16, 0, 0); } while (0)
; #define PG8_LDA(dst, b, h) do { _Pragma("unroll") for (int m = 0; m < 4; ++m) _Pragma("unroll") for (int k = 0; k < 2; ++k) dst[m][k] = *(const LAS bf16x8*)(lds + PG8_SA(b, h) + aoff + m * 2048 + k * 1024); } while (0)
; #define PG8_MMA(ai, bj, At, Bt) do { __builtin_amdgcn_s_setprio(1); _Pragma("unroll") for (int m = 0; m < 4; ++m) _Pragma("unroll") for (int n = 0; n < 2; ++n) _Pragma("unroll") for (int k = 0; k < 2; ++k) \
;         acc[ai][bj][m][n] = __builtin_amdgcn_mfma_f32_16x16x32_bf16(Bt[n][k], At[m][k], acc[ai][bj][m][n], 0, 0, 0); __builtin_amdgcn_s_setprio(0); } while (0)
; #define PG8_WAIT_V(n) asm volatile("s_waitcnt vmcnt(" #n ")" ::: "memory")
; #define PG8_WAIT_L(n) asm volatile("s_waitcnt lgkmcnt(" #n ")" ::: "memory")
; #define PG8_BAR __builtin_amdgcn_s_barrier()
; #define PG8_SCHED __builtin_amdgcn_sched_barrier(0)
; template <class Epi, bool HAS_MID>
; __device__ __forceinline__ void gemm_phase(LAS unsigned char* lds, const Gemm g, const Sched& S, const Epi& E) {
;     ...
;             PG8_LDA(At, 1, 1); PG8_STAGE(PG8_SB(1, 0), b3, voffB); PG8_STAGE(PG8_SB(1, 1), b3 + hstepB, voffB); PG8_STAGE(PG8_SA(1, 0), a3, voffA);
;             PG8_WAIT_V(8); PG8_WAIT_L(0); PG8_BAR; PG8_MMA(1, 0, At, B0); PG8_MMA(1, 1, At, B1); PG8_BAR; PG8_SCHED;
;         }
;         if (wr == 0) PG8_BAR;
	s_add_i32 s30, s30, s76
	v_lshl_add_u64 v[204:205], v[204:205], 0, s[38:39]
	s_mov_b32 m0, s30
	ds_read_b128 v[180:183], v151 offset:49152
	ds_read_b128 v[184:187], v151 offset:50176
	ds_read_b128 v[188:191], v151 offset:51200
	ds_read_b128 v[192:195], v151 offset:52224
	ds_read_b128 v[196:199], v151 offset:53248
	ds_read_b128 v[200:203], v151 offset:54272
	ds_read_b128 v[216:219], v151 offset:55296
	ds_read_b128 v[220:223], v151 offset:56320
	global_load_lds_dwordx4 v[204:205], off
	s_add_i32 m0, s30, 0x2000
	s_add_u32 s64, s72, 0x20080
	v_lshl_add_u64 v[204:205], v[208:209], 0, s[38:39]
	s_addc_u32 s65, s73, 0
	s_add_i32 s30, s36, s76
	global_load_lds_dwordx4 v[204:205], off
	v_lshl_add_u64 v[204:205], s[64:65], 0, v[130:131]
	s_mov_b32 m0, s30
	s_nop 0
	global_load_lds_dwordx4 v[204:205], off
	v_lshl_add_u64 v[204:205], s[64:65], 0, v[134:135]
	s_add_i32 m0, s30, 0x2000
	s_nop 0
	global_load_lds_dwordx4 v[204:205], off
	v_lshl_add_u64 v[204:205], v[210:211], 0, s[38:39]
	s_mov_b32 m0, s81
	s_nop 0
	global_load_lds_dwordx4 v[204:205], off
	v_lshl_add_u64 v[204:205], v[224:225], 0, s[38:39]
	s_mov_b32 m0, s82
	s_nop 0
	global_load_lds_dwordx4 v[204:205], off
	s_waitcnt vmcnt(8)
	s_waitcnt lgkmcnt(0)
	s_barrier
	s_waitcnt lgkmcnt(0)
	v_mfma_f32_16x16x32_bf16 v[60:63], v[140:143], v[180:183], v[60:63]
	v_mfma_f32_16x16x32_bf16 v[56:59], v[152:155], v[180:183], v[56:59]
	v_mfma_f32_16x16x32_bf16 v[44:47], v[140:143], v[188:191], v[44:47]
	v_mfma_f32_16x16x32_bf16 v[40:43], v[152:155], v[188:191], v[40:43]
	v_mfma_f32_16x16x32_bf16 v[28:31], v[140:143], v[196:199], v[28:31]
	v_mfma_f32_16x16x32_bf16 v[24:27], v[152:155], v[196:199], v[24:27]
	v_mfma_f32_16x16x32_bf16 v[12:15], v[140:143], v[216:219], v[12:15]
	v_mfma_f32_16x16x32_bf16 v[8:11], v[152:155], v[216:219], v[8:11]
	v_mfma_f32_16x16x32_bf16 v[60:63], v[144:147], v[184:187], v[60:63]
	v_mfma_f32_16x16x32_bf16 v[56:59], v[156:159], v[184:187], v[56:59]
	v_mfma_f32_16x16x32_bf16 v[44:47], v[144:147], v[192:195], v[44:47]
	v_mfma_f32_16x16x32_bf16 v[40:43], v[156:159], v[192:195], v[40:43]
	v_mfma_f32_16x16x32_bf16 v[28:31], v[144:147], v[200:203], v[28:31]
	v_mfma_f32_16x16x32_bf16 v[24:27], v[156:159], v[200:203], v[24:27]
	v_mfma_f32_16x16x32_bf16 v[12:15], v[144:147], v[220:223], v[12:15]
	v_mfma_f32_16x16x32_bf16 v[8:11], v[156:159], v[220:223], v[8:11]
	v_mfma_f32_16x16x32_bf16 v[52:55], v[164:167], v[180:183], v[52:55]
	v_mfma_f32_16x16x32_bf16 v[48:51], v[172:175], v[180:183], v[48:51]
	v_mfma_f32_16x16x32_bf16 v[36:39], v[164:167], v[188:191], v[36:39]
	v_mfma_f32_16x16x32_bf16 v[32:35], v[172:175], v[188:191], v[32:35]
	v_mfma_f32_16x16x32_bf16 v[20:23], v[164:167], v[196:199], v[20:23]
	v_mfma_f32_16x16x32_bf16 v[16:19], v[172:175], v[196:199], v[16:19]
	v_mfma_f32_16x16x32_bf16 v[4:7], v[164:167], v[216:219], v[4:7]
	v_mfma_f32_16x16x32_bf16 v[0:3], v[172:175], v[216:219], v[0:3]
	v_mfma_f32_16x16x32_bf16 v[52:55], v[168:171], v[184:187], v[52:55]
	v_mfma_f32_16x16x32_bf16 v[48:51], v[176:179], v[184:187], v[48:51]
	v_mfma_f32_16x16x32_bf16 v[36:39], v[168:171], v[192:195], v[36:39]
	v_mfma_f32_16x16x32_bf16 v[32:35], v[176:179], v[192:195], v[32:35]
	v_mfma_f32_16x16x32_bf16 v[20:23], v[168:171], v[200:203], v[20:23]
	v_mfma_f32_16x16x32_bf16 v[16:19], v[176:179], v[200:203], v[16:19]
	v_mfma_f32_16x16x32_bf16 v[4:7], v[168:171], v[220:223], v[4:7]
	v_mfma_f32_16x16x32_bf16 v[0:3], v[176:179], v[220:223], v[0:3]
	s_barrier
	s_add_i32 s43, s43, 2
	s_add_u32 s40, s40, 0x100
	s_addc_u32 s42, s42, 0
	s_cmp_gt_u32 s43, 5
	s_mov_b64 s[70:71], s[4:5]
	s_cbranch_scc0 .LBB0_1175
	s_and_b64 vcc, exec, s[22:23]
	s_cbranch_vccz .LBB0_1178
	s_barrier

; #define PG8_STAGE(bufoff, gbase, voff) do { _Pragma("unroll") for (int _i = 0; _i < 2; ++_i) \
;         __builtin_amdgcn_global_load_lds((const unsigned*)((const char*)(gbase) + (voff)[_i]), (LAS unsigned*)(lds + (bufoff) + ldsw + _i * 8192), 16, 0, 0); } while (0)
; #define PG8_LDA(dst, b, h) do { _Pragma("unroll") for (int m = 0; m < 4; ++m) _Pragma("unroll") for (int k = 0; k < 2; ++k) dst[m][k] = *(const LAS bf16x8*)(lds + PG8_SA(b, h) + aoff + m * 2048 + k * 1024); } while (0)
; #define PG8_LDB(dst, b, h) do { _Pragma("unroll") for (int n = 0; n < 2; ++n) _Pragma("unroll") for (int k = 0; k < 2; ++k) dst[n][k] = *(const LAS bf16x8*)(lds + PG8_SB(b, h) + boff + n * 2048 + k * 1024); } while (0)
; #define PG8_WAIT_V(n) asm volatile("s_waitcnt vmcnt(" #n ")" ::: "memory")
; #define PG8_WAIT_L(n) asm volatile("s_waitcnt lgkmcnt(" #n ")" ::: "memory")
; template <class Epi, bool HAS_MID>
; __device__ __forceinline__ void gemm_phase(LAS unsigned char* lds, const Gemm g, const Sched& S, const Epi& E) {
;     ...
;         for (int t = 0; t < nt; t += 2) {
;             const bool last = (t == nt - 2);
;             const char* a1 = PG8_APT(t + 1);
;             const char* a2 = last ? nA : PG8_APT(t + 2); const char* b2 = last ? nB : cB + (size_t)(t + 2) * kstep;
;             const char* a3 = a2 + kstep; const char* b3 = b2 + kstep;
;             PG8_LDB(B0, 0, 0); PG8_LDB(B1, 0, 1); PG8_SCHED; PG8_LDA(At, 0, 0); PG8_STAGE(PG8_SA(1, 1), a1 + hstepA, voffA);
;             PG8_WAIT_V(8); PG8_WAIT_L(0); PG8_BAR; PG8_MMA(0, 0, At, B0); PG8_MMA(0, 1, At, B1); PG8_BAR; PG8_SCHED;
;             PG8_LDA(At, 0, 1); PG8_STAGE(PG8_SB(0, 0), b2, voffB); PG8_STAGE(PG8_SB(0, 1), b2 + hstepB, voffB); PG8_STAGE(PG8_SA(0, 0), a2, voffA);
;             PG8_WAIT_V(8); PG8_WAIT_L(0); PG8_BAR; PG8_MMA(1, 0, At, B0); PG8_MMA(1, 1, At, B1); PG8_BAR; PG8_SCHED;
;             PG8_LDB(B0, 1, 0); PG8_LDB(B1, 1, 1); PG8_SCHED; PG8_LDA(At, 1, 0); PG8_STAGE(PG8_SA(0, 1), a2 + hstepA, voffA);
;             PG8_WAIT_V(8); PG8_WAIT_L(0); PG8_BAR; PG8_MMA(0, 0, At, B0); PG8_MMA(0, 1, At, B1); PG8_BAR; PG8_SCHED;
;             PG8_LDA(At, 1, 1); PG8_STAGE(PG8_SB(1, 0), b3, voffB); PG8_STAGE(PG8_SB(1, 1), b3 + hstepB, voffB); PG8_STAGE(PG8_SA(1, 0), a3, voffA);
;             PG8_WAIT_V(8); PG8_WAIT_L(0); PG8_BAR; PG8_MMA(1, 0, At, B0); PG8_MMA(1, 1, At, B1); PG8_BAR; PG8_SCHED;
.LBB0_1225:
	s_add_u32 s4, s70, 0x100
	s_addc_u32 s5, s71, 0
	s_add_i32 s30, 0, 0x10000
	s_cmp_eq_u32 s52, 4
	s_cselect_b32 s75, s27, s5
	s_cselect_b32 s74, s26, s4
	v_add_u32_e32 v140, s30, v143
	s_cselect_b32 s73, s25, s51
	s_cselect_b32 s72, s43, s48
	s_add_i32 s36, 0, 0x14000
	ds_read_b128 v[146:149], v140
	ds_read_b128 v[150:153], v140 offset:1024
	ds_read_b128 v[154:157], v140 offset:2048
	ds_read_b128 v[164:167], v140 offset:3072
	v_add_u32_e32 v140, s36, v143
	ds_read_b128 v[168:171], v140
	ds_read_b128 v[172:175], v140 offset:1024
	ds_read_b128 v[176:179], v140 offset:2048
	ds_read_b128 v[180:183], v140 offset:3072
	v_lshl_add_u64 v[140:141], s[70:71], 0, v[138:139]
	s_add_i32 m0, s77, 0xc000
	ds_read_b128 v[184:187], v144
	ds_read_b128 v[188:191], v144 offset:1024
	ds_read_b128 v[192:195], v144 offset:2048
	ds_read_b128 v[196:199], v144 offset:3072
	ds_read_b128 v[200:203], v144 offset:4096
	ds_read_b128 v[216:219], v144 offset:5120
	ds_read_b128 v[220:223], v144 offset:6144
	ds_read_b128 v[224:227], v144 offset:7168
	global_load_lds_dwordx4 v[140:141], off
	v_lshl_add_u64 v[140:141], s[70:71], 0, v[136:137]
	s_add_i32 m0, s77, 0xe000
	s_nop 0
	global_load_lds_dwordx4 v[140:141], off
	s_waitcnt vmcnt(8)
	s_waitcnt lgkmcnt(0)
	s_barrier
	s_waitcnt lgkmcnt(0)
	v_mfma_f32_16x16x32_bf16 v[124:127], v[146:149], v[184:187], v[124:127]
	v_mfma_f32_16x16x32_bf16 v[120:123], v[154:157], v[184:187], v[120:123]
	v_mfma_f32_16x16x32_bf16 v[108:111], v[146:149], v[192:195], v[108:111]
	v_mfma_f32_16x16x32_bf16 v[104:107], v[154:157], v[192:195], v[104:107]
	v_mfma_f32_16x16x32_bf16 v[92:95], v[146:149], v[200:203], v[92:95]
	v_mfma_f32_16x16x32_bf16 v[88:91], v[154:157], v[200:203], v[88:91]
	v_mfma_f32_16x16x32_bf16 v[76:79], v[146:149], v[220:223], v[76:79]
	v_mfma_f32_16x16x32_bf16 v[72:75], v[154:157], v[220:223], v[72:75]
	v_mfma_f32_16x16x32_bf16 v[124:127], v[150:153], v[188:191], v[124:127]
	v_mfma_f32_16x16x32_bf16 v[120:123], v[164:167], v[188:191], v[120:123]
	v_mfma_f32_16x16x32_bf16 v[108:111], v[150:153], v[196:199], v[108:111]
	v_mfma_f32_16x16x32_bf16 v[104:107], v[164:167], v[196:199], v[104:107]
	v_mfma_f32_16x16x32_bf16 v[92:95], v[150:153], v[216:219], v[92:95]
	v_mfma_f32_16x16x32_bf16 v[88:91], v[164:167], v[216:219], v[88:91]
	v_mfma_f32_16x16x32_bf16 v[76:79], v[150:153], v[224:227], v[76:79]
	v_mfma_f32_16x16x32_bf16 v[72:75], v[164:167], v[224:227], v[72:75]
	v_mfma_f32_16x16x32_bf16 v[116:119], v[168:171], v[184:187], v[116:119]
	v_mfma_f32_16x16x32_bf16 v[112:115], v[176:179], v[184:187], v[112:115]
	v_mfma_f32_16x16x32_bf16 v[100:103], v[168:171], v[192:195], v[100:103]
	v_mfma_f32_16x16x32_bf16 v[96:99], v[176:179], v[192:195], v[96:99]
	v_mfma_f32_16x16x32_bf16 v[84:87], v[168:171], v[200:203], v[84:87]
	v_mfma_f32_16x16x32_bf16 v[80:83], v[176:179], v[200:203], v[80:83]
	v_mfma_f32_16x16x32_bf16 v[68:71], v[168:171], v[220:223], v[68:71]
	v_mfma_f32_16x16x32_bf16 v[64:67], v[176:179], v[220:223], v[64:67]
	v_mfma_f32_16x16x32_bf16 v[116:119], v[172:175], v[188:191], v[116:119]
	v_mfma_f32_16x16x32_bf16 v[112:115], v[180:183], v[188:191], v[112:115]
	v_mfma_f32_16x16x32_bf16 v[100:103], v[172:175], v[196:199], v[100:103]
	v_mfma_f32_16x16x32_bf16 v[96:99], v[180:183], v[196:199], v[96:99]
	v_mfma_f32_16x16x32_bf16 v[84:87], v[172:175], v[216:219], v[84:87]
	v_mfma_f32_16x16x32_bf16 v[80:83], v[180:183], v[216:219], v[80:83]
	v_mfma_f32_16x16x32_bf16 v[68:71], v[172:175], v[224:227], v[68:71]
	v_mfma_f32_16x16x32_bf16 v[64:67], v[180:183], v[224:227], v[64:67]
	s_barrier
	s_add_i32 s30, s30, s61
	v_lshl_add_u64 v[140:141], s[72:73], 0, v[132:133]
	s_mov_b32 m0, s30
	ds_read_b128 v[184:187], v144 offset:16384
	ds_read_b128 v[188:191], v144 offset:17408
	ds_read_b128 v[192:195], v144 offset:18432
	ds_read_b128 v[196:199], v144 offset:19456
	ds_read_b128 v[200:203], v144 offset:20480
	ds_read_b128 v[216:219], v144 offset:21504
	ds_read_b128 v[220:223], v144 offset:22528
	ds_read_b128 v[224:227], v144 offset:23552
	global_load_lds_dwordx4 v[140:141], off
	s_add_i32 m0, s30, 0x2000
	s_add_u32 s64, s72, 0x20000
	v_lshl_add_u64 v[158:159], s[72:73], 0, v[128:129]
	s_addc_u32 s65, s73, 0
	s_add_i32 s30, s36, s61
	global_load_lds_dwordx4 v[158:159], off
	v_lshl_add_u64 v[204:205], s[64:65], 0, v[132:133]
	s_mov_b32 m0, s30
	v_lshl_add_u64 v[208:209], s[74:75], 0, v[130:131]
	global_load_lds_dwordx4 v[204:205], off
	v_lshl_add_u64 v[204:205], s[64:65], 0, v[128:129]
	s_add_i32 m0, s30, 0x2000
	s_nop 0
	global_load_lds_dwordx4 v[204:205], off
	v_lshl_add_u64 v[204:205], s[74:75], 0, v[134:135]
	s_mov_b32 m0, s77
	s_nop 0
	global_load_lds_dwordx4 v[204:205], off
	s_mov_b32 m0, s78
	s_nop 0
	global_load_lds_dwordx4 v[208:209], off
	s_waitcnt vmcnt(8)
	s_waitcnt lgkmcnt(0)
	s_barrier
; #define PG8_STAGE(bufoff, gbase, voff) do { _Pragma("unroll") for (int _i = 0; _i < 2; ++_i) \
;         __builtin_amdgcn_global_load_lds((const unsigned*)((const char*)(gbase) + (voff)[_i]), (LAS unsigned*)(lds + (bufoff) + ldsw + _i * 8192), 16, 0, 0); } while (0)
; #define PG8_LDA(dst, b, h) do { _Pragma("unroll") for (int m = 0; m < 4; ++m) _Pragma("unroll") for (int k = 0; k < 2; ++k) dst[m][k] = *(const LAS bf16x8*)(lds + PG8_SA(b, h) + aoff + m * 2048 + k * 1024); } while (0)
; #define PG8_LDB(dst, b, h) do { _Pragma("unroll") for (int n = 0; n < 2; ++n) _Pragma("unroll") for (int k = 0; k < 2; ++k) dst[n][k] = *(const LAS bf16x8*)(lds + PG8_SB(b, h) + boff + n * 2048 + k * 1024); } while (0)
; #define PG8_MMA(ai, bj, At, Bt) do { __builtin_amdgcn_s_setprio(1); _Pragma("unroll") for (int m = 0; m < 4; ++m) _Pragma("unroll") for (int n = 0; n < 2; ++n) _Pragma("unroll") for (int k = 0; k < 2; ++k) \
;         acc[ai][bj][m][n] = __builtin_amdgcn_mfma_f32_16x16x32_bf16(Bt[n][k], At[m][k], acc[ai][bj][m][n], 0, 0, 0); __builtin_amdgcn_s_setprio(0); } while (0)
; #define PG8_WAIT_V(n) asm volatile("s_waitcnt vmcnt(" #n ")" ::: "memory")
; #define PG8_WAIT_L(n) asm volatile("s_waitcnt lgkmcnt(" #n ")" ::: "memory")
; #define PG8_BAR __builtin_amdgcn_s_barrier()
; #define PG8_SCHED __builtin_amdgcn_sched_barrier(0)
; template <class Epi, bool HAS_MID>
; __device__ __forceinline__ void gemm_phase(LAS unsigned char* lds, const Gemm g, const Sched& S, const Epi& E) {
;     ...
;             PG8_WAIT_V(8); PG8_WAIT_L(0); PG8_BAR; PG8_MMA(1, 0, At, B0); PG8_MMA(1, 1, At, B1); PG8_BAR; PG8_SCHED;
;             PG8_LDB(B0, 1, 0); PG8_LDB(B1, 1, 1); PG8_SCHED; PG8_LDA(At, 1, 0); PG8_STAGE(PG8_SA(0, 1), a2 + hstepA, voffA);
;             PG8_WAIT_V(8); PG8_WAIT_L(0); PG8_BAR; PG8_MMA(0, 0, At, B0); PG8_MMA(0, 1, At, B1); PG8_BAR; PG8_SCHED;
;             PG8_LDA(At, 1, 1); PG8_STAGE(PG8_SB(1, 0), b3, voffB); PG8_STAGE(PG8_SB(1, 1), b3 + hstepB, voffB); PG8_STAGE(PG8_SA(1, 0), a3, voffA);
	s_waitcnt lgkmcnt(0)
	v_mfma_f32_16x16x32_bf16 v[60:63], v[146:149], v[184:187], v[60:63]
	v_mfma_f32_16x16x32_bf16 v[56:59], v[154:157], v[184:187], v[56:59]
	v_mfma_f32_16x16x32_bf16 v[44:47], v[146:149], v[192:195], v[44:47]
	v_mfma_f32_16x16x32_bf16 v[40:43], v[154:157], v[192:195], v[40:43]
	v_mfma_f32_16x16x32_bf16 v[28:31], v[146:149], v[200:203], v[28:31]
	v_mfma_f32_16x16x32_bf16 v[24:27], v[154:157], v[200:203], v[24:27]
	v_mfma_f32_16x16x32_bf16 v[12:15], v[146:149], v[220:223], v[12:15]
	v_mfma_f32_16x16x32_bf16 v[8:11], v[154:157], v[220:223], v[8:11]
	v_mfma_f32_16x16x32_bf16 v[60:63], v[150:153], v[188:191], v[60:63]
	v_mfma_f32_16x16x32_bf16 v[56:59], v[164:167], v[188:191], v[56:59]
	v_mfma_f32_16x16x32_bf16 v[44:47], v[150:153], v[196:199], v[44:47]
	v_mfma_f32_16x16x32_bf16 v[40:43], v[164:167], v[196:199], v[40:43]
	v_mfma_f32_16x16x32_bf16 v[28:31], v[150:153], v[216:219], v[28:31]
	v_mfma_f32_16x16x32_bf16 v[24:27], v[164:167], v[216:219], v[24:27]
	v_mfma_f32_16x16x32_bf16 v[12:15], v[150:153], v[224:227], v[12:15]
	v_mfma_f32_16x16x32_bf16 v[8:11], v[164:167], v[224:227], v[8:11]
	v_mfma_f32_16x16x32_bf16 v[52:55], v[168:171], v[184:187], v[52:55]
	v_mfma_f32_16x16x32_bf16 v[48:51], v[176:179], v[184:187], v[48:51]
	v_mfma_f32_16x16x32_bf16 v[36:39], v[168:171], v[192:195], v[36:39]
	v_mfma_f32_16x16x32_bf16 v[32:35], v[176:179], v[192:195], v[32:35]
	v_mfma_f32_16x16x32_bf16 v[20:23], v[168:171], v[200:203], v[20:23]
	v_mfma_f32_16x16x32_bf16 v[16:19], v[176:179], v[200:203], v[16:19]
	v_mfma_f32_16x16x32_bf16 v[4:7], v[168:171], v[220:223], v[4:7]
	v_mfma_f32_16x16x32_bf16 v[0:3], v[176:179], v[220:223], v[0:3]
	v_mfma_f32_16x16x32_bf16 v[52:55], v[172:175], v[188:191], v[52:55]
	v_mfma_f32_16x16x32_bf16 v[48:51], v[180:183], v[188:191], v[48:51]
	v_mfma_f32_16x16x32_bf16 v[36:39], v[172:175], v[196:199], v[36:39]
	v_mfma_f32_16x16x32_bf16 v[32:35], v[180:183], v[196:199], v[32:35]
	v_mfma_f32_16x16x32_bf16 v[20:23], v[172:175], v[216:219], v[20:23]
	v_mfma_f32_16x16x32_bf16 v[16:19], v[180:183], v[216:219], v[16:19]
	v_mfma_f32_16x16x32_bf16 v[4:7], v[172:175], v[224:227], v[4:7]
	v_mfma_f32_16x16x32_bf16 v[0:3], v[180:183], v[224:227], v[0:3]
	s_barrier
	s_add_i32 s30, 0, 0x18000
	v_add_u32_e32 v145, s30, v143
	s_add_i32 s36, 0, 0x1c000
	ds_read_b128 v[146:149], v145
	ds_read_b128 v[150:153], v145 offset:1024
	ds_read_b128 v[154:157], v145 offset:2048
	ds_read_b128 v[164:167], v145 offset:3072
	v_add_u32_e32 v145, s36, v143
	ds_read_b128 v[168:171], v145
	ds_read_b128 v[172:175], v145 offset:1024
	ds_read_b128 v[176:179], v145 offset:2048
	ds_read_b128 v[180:183], v145 offset:3072
	s_add_u32 s64, s74, 0x2c0000
	s_addc_u32 s65, s75, 0
	s_mov_b32 m0, s79
	v_lshl_add_u64 v[210:211], s[64:65], 0, v[134:135]
	ds_read_b128 v[184:187], v144 offset:32768
	ds_read_b128 v[188:191], v144 offset:33792
	ds_read_b128 v[192:195], v144 offset:34816
	ds_read_b128 v[196:199], v144 offset:35840
	ds_read_b128 v[200:203], v144 offset:36864
	ds_read_b128 v[216:219], v144 offset:37888
	ds_read_b128 v[220:223], v144 offset:38912
	ds_read_b128 v[224:227], v144 offset:39936
	global_load_lds_dwordx4 v[210:211], off
	v_lshl_add_u64 v[210:211], s[64:65], 0, v[130:131]
	s_mov_b32 m0, s80
	s_nop 0
	global_load_lds_dwordx4 v[210:211], off
	s_waitcnt vmcnt(8)
	s_waitcnt lgkmcnt(0)
	s_barrier
	s_waitcnt lgkmcnt(0)
	v_mfma_f32_16x16x32_bf16 v[124:127], v[146:149], v[184:187], v[124:127]
	v_mfma_f32_16x16x32_bf16 v[120:123], v[154:157], v[184:187], v[120:123]
	v_mfma_f32_16x16x32_bf16 v[108:111], v[146:149], v[192:195], v[108:111]
	v_mfma_f32_16x16x32_bf16 v[104:107], v[154:157], v[192:195], v[104:107]
	v_mfma_f32_16x16x32_bf16 v[92:95], v[146:149], v[200:203], v[92:95]
	v_mfma_f32_16x16x32_bf16 v[88:91], v[154:157], v[200:203], v[88:91]
	v_mfma_f32_16x16x32_bf16 v[76:79], v[146:149], v[220:223], v[76:79]
	v_mfma_f32_16x16x32_bf16 v[72:75], v[154:157], v[220:223], v[72:75]
	v_mfma_f32_16x16x32_bf16 v[124:127], v[150:153], v[188:191], v[124:127]
	v_mfma_f32_16x16x32_bf16 v[120:123], v[164:167], v[188:191], v[120:123]
	v_mfma_f32_16x16x32_bf16 v[108:111], v[150:153], v[196:199], v[108:111]
	v_mfma_f32_16x16x32_bf16 v[104:107], v[164:167], v[196:199], v[104:107]
	v_mfma_f32_16x16x32_bf16 v[92:95], v[150:153], v[216:219], v[92:95]
	v_mfma_f32_16x16x32_bf16 v[88:91], v[164:167], v[216:219], v[88:91]
	v_mfma_f32_16x16x32_bf16 v[76:79], v[150:153], v[224:227], v[76:79]
	v_mfma_f32_16x16x32_bf16 v[72:75], v[164:167], v[224:227], v[72:75]
	v_mfma_f32_16x16x32_bf16 v[116:119], v[168:171], v[184:187], v[116:119]
	v_mfma_f32_16x16x32_bf16 v[112:115], v[176:179], v[184:187], v[112:115]
	v_mfma_f32_16x16x32_bf16 v[100:103], v[168:171], v[192:195], v[100:103]
	v_mfma_f32_16x16x32_bf16 v[96:99], v[176:179], v[192:195], v[96:99]
	v_mfma_f32_16x16x32_bf16 v[84:87], v[168:171], v[200:203], v[84:87]
	v_mfma_f32_16x16x32_bf16 v[80:83], v[176:179], v[200:203], v[80:83]
	v_mfma_f32_16x16x32_bf16 v[68:71], v[168:171], v[220:223], v[68:71]
	v_mfma_f32_16x16x32_bf16 v[64:67], v[176:179], v[220:223], v[64:67]
	v_mfma_f32_16x16x32_bf16 v[116:119], v[172:175], v[188:191], v[116:119]
	v_mfma_f32_16x16x32_bf16 v[112:115], v[180:183], v[188:191], v[112:115]
	v_mfma_f32_16x16x32_bf16 v[100:103], v[172:175], v[196:199], v[100:103]
	v_mfma_f32_16x16x32_bf16 v[96:99], v[180:183], v[196:199], v[96:99]
	v_mfma_f32_16x16x32_bf16 v[84:87], v[172:175], v[216:219], v[84:87]
	v_mfma_f32_16x16x32_bf16 v[80:83], v[180:183], v[216:219], v[80:83]
	v_mfma_f32_16x16x32_bf16 v[68:71], v[172:175], v[224:227], v[68:71]
	v_mfma_f32_16x16x32_bf16 v[64:67], v[180:183], v[224:227], v[64:67]
	s_barrier
; #define PG8_STAGE(bufoff, gbase, voff) do { _Pragma("unroll") for (int _i = 0; _i < 2; ++_i) \
;         __builtin_amdgcn_global_load_lds((const unsigned*)((const char*)(gbase) + (voff)[_i]), (LAS unsigned*)(lds + (bufoff) + ldsw + _i * 8192), 16, 0, 0); } while (0)
; #define PG8_LDA(dst, b, h) do { _Pragma("unroll") for (int m = 0; m < 4; ++m) _Pragma("unroll") for (int k = 0; k < 2; ++k) dst[m][k] = *(const LAS bf16x8*)(lds + PG8_SA(b, h) + aoff + m * 2048 + k * 1024); } while (0)
; #define PG8_MMA(ai, bj, At, Bt) do { __builtin_amdgcn_s_setprio(1); _Pragma("unroll") for (int m = 0; m < 4; ++m) _Pragma("unroll") for (int n = 0; n < 2; ++n) _Pragma("unroll") for (int k = 0; k < 2; ++k) \
;         acc[ai][bj][m][n] = __builtin_amdgcn_mfma_f32_16x16x32_bf16(Bt[n][k], At[m][k], acc[ai][bj][m][n], 0, 0, 0); __builtin_amdgcn_s_setprio(0); } while (0)
; #define PG8_WAIT_V(n) asm volatile("s_waitcnt vmcnt(" #n ")" ::: "memory")
; #define PG8_WAIT_L(n) asm volatile("s_waitcnt lgkmcnt(" #n ")" ::: "memory")
; #define PG8_BAR __builtin_amdgcn_s_barrier()
; #define PG8_SCHED __builtin_amdgcn_sched_barrier(0)
; template <class Epi, bool HAS_MID>
; __device__ __forceinline__ void gemm_phase(LAS unsigned char* lds, const Gemm g, const Sched& S, const Epi& E) {
;     ...
;             PG8_LDA(At, 1, 1); PG8_STAGE(PG8_SB(1, 0), b3, voffB); PG8_STAGE(PG8_SB(1, 1), b3 + hstepB, voffB); PG8_STAGE(PG8_SA(1, 0), a3, voffA);
;             PG8_WAIT_V(8); PG8_WAIT_L(0); PG8_BAR; PG8_MMA(1, 0, At, B0); PG8_MMA(1, 1, At, B1); PG8_BAR; PG8_SCHED;
;         }
;         if (wr == 0) PG8_BAR;
	s_add_i32 s30, s30, s61
	v_lshl_add_u64 v[140:141], v[140:141], 0, s[38:39]
	s_mov_b32 m0, s30
	ds_read_b128 v[184:187], v144 offset:49152
	ds_read_b128 v[188:191], v144 offset:50176
	ds_read_b128 v[192:195], v144 offset:51200
	ds_read_b128 v[196:199], v144 offset:52224
	ds_read_b128 v[200:203], v144 offset:53248
	ds_read_b128 v[216:219], v144 offset:54272
	ds_read_b128 v[220:223], v144 offset:55296
	ds_read_b128 v[224:227], v144 offset:56320
	global_load_lds_dwordx4 v[140:141], off
	s_add_i32 m0, s30, 0x2000
	s_add_u32 s64, s72, 0x20080
	v_lshl_add_u64 v[140:141], v[158:159], 0, s[38:39]
	s_addc_u32 s65, s73, 0
	s_add_i32 s30, s36, s61
	global_load_lds_dwordx4 v[140:141], off
	v_lshl_add_u64 v[140:141], s[64:65], 0, v[132:133]
	s_mov_b32 m0, s30
	s_nop 0
	global_load_lds_dwordx4 v[140:141], off
	v_lshl_add_u64 v[140:141], s[64:65], 0, v[128:129]
	s_add_i32 m0, s30, 0x2000
	s_nop 0
	global_load_lds_dwordx4 v[140:141], off
	v_lshl_add_u64 v[140:141], v[204:205], 0, s[38:39]
	s_mov_b32 m0, s10
	s_nop 0
	global_load_lds_dwordx4 v[140:141], off
	v_lshl_add_u64 v[140:141], v[208:209], 0, s[38:39]
	s_mov_b32 m0, s81
	s_nop 0
	global_load_lds_dwordx4 v[140:141], off
	s_waitcnt vmcnt(8)
	s_waitcnt lgkmcnt(0)
	s_barrier
	s_waitcnt lgkmcnt(0)
	v_mfma_f32_16x16x32_bf16 v[60:63], v[146:149], v[184:187], v[60:63]
	v_mfma_f32_16x16x32_bf16 v[56:59], v[154:157], v[184:187], v[56:59]
	v_mfma_f32_16x16x32_bf16 v[44:47], v[146:149], v[192:195], v[44:47]
	v_mfma_f32_16x16x32_bf16 v[40:43], v[154:157], v[192:195], v[40:43]
	v_mfma_f32_16x16x32_bf16 v[28:31], v[146:149], v[200:203], v[28:31]
	v_mfma_f32_16x16x32_bf16 v[24:27], v[154:157], v[200:203], v[24:27]
	v_mfma_f32_16x16x32_bf16 v[12:15], v[146:149], v[220:223], v[12:15]
	v_mfma_f32_16x16x32_bf16 v[8:11], v[154:157], v[220:223], v[8:11]
	v_mfma_f32_16x16x32_bf16 v[60:63], v[150:153], v[188:191], v[60:63]
	v_mfma_f32_16x16x32_bf16 v[56:59], v[164:167], v[188:191], v[56:59]
	v_mfma_f32_16x16x32_bf16 v[44:47], v[150:153], v[196:199], v[44:47]
	v_mfma_f32_16x16x32_bf16 v[40:43], v[164:167], v[196:199], v[40:43]
	v_mfma_f32_16x16x32_bf16 v[28:31], v[150:153], v[216:219], v[28:31]
	v_mfma_f32_16x16x32_bf16 v[24:27], v[164:167], v[216:219], v[24:27]
	v_mfma_f32_16x16x32_bf16 v[12:15], v[150:153], v[224:227], v[12:15]
	v_mfma_f32_16x16x32_bf16 v[8:11], v[164:167], v[224:227], v[8:11]
	v_mfma_f32_16x16x32_bf16 v[52:55], v[168:171], v[184:187], v[52:55]
	v_mfma_f32_16x16x32_bf16 v[48:51], v[176:179], v[184:187], v[48:51]
	v_mfma_f32_16x16x32_bf16 v[36:39], v[168:171], v[192:195], v[36:39]
	v_mfma_f32_16x16x32_bf16 v[32:35], v[176:179], v[192:195], v[32:35]
	v_mfma_f32_16x16x32_bf16 v[20:23], v[168:171], v[200:203], v[20:23]
	v_mfma_f32_16x16x32_bf16 v[16:19], v[176:179], v[200:203], v[16:19]
	v_mfma_f32_16x16x32_bf16 v[4:7], v[168:171], v[220:223], v[4:7]
	v_mfma_f32_16x16x32_bf16 v[0:3], v[176:179], v[220:223], v[0:3]
	v_mfma_f32_16x16x32_bf16 v[52:55], v[172:175], v[188:191], v[52:55]
	v_mfma_f32_16x16x32_bf16 v[48:51], v[180:183], v[188:191], v[48:51]
	v_mfma_f32_16x16x32_bf16 v[36:39], v[172:175], v[196:199], v[36:39]
	v_mfma_f32_16x16x32_bf16 v[32:35], v[180:183], v[196:199], v[32:35]
	v_mfma_f32_16x16x32_bf16 v[20:23], v[172:175], v[216:219], v[20:23]
	v_mfma_f32_16x16x32_bf16 v[16:19], v[180:183], v[216:219], v[16:19]
	v_mfma_f32_16x16x32_bf16 v[4:7], v[172:175], v[224:227], v[4:7]
	v_mfma_f32_16x16x32_bf16 v[0:3], v[180:183], v[224:227], v[0:3]
	s_barrier
	s_add_i32 s52, s52, 2
	s_add_u32 s48, s48, 0x100
	s_addc_u32 s51, s51, 0
	s_cmp_gt_u32 s52, 5
	s_mov_b64 s[70:71], s[4:5]
	s_cbranch_scc0 .LBB0_1225
	s_and_b64 vcc, exec, s[22:23]
	s_cbranch_vccz .LBB0_1228
	s_barrier

; #define PG8_STAGE(bufoff, gbase, voff) do { _Pragma("unroll") for (int _i = 0; _i < 2; ++_i) \
;         __builtin_amdgcn_global_load_lds((const unsigned*)((const char*)(gbase) + (voff)[_i]), (LAS unsigned*)(lds + (bufoff) + ldsw + _i * 8192), 16, 0, 0); } while (0)
; #define PG8_LDA(dst, b, h) do { _Pragma("unroll") for (int m = 0; m < 4; ++m) _Pragma("unroll") for (int k = 0; k < 2; ++k) dst[m][k] = *(const LAS bf16x8*)(lds + PG8_SA(b, h) + aoff + m * 2048 + k * 1024); } while (0)
; #define PG8_LDB(dst, b, h) do { _Pragma("unroll") for (int n = 0; n < 2; ++n) _Pragma("unroll") for (int k = 0; k < 2; ++k) dst[n][k] = *(const LAS bf16x8*)(lds + PG8_SB(b, h) + boff + n * 2048 + k * 1024); } while (0)
; #define PG8_WAIT_V(n) asm volatile("s_waitcnt vmcnt(" #n ")" ::: "memory")
; #define PG8_WAIT_L(n) asm volatile("s_waitcnt lgkmcnt(" #n ")" ::: "memory")
; template <class Epi, bool HAS_MID>
; __device__ __forceinline__ void gemm_phase(LAS unsigned char* lds, const Gemm g, const Sched& S, const Epi& E) {
;     ...
;         for (int t = 0; t < nt; t += 2) {
;             const bool last = (t == nt - 2);
;             const char* a1 = PG8_APT(t + 1);
;             const char* a2 = last ? nA : PG8_APT(t + 2); const char* b2 = last ? nB : cB + (size_t)(t + 2) * kstep;
;             const char* a3 = a2 + kstep; const char* b3 = b2 + kstep;
;             PG8_LDB(B0, 0, 0); PG8_LDB(B1, 0, 1); PG8_SCHED; PG8_LDA(At, 0, 0); PG8_STAGE(PG8_SA(1, 1), a1 + hstepA, voffA);
;             PG8_WAIT_V(8); PG8_WAIT_L(0); PG8_BAR; PG8_MMA(0, 0, At, B0); PG8_MMA(0, 1, At, B1); PG8_BAR; PG8_SCHED;
;             PG8_LDA(At, 0, 1); PG8_STAGE(PG8_SB(0, 0), b2, voffB); PG8_STAGE(PG8_SB(0, 1), b2 + hstepB, voffB); PG8_STAGE(PG8_SA(0, 0), a2, voffA);
;             PG8_WAIT_V(8); PG8_WAIT_L(0); PG8_BAR; PG8_MMA(1, 0, At, B0); PG8_MMA(1, 1, At, B1); PG8_BAR; PG8_SCHED;
;             PG8_LDB(B0, 1, 0); PG8_LDB(B1, 1, 1); PG8_SCHED; PG8_LDA(At, 1, 0); PG8_STAGE(PG8_SA(0, 1), a2 + hstepA, voffA);
;             PG8_WAIT_V(8); PG8_WAIT_L(0); PG8_BAR; PG8_MMA(0, 0, At, B0); PG8_MMA(0, 1, At, B1); PG8_BAR; PG8_SCHED;
;             PG8_LDA(At, 1, 1); PG8_STAGE(PG8_SB(1, 0), b3, voffB); PG8_STAGE(PG8_SB(1, 1), b3 + hstepB, voffB); PG8_STAGE(PG8_SA(1, 0), a3, voffA);
;             PG8_WAIT_V(8); PG8_WAIT_L(0); PG8_BAR; PG8_MMA(1, 0, At, B0); PG8_MMA(1, 1, At, B1); PG8_BAR; PG8_SCHED;
.LBB0_1543:
	s_add_u32 s30, s68, 0xfff80080
	s_addc_u32 s36, s69, -1
	s_add_i32 s37, 0, 0x10000
	s_cmp_eq_u32 s48, 28
	s_cselect_b32 s73, s21, s36
	s_cselect_b32 s72, s35, s30
	s_cselect_b32 s71, s19, s43
	s_cselect_b32 s70, s40, s42
	s_add_i32 s30, 0, 0x14000
	v_add_u32_e32 v150, s37, v155
	v_add_u32_e32 v158, s30, v155
	ds_read_b128 v[128:131], v150
	ds_read_b128 v[142:145], v150 offset:1024
	ds_read_b128 v[146:149], v150 offset:2048
	ds_read_b128 v[150:153], v150 offset:3072
	ds_read_b128 v[164:167], v158
	ds_read_b128 v[168:171], v158 offset:1024
	ds_read_b128 v[172:175], v158 offset:2048
	ds_read_b128 v[176:179], v158 offset:3072
	v_lshl_add_u64 v[158:159], s[68:69], 0, v[140:141]
	s_add_i32 m0, s74, 0xc000
	ds_read_b128 v[180:183], v157
	ds_read_b128 v[184:187], v157 offset:1024
	ds_read_b128 v[188:191], v157 offset:2048
	ds_read_b128 v[192:195], v157 offset:3072
	ds_read_b128 v[196:199], v157 offset:4096
	ds_read_b128 v[200:203], v157 offset:5120
	ds_read_b128 v[208:211], v157 offset:6144
	ds_read_b128 v[216:219], v157 offset:7168
	global_load_lds_dwordx4 v[158:159], off
	v_lshl_add_u64 v[158:159], s[68:69], 0, v[138:139]
	s_add_i32 m0, s74, 0xe000
	s_nop 0
	global_load_lds_dwordx4 v[158:159], off
	s_waitcnt vmcnt(8)
	s_waitcnt lgkmcnt(0)
	s_barrier
	s_waitcnt lgkmcnt(0)
	v_mfma_f32_16x16x32_bf16 v[124:127], v[128:131], v[180:183], v[124:127]
	v_mfma_f32_16x16x32_bf16 v[120:123], v[146:149], v[180:183], v[120:123]
	v_mfma_f32_16x16x32_bf16 v[108:111], v[128:131], v[188:191], v[108:111]
	v_mfma_f32_16x16x32_bf16 v[104:107], v[146:149], v[188:191], v[104:107]
	v_mfma_f32_16x16x32_bf16 v[92:95], v[128:131], v[196:199], v[92:95]
	v_mfma_f32_16x16x32_bf16 v[88:91], v[146:149], v[196:199], v[88:91]
	v_mfma_f32_16x16x32_bf16 v[76:79], v[128:131], v[208:211], v[76:79]
	v_mfma_f32_16x16x32_bf16 v[72:75], v[146:149], v[208:211], v[72:75]
	v_mfma_f32_16x16x32_bf16 v[124:127], v[142:145], v[184:187], v[124:127]
	v_mfma_f32_16x16x32_bf16 v[120:123], v[150:153], v[184:187], v[120:123]
	v_mfma_f32_16x16x32_bf16 v[108:111], v[142:145], v[192:195], v[108:111]
	v_mfma_f32_16x16x32_bf16 v[104:107], v[150:153], v[192:195], v[104:107]
	v_mfma_f32_16x16x32_bf16 v[92:95], v[142:145], v[200:203], v[92:95]
	v_mfma_f32_16x16x32_bf16 v[88:91], v[150:153], v[200:203], v[88:91]
	v_mfma_f32_16x16x32_bf16 v[76:79], v[142:145], v[216:219], v[76:79]
	v_mfma_f32_16x16x32_bf16 v[72:75], v[150:153], v[216:219], v[72:75]
	v_mfma_f32_16x16x32_bf16 v[116:119], v[164:167], v[180:183], v[116:119]
	v_mfma_f32_16x16x32_bf16 v[112:115], v[172:175], v[180:183], v[112:115]
	v_mfma_f32_16x16x32_bf16 v[100:103], v[164:167], v[188:191], v[100:103]
	v_mfma_f32_16x16x32_bf16 v[96:99], v[172:175], v[188:191], v[96:99]
	v_mfma_f32_16x16x32_bf16 v[84:87], v[164:167], v[196:199], v[84:87]
	v_mfma_f32_16x16x32_bf16 v[80:83], v[172:175], v[196:199], v[80:83]
	v_mfma_f32_16x16x32_bf16 v[68:71], v[164:167], v[208:211], v[68:71]
	v_mfma_f32_16x16x32_bf16 v[64:67], v[172:175], v[208:211], v[64:67]
	v_mfma_f32_16x16x32_bf16 v[116:119], v[168:171], v[184:187], v[116:119]
	v_mfma_f32_16x16x32_bf16 v[112:115], v[176:179], v[184:187], v[112:115]
	v_mfma_f32_16x16x32_bf16 v[100:103], v[168:171], v[192:195], v[100:103]
	v_mfma_f32_16x16x32_bf16 v[96:99], v[176:179], v[192:195], v[96:99]
	v_mfma_f32_16x16x32_bf16 v[84:87], v[168:171], v[200:203], v[84:87]
	v_mfma_f32_16x16x32_bf16 v[80:83], v[176:179], v[200:203], v[80:83]
	v_mfma_f32_16x16x32_bf16 v[68:71], v[168:171], v[216:219], v[68:71]
	v_mfma_f32_16x16x32_bf16 v[64:67], v[176:179], v[216:219], v[64:67]
	s_barrier
	s_add_i32 s36, s37, s61
	v_lshl_add_u64 v[158:159], s[70:71], 0, v[160:161]
	s_mov_b32 m0, s36
	ds_read_b128 v[180:183], v157 offset:16384
	ds_read_b128 v[184:187], v157 offset:17408
	ds_read_b128 v[188:191], v157 offset:18432
	ds_read_b128 v[192:195], v157 offset:19456
	ds_read_b128 v[196:199], v157 offset:20480
	ds_read_b128 v[200:203], v157 offset:21504
	ds_read_b128 v[208:211], v157 offset:22528
	ds_read_b128 v[216:219], v157 offset:23552
	global_load_lds_dwordx4 v[158:159], off
	s_add_i32 m0, s36, 0x2000
	s_add_u32 s64, s70, 0x100000
	v_lshl_add_u64 v[204:205], s[70:71], 0, v[136:137]
	s_addc_u32 s65, s71, 0
	s_add_i32 s30, s30, s61
	global_load_lds_dwordx4 v[204:205], off
	v_lshl_add_u64 v[220:221], s[64:65], 0, v[160:161]
	s_mov_b32 m0, s30
	v_lshl_add_u64 v[222:223], s[72:73], 0, v[134:135]
	global_load_lds_dwordx4 v[220:221], off
	v_lshl_add_u64 v[220:221], s[64:65], 0, v[136:137]
	s_add_i32 m0, s30, 0x2000
	s_nop 0
	global_load_lds_dwordx4 v[220:221], off
	v_lshl_add_u64 v[220:221], s[72:73], 0, v[132:133]
	s_mov_b32 m0, s74
	s_nop 0
	global_load_lds_dwordx4 v[220:221], off
	s_mov_b32 m0, s75
	s_nop 0
	global_load_lds_dwordx4 v[222:223], off
	s_waitcnt vmcnt(8)
	s_waitcnt lgkmcnt(0)
	s_barrier
; #define PG8_STAGE(bufoff, gbase, voff) do { _Pragma("unroll") for (int _i = 0; _i < 2; ++_i) \
;         __builtin_amdgcn_global_load_lds((const unsigned*)((const char*)(gbase) + (voff)[_i]), (LAS unsigned*)(lds + (bufoff) + ldsw + _i * 8192), 16, 0, 0); } while (0)
; #define PG8_LDA(dst, b, h) do { _Pragma("unroll") for (int m = 0; m < 4; ++m) _Pragma("unroll") for (int k = 0; k < 2; ++k) dst[m][k] = *(const LAS bf16x8*)(lds + PG8_SA(b, h) + aoff + m * 2048 + k * 1024); } while (0)
; #define PG8_LDB(dst, b, h) do { _Pragma("unroll") for (int n = 0; n < 2; ++n) _Pragma("unroll") for (int k = 0; k < 2; ++k) dst[n][k] = *(const LAS bf16x8*)(lds + PG8_SB(b, h) + boff + n * 2048 + k * 1024); } while (0)
; #define PG8_MMA(ai, bj, At, Bt) do { __builtin_amdgcn_s_setprio(1); _Pragma("unroll") for (int m = 0; m < 4; ++m) _Pragma("unroll") for (int n = 0; n < 2; ++n) _Pragma("unroll") for (int k = 0; k < 2; ++k) \
;         acc[ai][bj][m][n] = __builtin_amdgcn_mfma_f32_16x16x32_bf16(Bt[n][k], At[m][k], acc[ai][bj][m][n], 0, 0, 0); __builtin_amdgcn_s_setprio(0); } while (0)
; #define PG8_WAIT_V(n) asm volatile("s_waitcnt vmcnt(" #n ")" ::: "memory")
; #define PG8_WAIT_L(n) asm volatile("s_waitcnt lgkmcnt(" #n ")" ::: "memory")
; #define PG8_BAR __builtin_amdgcn_s_barrier()
; #define PG8_SCHED __builtin_amdgcn_sched_barrier(0)
; template <class Epi, bool HAS_MID>
; __device__ __forceinline__ void gemm_phase(LAS unsigned char* lds, const Gemm g, const Sched& S, const Epi& E) {
;     ...
;             PG8_WAIT_V(8); PG8_WAIT_L(0); PG8_BAR; PG8_MMA(1, 0, At, B0); PG8_MMA(1, 1, At, B1); PG8_BAR; PG8_SCHED;
;             PG8_LDB(B0, 1, 0); PG8_LDB(B1, 1, 1); PG8_SCHED; PG8_LDA(At, 1, 0); PG8_STAGE(PG8_SA(0, 1), a2 + hstepA, voffA);
;             PG8_WAIT_V(8); PG8_WAIT_L(0); PG8_BAR; PG8_MMA(0, 0, At, B0); PG8_MMA(0, 1, At, B1); PG8_BAR; PG8_SCHED;
;             PG8_LDA(At, 1, 1); PG8_STAGE(PG8_SB(1, 0), b3, voffB); PG8_STAGE(PG8_SB(1, 1), b3 + hstepB, voffB); PG8_STAGE(PG8_SA(1, 0), a3, voffA);
	s_waitcnt lgkmcnt(0)
	v_mfma_f32_16x16x32_bf16 v[60:63], v[128:131], v[180:183], v[60:63]
	v_mfma_f32_16x16x32_bf16 v[56:59], v[146:149], v[180:183], v[56:59]
	v_mfma_f32_16x16x32_bf16 v[44:47], v[128:131], v[188:191], v[44:47]
	v_mfma_f32_16x16x32_bf16 v[40:43], v[146:149], v[188:191], v[40:43]
	v_mfma_f32_16x16x32_bf16 v[28:31], v[128:131], v[196:199], v[28:31]
	v_mfma_f32_16x16x32_bf16 v[24:27], v[146:149], v[196:199], v[24:27]
	v_mfma_f32_16x16x32_bf16 v[12:15], v[128:131], v[208:211], v[12:15]
	v_mfma_f32_16x16x32_bf16 v[8:11], v[146:149], v[208:211], v[8:11]
	v_mfma_f32_16x16x32_bf16 v[60:63], v[142:145], v[184:187], v[60:63]
	v_mfma_f32_16x16x32_bf16 v[56:59], v[150:153], v[184:187], v[56:59]
	v_mfma_f32_16x16x32_bf16 v[44:47], v[142:145], v[192:195], v[44:47]
	v_mfma_f32_16x16x32_bf16 v[40:43], v[150:153], v[192:195], v[40:43]
	v_mfma_f32_16x16x32_bf16 v[28:31], v[142:145], v[200:203], v[28:31]
	v_mfma_f32_16x16x32_bf16 v[24:27], v[150:153], v[200:203], v[24:27]
	v_mfma_f32_16x16x32_bf16 v[12:15], v[142:145], v[216:219], v[12:15]
	v_mfma_f32_16x16x32_bf16 v[8:11], v[150:153], v[216:219], v[8:11]
	v_mfma_f32_16x16x32_bf16 v[52:55], v[164:167], v[180:183], v[52:55]
	v_mfma_f32_16x16x32_bf16 v[48:51], v[172:175], v[180:183], v[48:51]
	v_mfma_f32_16x16x32_bf16 v[36:39], v[164:167], v[188:191], v[36:39]
	v_mfma_f32_16x16x32_bf16 v[32:35], v[172:175], v[188:191], v[32:35]
	v_mfma_f32_16x16x32_bf16 v[20:23], v[164:167], v[196:199], v[20:23]
	v_mfma_f32_16x16x32_bf16 v[16:19], v[172:175], v[196:199], v[16:19]
	v_mfma_f32_16x16x32_bf16 v[4:7], v[164:167], v[208:211], v[4:7]
	v_mfma_f32_16x16x32_bf16 v[0:3], v[172:175], v[208:211], v[0:3]
	v_mfma_f32_16x16x32_bf16 v[52:55], v[168:171], v[184:187], v[52:55]
	v_mfma_f32_16x16x32_bf16 v[48:51], v[176:179], v[184:187], v[48:51]
	v_mfma_f32_16x16x32_bf16 v[36:39], v[168:171], v[192:195], v[36:39]
	v_mfma_f32_16x16x32_bf16 v[32:35], v[176:179], v[192:195], v[32:35]
	v_mfma_f32_16x16x32_bf16 v[20:23], v[168:171], v[200:203], v[20:23]
	v_mfma_f32_16x16x32_bf16 v[16:19], v[176:179], v[200:203], v[16:19]
	v_mfma_f32_16x16x32_bf16 v[4:7], v[168:171], v[216:219], v[4:7]
	v_mfma_f32_16x16x32_bf16 v[0:3], v[176:179], v[216:219], v[0:3]
	s_barrier
	s_add_i32 s30, 0, 0x18000
	s_add_i32 s36, 0, 0x1c000
	v_add_u32_e32 v150, s30, v155
	v_add_u32_e32 v176, s36, v155
	ds_read_b128 v[128:131], v150
	ds_read_b128 v[142:145], v150 offset:1024
	ds_read_b128 v[146:149], v150 offset:2048
	ds_read_b128 v[150:153], v150 offset:3072
	ds_read_b128 v[164:167], v176
	ds_read_b128 v[168:171], v176 offset:1024
	ds_read_b128 v[172:175], v176 offset:2048
	ds_read_b128 v[176:179], v176 offset:3072
	s_add_u32 s64, s72, 0x80000
	s_addc_u32 s65, s73, 0
	s_mov_b32 m0, s76
	v_lshl_add_u64 v[224:225], s[64:65], 0, v[132:133]
	ds_read_b128 v[180:183], v157 offset:32768
	ds_read_b128 v[184:187], v157 offset:33792
	ds_read_b128 v[188:191], v157 offset:34816
	ds_read_b128 v[192:195], v157 offset:35840
	ds_read_b128 v[196:199], v157 offset:36864
	ds_read_b128 v[200:203], v157 offset:37888
	ds_read_b128 v[208:211], v157 offset:38912
	ds_read_b128 v[216:219], v157 offset:39936
	global_load_lds_dwordx4 v[224:225], off
	v_lshl_add_u64 v[224:225], s[64:65], 0, v[134:135]
	s_mov_b32 m0, s77
	s_nop 0
	global_load_lds_dwordx4 v[224:225], off
	s_waitcnt vmcnt(8)
	s_waitcnt lgkmcnt(0)
	s_barrier
	s_waitcnt lgkmcnt(0)
	v_mfma_f32_16x16x32_bf16 v[124:127], v[128:131], v[180:183], v[124:127]
	v_mfma_f32_16x16x32_bf16 v[120:123], v[146:149], v[180:183], v[120:123]
	v_mfma_f32_16x16x32_bf16 v[108:111], v[128:131], v[188:191], v[108:111]
	v_mfma_f32_16x16x32_bf16 v[104:107], v[146:149], v[188:191], v[104:107]
	v_mfma_f32_16x16x32_bf16 v[92:95], v[128:131], v[196:199], v[92:95]
	v_mfma_f32_16x16x32_bf16 v[88:91], v[146:149], v[196:199], v[88:91]
	v_mfma_f32_16x16x32_bf16 v[76:79], v[128:131], v[208:211], v[76:79]
	v_mfma_f32_16x16x32_bf16 v[72:75], v[146:149], v[208:211], v[72:75]
	v_mfma_f32_16x16x32_bf16 v[124:127], v[142:145], v[184:187], v[124:127]
	v_mfma_f32_16x16x32_bf16 v[120:123], v[150:153], v[184:187], v[120:123]
	v_mfma_f32_16x16x32_bf16 v[108:111], v[142:145], v[192:195], v[108:111]
	v_mfma_f32_16x16x32_bf16 v[104:107], v[150:153], v[192:195], v[104:107]
	v_mfma_f32_16x16x32_bf16 v[92:95], v[142:145], v[200:203], v[92:95]
	v_mfma_f32_16x16x32_bf16 v[88:91], v[150:153], v[200:203], v[88:91]
	v_mfma_f32_16x16x32_bf16 v[76:79], v[142:145], v[216:219], v[76:79]
	v_mfma_f32_16x16x32_bf16 v[72:75], v[150:153], v[216:219], v[72:75]
	v_mfma_f32_16x16x32_bf16 v[116:119], v[164:167], v[180:183], v[116:119]
	v_mfma_f32_16x16x32_bf16 v[112:115], v[172:175], v[180:183], v[112:115]
	v_mfma_f32_16x16x32_bf16 v[100:103], v[164:167], v[188:191], v[100:103]
	v_mfma_f32_16x16x32_bf16 v[96:99], v[172:175], v[188:191], v[96:99]
	v_mfma_f32_16x16x32_bf16 v[84:87], v[164:167], v[196:199], v[84:87]
	v_mfma_f32_16x16x32_bf16 v[80:83], v[172:175], v[196:199], v[80:83]
	v_mfma_f32_16x16x32_bf16 v[68:71], v[164:167], v[208:211], v[68:71]
	v_mfma_f32_16x16x32_bf16 v[64:67], v[172:175], v[208:211], v[64:67]
	v_mfma_f32_16x16x32_bf16 v[116:119], v[168:171], v[184:187], v[116:119]
	v_mfma_f32_16x16x32_bf16 v[112:115], v[176:179], v[184:187], v[112:115]
	v_mfma_f32_16x16x32_bf16 v[100:103], v[168:171], v[192:195], v[100:103]
	v_mfma_f32_16x16x32_bf16 v[96:99], v[176:179], v[192:195], v[96:99]
	v_mfma_f32_16x16x32_bf16 v[84:87], v[168:171], v[200:203], v[84:87]
	v_mfma_f32_16x16x32_bf16 v[80:83], v[176:179], v[200:203], v[80:83]
	v_mfma_f32_16x16x32_bf16 v[68:71], v[168:171], v[216:219], v[68:71]
	v_mfma_f32_16x16x32_bf16 v[64:67], v[176:179], v[216:219], v[64:67]
	s_barrier
; #define PG8_STAGE(bufoff, gbase, voff) do { _Pragma("unroll") for (int _i = 0; _i < 2; ++_i) \
;         __builtin_amdgcn_global_load_lds((const unsigned*)((const char*)(gbase) + (voff)[_i]), (LAS unsigned*)(lds + (bufoff) + ldsw + _i * 8192), 16, 0, 0); } while (0)
; #define PG8_LDA(dst, b, h) do { _Pragma("unroll") for (int m = 0; m < 4; ++m) _Pragma("unroll") for (int k = 0; k < 2; ++k) dst[m][k] = *(const LAS bf16x8*)(lds + PG8_SA(b, h) + aoff + m * 2048 + k * 1024); } while (0)
; #define PG8_MMA(ai, bj, At, Bt) do { __builtin_amdgcn_s_setprio(1); _Pragma("unroll") for (int m = 0; m < 4; ++m) _Pragma("unroll") for (int n = 0; n < 2; ++n) _Pragma("unroll") for (int k = 0; k < 2; ++k) \
;         acc[ai][bj][m][n] = __builtin_amdgcn_mfma_f32_16x16x32_bf16(Bt[n][k], At[m][k], acc[ai][bj][m][n], 0, 0, 0); __builtin_amdgcn_s_setprio(0); } while (0)
; #define PG8_WAIT_V(n) asm volatile("s_waitcnt vmcnt(" #n ")" ::: "memory")
; #define PG8_WAIT_L(n) asm volatile("s_waitcnt lgkmcnt(" #n ")" ::: "memory")
; #define PG8_BAR __builtin_amdgcn_s_barrier()
; #define PG8_SCHED __builtin_amdgcn_sched_barrier(0)
; template <class Epi, bool HAS_MID>
; __device__ __forceinline__ void gemm_phase(LAS unsigned char* lds, const Gemm g, const Sched& S, const Epi& E) {
;     ...
;             PG8_LDA(At, 1, 1); PG8_STAGE(PG8_SB(1, 0), b3, voffB); PG8_STAGE(PG8_SB(1, 1), b3 + hstepB, voffB); PG8_STAGE(PG8_SA(1, 0), a3, voffA);
;             PG8_WAIT_V(8); PG8_WAIT_L(0); PG8_BAR; PG8_MMA(1, 0, At, B0); PG8_MMA(1, 1, At, B1); PG8_BAR; PG8_SCHED;
;         }
;         if (wr == 0) PG8_BAR;
	s_add_i32 s30, s30, s61
	v_lshl_add_u64 v[158:159], v[158:159], 0, s[38:39]
	s_mov_b32 m0, s30
	ds_read_b128 v[180:183], v157 offset:49152
	ds_read_b128 v[184:187], v157 offset:50176
	ds_read_b128 v[188:191], v157 offset:51200
	ds_read_b128 v[192:195], v157 offset:52224
	ds_read_b128 v[196:199], v157 offset:53248
	ds_read_b128 v[200:203], v157 offset:54272
	ds_read_b128 v[208:211], v157 offset:55296
	ds_read_b128 v[216:219], v157 offset:56320
	global_load_lds_dwordx4 v[158:159], off
	s_add_i32 m0, s30, 0x2000
	s_add_u32 s64, s70, 0x100080
	v_lshl_add_u64 v[158:159], v[204:205], 0, s[38:39]
	s_addc_u32 s65, s71, 0
	s_add_i32 s30, s36, s61
	global_load_lds_dwordx4 v[158:159], off
	v_lshl_add_u64 v[158:159], s[64:65], 0, v[160:161]
	s_mov_b32 m0, s30
	s_nop 0
	global_load_lds_dwordx4 v[158:159], off
	v_lshl_add_u64 v[158:159], s[64:65], 0, v[136:137]
	s_add_i32 m0, s30, 0x2000
	s_nop 0
	global_load_lds_dwordx4 v[158:159], off
	v_lshl_add_u64 v[158:159], v[220:221], 0, s[38:39]
	s_mov_b32 m0, s78
	s_nop 0
	global_load_lds_dwordx4 v[158:159], off
	v_lshl_add_u64 v[158:159], v[222:223], 0, s[38:39]
	s_mov_b32 m0, s79
	s_nop 0
	global_load_lds_dwordx4 v[158:159], off
	s_waitcnt vmcnt(8)
	s_waitcnt lgkmcnt(0)
	s_barrier
	s_waitcnt lgkmcnt(0)
	v_mfma_f32_16x16x32_bf16 v[60:63], v[128:131], v[180:183], v[60:63]
	v_mfma_f32_16x16x32_bf16 v[56:59], v[146:149], v[180:183], v[56:59]
	v_mfma_f32_16x16x32_bf16 v[44:47], v[128:131], v[188:191], v[44:47]
	v_mfma_f32_16x16x32_bf16 v[40:43], v[146:149], v[188:191], v[40:43]
	v_mfma_f32_16x16x32_bf16 v[28:31], v[128:131], v[196:199], v[28:31]
	v_mfma_f32_16x16x32_bf16 v[24:27], v[146:149], v[196:199], v[24:27]
	v_mfma_f32_16x16x32_bf16 v[12:15], v[128:131], v[208:211], v[12:15]
	v_mfma_f32_16x16x32_bf16 v[8:11], v[146:149], v[208:211], v[8:11]
	v_mfma_f32_16x16x32_bf16 v[60:63], v[142:145], v[184:187], v[60:63]
	v_mfma_f32_16x16x32_bf16 v[56:59], v[150:153], v[184:187], v[56:59]
	v_mfma_f32_16x16x32_bf16 v[44:47], v[142:145], v[192:195], v[44:47]
	v_mfma_f32_16x16x32_bf16 v[40:43], v[150:153], v[192:195], v[40:43]
	v_mfma_f32_16x16x32_bf16 v[28:31], v[142:145], v[200:203], v[28:31]
	v_mfma_f32_16x16x32_bf16 v[24:27], v[150:153], v[200:203], v[24:27]
	v_mfma_f32_16x16x32_bf16 v[12:15], v[142:145], v[216:219], v[12:15]
	v_mfma_f32_16x16x32_bf16 v[8:11], v[150:153], v[216:219], v[8:11]
	v_mfma_f32_16x16x32_bf16 v[52:55], v[164:167], v[180:183], v[52:55]
	v_mfma_f32_16x16x32_bf16 v[48:51], v[172:175], v[180:183], v[48:51]
	v_mfma_f32_16x16x32_bf16 v[36:39], v[164:167], v[188:191], v[36:39]
	v_mfma_f32_16x16x32_bf16 v[32:35], v[172:175], v[188:191], v[32:35]
	v_mfma_f32_16x16x32_bf16 v[20:23], v[164:167], v[196:199], v[20:23]
	v_mfma_f32_16x16x32_bf16 v[16:19], v[172:175], v[196:199], v[16:19]
	v_mfma_f32_16x16x32_bf16 v[4:7], v[164:167], v[208:211], v[4:7]
	v_mfma_f32_16x16x32_bf16 v[0:3], v[172:175], v[208:211], v[0:3]
	v_mfma_f32_16x16x32_bf16 v[52:55], v[168:171], v[184:187], v[52:55]
	v_mfma_f32_16x16x32_bf16 v[48:51], v[176:179], v[184:187], v[48:51]
	v_mfma_f32_16x16x32_bf16 v[36:39], v[168:171], v[192:195], v[36:39]
	v_mfma_f32_16x16x32_bf16 v[32:35], v[176:179], v[192:195], v[32:35]
	v_mfma_f32_16x16x32_bf16 v[20:23], v[168:171], v[200:203], v[20:23]
	v_mfma_f32_16x16x32_bf16 v[16:19], v[176:179], v[200:203], v[16:19]
	v_mfma_f32_16x16x32_bf16 v[4:7], v[168:171], v[216:219], v[4:7]
	v_mfma_f32_16x16x32_bf16 v[0:3], v[176:179], v[216:219], v[0:3]
	s_barrier
	s_add_i32 s48, s48, 2
	s_add_u32 s42, s42, 0x100
	s_addc_u32 s43, s43, 0
	s_add_u32 s68, s68, 0x100
	s_addc_u32 s69, s69, 0
	s_cmp_gt_u32 s48, 29
	s_cbranch_scc0 .LBB0_1543
	s_and_b64 vcc, exec, s[16:17]
	s_cbranch_vccz .LBB0_1546
	s_barrier

; #define PG8_STAGE(bufoff, gbase, voff) do { _Pragma("unroll") for (int _i = 0; _i < 2; ++_i) \
;         __builtin_amdgcn_global_load_lds((const unsigned*)((const char*)(gbase) + (voff)[_i]), (LAS unsigned*)(lds + (bufoff) + ldsw + _i * 8192), 16, 0, 0); } while (0)
; #define PG8_LDA(dst, b, h) do { _Pragma("unroll") for (int m = 0; m < 4; ++m) _Pragma("unroll") for (int k = 0; k < 2; ++k) dst[m][k] = *(const LAS bf16x8*)(lds + PG8_SA(b, h) + aoff + m * 2048 + k * 1024); } while (0)
; #define PG8_LDB(dst, b, h) do { _Pragma("unroll") for (int n = 0; n < 2; ++n) _Pragma("unroll") for (int k = 0; k < 2; ++k) dst[n][k] = *(const LAS bf16x8*)(lds + PG8_SB(b, h) + boff + n * 2048 + k * 1024); } while (0)
; #define PG8_WAIT_V(n) asm volatile("s_waitcnt vmcnt(" #n ")" ::: "memory")
; #define PG8_WAIT_L(n) asm volatile("s_waitcnt lgkmcnt(" #n ")" ::: "memory")
; template <class Epi, bool HAS_MID>
; __device__ __forceinline__ void gemm_phase(LAS unsigned char* lds, const Gemm g, const Sched& S, const Epi& E) {
;     ...
;         for (int t = 0; t < nt; t += 2) {
;             const bool last = (t == nt - 2);
;             const char* a1 = PG8_APT(t + 1);
;             const char* a2 = last ? nA : PG8_APT(t + 2); const char* b2 = last ? nB : cB + (size_t)(t + 2) * kstep;
;             const char* a3 = a2 + kstep; const char* b3 = b2 + kstep;
;             PG8_LDB(B0, 0, 0); PG8_LDB(B1, 0, 1); PG8_SCHED; PG8_LDA(At, 0, 0); PG8_STAGE(PG8_SA(1, 1), a1 + hstepA, voffA);
;             PG8_WAIT_V(8); PG8_WAIT_L(0); PG8_BAR; PG8_MMA(0, 0, At, B0); PG8_MMA(0, 1, At, B1); PG8_BAR; PG8_SCHED;
;             PG8_LDA(At, 0, 1); PG8_STAGE(PG8_SB(0, 0), b2, voffB); PG8_STAGE(PG8_SB(0, 1), b2 + hstepB, voffB); PG8_STAGE(PG8_SA(0, 0), a2, voffA);
;             PG8_WAIT_V(8); PG8_WAIT_L(0); PG8_BAR; PG8_MMA(1, 0, At, B0); PG8_MMA(1, 1, At, B1); PG8_BAR; PG8_SCHED;
;             PG8_LDB(B0, 1, 0); PG8_LDB(B1, 1, 1); PG8_SCHED; PG8_LDA(At, 1, 0); PG8_STAGE(PG8_SA(0, 1), a2 + hstepA, voffA);
;             PG8_WAIT_V(8); PG8_WAIT_L(0); PG8_BAR; PG8_MMA(0, 0, At, B0); PG8_MMA(0, 1, At, B1); PG8_BAR; PG8_SCHED;
;             PG8_LDA(At, 1, 1); PG8_STAGE(PG8_SB(1, 0), b3, voffB); PG8_STAGE(PG8_SB(1, 1), b3 + hstepB, voffB); PG8_STAGE(PG8_SA(1, 0), a3, voffA);
;             PG8_WAIT_V(8); PG8_WAIT_L(0); PG8_BAR; PG8_MMA(1, 0, At, B0); PG8_MMA(1, 1, At, B1); PG8_BAR; PG8_SCHED;
.LBB0_1562:
	s_add_u32 s30, s74, 0xfff80080
	s_addc_u32 s36, s75, -1
	s_add_i32 s37, 0, 0x10000
	s_cmp_eq_u32 s51, 28
	s_cselect_b32 s79, s27, s36
	s_cselect_b32 s78, s40, s30
	s_cselect_b32 s77, s25, s48
	s_cselect_b32 s76, s42, s43
	s_add_i32 s30, 0, 0x14000
	v_add_u32_e32 v150, s37, v158
	v_add_u32_e32 v154, s30, v158
	ds_read_b128 v[128:131], v150
	ds_read_b128 v[142:145], v150 offset:1024
	ds_read_b128 v[146:149], v150 offset:2048
	ds_read_b128 v[150:153], v150 offset:3072
	ds_read_b128 v[166:169], v154
	ds_read_b128 v[170:173], v154 offset:1024
	ds_read_b128 v[174:177], v154 offset:2048
	ds_read_b128 v[178:181], v154 offset:3072
	v_lshl_add_u64 v[154:155], s[74:75], 0, v[140:141]
	s_add_i32 m0, s83, 0xc000
	ds_read_b128 v[182:185], v164
	ds_read_b128 v[186:189], v164 offset:1024
	ds_read_b128 v[190:193], v164 offset:2048
	ds_read_b128 v[194:197], v164 offset:3072
	ds_read_b128 v[198:201], v164 offset:4096
	ds_read_b128 v[202:205], v164 offset:5120
	ds_read_b128 v[208:211], v164 offset:6144
	ds_read_b128 v[216:219], v164 offset:7168
	global_load_lds_dwordx4 v[154:155], off
	v_lshl_add_u64 v[154:155], s[74:75], 0, v[138:139]
	s_add_i32 m0, s83, 0xe000
	s_nop 0
	global_load_lds_dwordx4 v[154:155], off
	s_waitcnt vmcnt(8)
	s_waitcnt lgkmcnt(0)
	s_barrier
	s_waitcnt lgkmcnt(0)
	v_mfma_f32_16x16x32_bf16 v[124:127], v[128:131], v[182:185], v[124:127]
	v_mfma_f32_16x16x32_bf16 v[120:123], v[146:149], v[182:185], v[120:123]
	v_mfma_f32_16x16x32_bf16 v[108:111], v[128:131], v[190:193], v[108:111]
	v_mfma_f32_16x16x32_bf16 v[104:107], v[146:149], v[190:193], v[104:107]
	v_mfma_f32_16x16x32_bf16 v[92:95], v[128:131], v[198:201], v[92:95]
	v_mfma_f32_16x16x32_bf16 v[88:91], v[146:149], v[198:201], v[88:91]
	v_mfma_f32_16x16x32_bf16 v[76:79], v[128:131], v[208:211], v[76:79]
	v_mfma_f32_16x16x32_bf16 v[72:75], v[146:149], v[208:211], v[72:75]
	v_mfma_f32_16x16x32_bf16 v[124:127], v[142:145], v[186:189], v[124:127]
	v_mfma_f32_16x16x32_bf16 v[120:123], v[150:153], v[186:189], v[120:123]
	v_mfma_f32_16x16x32_bf16 v[108:111], v[142:145], v[194:197], v[108:111]
	v_mfma_f32_16x16x32_bf16 v[104:107], v[150:153], v[194:197], v[104:107]
	v_mfma_f32_16x16x32_bf16 v[92:95], v[142:145], v[202:205], v[92:95]
	v_mfma_f32_16x16x32_bf16 v[88:91], v[150:153], v[202:205], v[88:91]
	v_mfma_f32_16x16x32_bf16 v[76:79], v[142:145], v[216:219], v[76:79]
	v_mfma_f32_16x16x32_bf16 v[72:75], v[150:153], v[216:219], v[72:75]
	v_mfma_f32_16x16x32_bf16 v[116:119], v[166:169], v[182:185], v[116:119]
	v_mfma_f32_16x16x32_bf16 v[112:115], v[174:177], v[182:185], v[112:115]
	v_mfma_f32_16x16x32_bf16 v[100:103], v[166:169], v[190:193], v[100:103]
	v_mfma_f32_16x16x32_bf16 v[96:99], v[174:177], v[190:193], v[96:99]
	v_mfma_f32_16x16x32_bf16 v[84:87], v[166:169], v[198:201], v[84:87]
	v_mfma_f32_16x16x32_bf16 v[80:83], v[174:177], v[198:201], v[80:83]
	v_mfma_f32_16x16x32_bf16 v[68:71], v[166:169], v[208:211], v[68:71]
	v_mfma_f32_16x16x32_bf16 v[64:67], v[174:177], v[208:211], v[64:67]
	v_mfma_f32_16x16x32_bf16 v[116:119], v[170:173], v[186:189], v[116:119]
	v_mfma_f32_16x16x32_bf16 v[112:115], v[178:181], v[186:189], v[112:115]
	v_mfma_f32_16x16x32_bf16 v[100:103], v[170:173], v[194:197], v[100:103]
	v_mfma_f32_16x16x32_bf16 v[96:99], v[178:181], v[194:197], v[96:99]
	v_mfma_f32_16x16x32_bf16 v[84:87], v[170:173], v[202:205], v[84:87]
	v_mfma_f32_16x16x32_bf16 v[80:83], v[178:181], v[202:205], v[80:83]
	v_mfma_f32_16x16x32_bf16 v[68:71], v[170:173], v[216:219], v[68:71]
	v_mfma_f32_16x16x32_bf16 v[64:67], v[178:181], v[216:219], v[64:67]
	s_barrier
	s_add_i32 s36, s37, s89
	v_lshl_add_u64 v[154:155], s[76:77], 0, v[160:161]
	s_mov_b32 m0, s36
	ds_read_b128 v[182:185], v164 offset:16384
	ds_read_b128 v[186:189], v164 offset:17408
	ds_read_b128 v[190:193], v164 offset:18432
	ds_read_b128 v[194:197], v164 offset:19456
	ds_read_b128 v[198:201], v164 offset:20480
	ds_read_b128 v[202:205], v164 offset:21504
	ds_read_b128 v[208:211], v164 offset:22528
	ds_read_b128 v[216:219], v164 offset:23552
	global_load_lds_dwordx4 v[154:155], off
	s_add_i32 m0, s36, 0x2000
	s_add_u32 s64, s76, 0x100000
	v_lshl_add_u64 v[220:221], s[76:77], 0, v[136:137]
	s_addc_u32 s65, s77, 0
	s_add_i32 s30, s30, s89
	global_load_lds_dwordx4 v[220:221], off
	v_lshl_add_u64 v[222:223], s[64:65], 0, v[160:161]
	s_mov_b32 m0, s30
	v_lshl_add_u64 v[224:225], s[78:79], 0, v[134:135]
	global_load_lds_dwordx4 v[222:223], off
	v_lshl_add_u64 v[222:223], s[64:65], 0, v[136:137]
	s_add_i32 m0, s30, 0x2000
	s_nop 0
	global_load_lds_dwordx4 v[222:223], off
	v_lshl_add_u64 v[222:223], s[78:79], 0, v[132:133]
	s_mov_b32 m0, s83
	s_nop 0
	global_load_lds_dwordx4 v[222:223], off
	s_mov_b32 m0, s31
	s_nop 0
	global_load_lds_dwordx4 v[224:225], off
	s_waitcnt vmcnt(8)
	s_waitcnt lgkmcnt(0)
	s_barrier
; #define PG8_STAGE(bufoff, gbase, voff) do { _Pragma("unroll") for (int _i = 0; _i < 2; ++_i) \
;         __builtin_amdgcn_global_load_lds((const unsigned*)((const char*)(gbase) + (voff)[_i]), (LAS unsigned*)(lds + (bufoff) + ldsw + _i * 8192), 16, 0, 0); } while (0)
; #define PG8_LDA(dst, b, h) do { _Pragma("unroll") for (int m = 0; m < 4; ++m) _Pragma("unroll") for (int k = 0; k < 2; ++k) dst[m][k] = *(const LAS bf16x8*)(lds + PG8_SA(b, h) + aoff + m * 2048 + k * 1024); } while (0)
; #define PG8_LDB(dst, b, h) do { _Pragma("unroll") for (int n = 0; n < 2; ++n) _Pragma("unroll") for (int k = 0; k < 2; ++k) dst[n][k] = *(const LAS bf16x8*)(lds + PG8_SB(b, h) + boff + n * 2048 + k * 1024); } while (0)
; #define PG8_MMA(ai, bj, At, Bt) do { __builtin_amdgcn_s_setprio(1); _Pragma("unroll") for (int m = 0; m < 4; ++m) _Pragma("unroll") for (int n = 0; n < 2; ++n) _Pragma("unroll") for (int k = 0; k < 2; ++k) \
;         acc[ai][bj][m][n] = __builtin_amdgcn_mfma_f32_16x16x32_bf16(Bt[n][k], At[m][k], acc[ai][bj][m][n], 0, 0, 0); __builtin_amdgcn_s_setprio(0); } while (0)
; #define PG8_WAIT_V(n) asm volatile("s_waitcnt vmcnt(" #n ")" ::: "memory")
; #define PG8_WAIT_L(n) asm volatile("s_waitcnt lgkmcnt(" #n ")" ::: "memory")
; #define PG8_BAR __builtin_amdgcn_s_barrier()
; #define PG8_SCHED __builtin_amdgcn_sched_barrier(0)
; template <class Epi, bool HAS_MID>
; __device__ __forceinline__ void gemm_phase(LAS unsigned char* lds, const Gemm g, const Sched& S, const Epi& E) {
;     ...
;             PG8_WAIT_V(8); PG8_WAIT_L(0); PG8_BAR; PG8_MMA(1, 0, At, B0); PG8_MMA(1, 1, At, B1); PG8_BAR; PG8_SCHED;
;             PG8_LDB(B0, 1, 0); PG8_LDB(B1, 1, 1); PG8_SCHED; PG8_LDA(At, 1, 0); PG8_STAGE(PG8_SA(0, 1), a2 + hstepA, voffA);
;             PG8_WAIT_V(8); PG8_WAIT_L(0); PG8_BAR; PG8_MMA(0, 0, At, B0); PG8_MMA(0, 1, At, B1); PG8_BAR; PG8_SCHED;
;             PG8_LDA(At, 1, 1); PG8_STAGE(PG8_SB(1, 0), b3, voffB); PG8_STAGE(PG8_SB(1, 1), b3 + hstepB, voffB); PG8_STAGE(PG8_SA(1, 0), a3, voffA);
	s_waitcnt lgkmcnt(0)
	v_mfma_f32_16x16x32_bf16 v[60:63], v[128:131], v[182:185], v[60:63]
	v_mfma_f32_16x16x32_bf16 v[56:59], v[146:149], v[182:185], v[56:59]
	v_mfma_f32_16x16x32_bf16 v[44:47], v[128:131], v[190:193], v[44:47]
	v_mfma_f32_16x16x32_bf16 v[40:43], v[146:149], v[190:193], v[40:43]
	v_mfma_f32_16x16x32_bf16 v[28:31], v[128:131], v[198:201], v[28:31]
	v_mfma_f32_16x16x32_bf16 v[24:27], v[146:149], v[198:201], v[24:27]
	v_mfma_f32_16x16x32_bf16 v[12:15], v[128:131], v[208:211], v[12:15]
	v_mfma_f32_16x16x32_bf16 v[8:11], v[146:149], v[208:211], v[8:11]
	v_mfma_f32_16x16x32_bf16 v[60:63], v[142:145], v[186:189], v[60:63]
	v_mfma_f32_16x16x32_bf16 v[56:59], v[150:153], v[186:189], v[56:59]
	v_mfma_f32_16x16x32_bf16 v[44:47], v[142:145], v[194:197], v[44:47]
	v_mfma_f32_16x16x32_bf16 v[40:43], v[150:153], v[194:197], v[40:43]
	v_mfma_f32_16x16x32_bf16 v[28:31], v[142:145], v[202:205], v[28:31]
	v_mfma_f32_16x16x32_bf16 v[24:27], v[150:153], v[202:205], v[24:27]
	v_mfma_f32_16x16x32_bf16 v[12:15], v[142:145], v[216:219], v[12:15]
	v_mfma_f32_16x16x32_bf16 v[8:11], v[150:153], v[216:219], v[8:11]
	v_mfma_f32_16x16x32_bf16 v[52:55], v[166:169], v[182:185], v[52:55]
	v_mfma_f32_16x16x32_bf16 v[48:51], v[174:177], v[182:185], v[48:51]
	v_mfma_f32_16x16x32_bf16 v[36:39], v[166:169], v[190:193], v[36:39]
	v_mfma_f32_16x16x32_bf16 v[32:35], v[174:177], v[190:193], v[32:35]
	v_mfma_f32_16x16x32_bf16 v[20:23], v[166:169], v[198:201], v[20:23]
	v_mfma_f32_16x16x32_bf16 v[16:19], v[174:177], v[198:201], v[16:19]
	v_mfma_f32_16x16x32_bf16 v[4:7], v[166:169], v[208:211], v[4:7]
	v_mfma_f32_16x16x32_bf16 v[0:3], v[174:177], v[208:211], v[0:3]
	v_mfma_f32_16x16x32_bf16 v[52:55], v[170:173], v[186:189], v[52:55]
	v_mfma_f32_16x16x32_bf16 v[48:51], v[178:181], v[186:189], v[48:51]
	v_mfma_f32_16x16x32_bf16 v[36:39], v[170:173], v[194:197], v[36:39]
	v_mfma_f32_16x16x32_bf16 v[32:35], v[178:181], v[194:197], v[32:35]
	v_mfma_f32_16x16x32_bf16 v[20:23], v[170:173], v[202:205], v[20:23]
	v_mfma_f32_16x16x32_bf16 v[16:19], v[178:181], v[202:205], v[16:19]
	v_mfma_f32_16x16x32_bf16 v[4:7], v[170:173], v[216:219], v[4:7]
	v_mfma_f32_16x16x32_bf16 v[0:3], v[178:181], v[216:219], v[0:3]
	s_barrier
	s_add_i32 s30, 0, 0x18000
	s_add_i32 s36, 0, 0x1c000
	v_add_u32_e32 v150, s30, v158
	v_add_u32_e32 v165, s36, v158
	ds_read_b128 v[128:131], v150
	ds_read_b128 v[142:145], v150 offset:1024
	ds_read_b128 v[146:149], v150 offset:2048
	ds_read_b128 v[150:153], v150 offset:3072
	ds_read_b128 v[166:169], v165
	ds_read_b128 v[170:173], v165 offset:1024
	ds_read_b128 v[174:177], v165 offset:2048
	ds_read_b128 v[178:181], v165 offset:3072
	s_add_u32 s64, s78, 0x80000
	s_addc_u32 s65, s79, 0
	s_mov_b32 m0, s54
	v_lshl_add_u64 v[226:227], s[64:65], 0, v[132:133]
	ds_read_b128 v[182:185], v164 offset:32768
	ds_read_b128 v[186:189], v164 offset:33792
	ds_read_b128 v[190:193], v164 offset:34816
	ds_read_b128 v[194:197], v164 offset:35840
	ds_read_b128 v[198:201], v164 offset:36864
	ds_read_b128 v[202:205], v164 offset:37888
	ds_read_b128 v[208:211], v164 offset:38912
	ds_read_b128 v[216:219], v164 offset:39936
	global_load_lds_dwordx4 v[226:227], off
	v_lshl_add_u64 v[226:227], s[64:65], 0, v[134:135]
	s_mov_b32 m0, s55
	s_nop 0
	global_load_lds_dwordx4 v[226:227], off
	s_waitcnt vmcnt(8)
	s_waitcnt lgkmcnt(0)
	s_barrier
	s_waitcnt lgkmcnt(0)
	v_mfma_f32_16x16x32_bf16 v[124:127], v[128:131], v[182:185], v[124:127]
	v_mfma_f32_16x16x32_bf16 v[120:123], v[146:149], v[182:185], v[120:123]
	v_mfma_f32_16x16x32_bf16 v[108:111], v[128:131], v[190:193], v[108:111]
	v_mfma_f32_16x16x32_bf16 v[104:107], v[146:149], v[190:193], v[104:107]
	v_mfma_f32_16x16x32_bf16 v[92:95], v[128:131], v[198:201], v[92:95]
	v_mfma_f32_16x16x32_bf16 v[88:91], v[146:149], v[198:201], v[88:91]
	v_mfma_f32_16x16x32_bf16 v[76:79], v[128:131], v[208:211], v[76:79]
	v_mfma_f32_16x16x32_bf16 v[72:75], v[146:149], v[208:211], v[72:75]
	v_mfma_f32_16x16x32_bf16 v[124:127], v[142:145], v[186:189], v[124:127]
	v_mfma_f32_16x16x32_bf16 v[120:123], v[150:153], v[186:189], v[120:123]
	v_mfma_f32_16x16x32_bf16 v[108:111], v[142:145], v[194:197], v[108:111]
	v_mfma_f32_16x16x32_bf16 v[104:107], v[150:153], v[194:197], v[104:107]
	v_mfma_f32_16x16x32_bf16 v[92:95], v[142:145], v[202:205], v[92:95]
	v_mfma_f32_16x16x32_bf16 v[88:91], v[150:153], v[202:205], v[88:91]
	v_mfma_f32_16x16x32_bf16 v[76:79], v[142:145], v[216:219], v[76:79]
	v_mfma_f32_16x16x32_bf16 v[72:75], v[150:153], v[216:219], v[72:75]
	v_mfma_f32_16x16x32_bf16 v[116:119], v[166:169], v[182:185], v[116:119]
	v_mfma_f32_16x16x32_bf16 v[112:115], v[174:177], v[182:185], v[112:115]
	v_mfma_f32_16x16x32_bf16 v[100:103], v[166:169], v[190:193], v[100:103]
	v_mfma_f32_16x16x32_bf16 v[96:99], v[174:177], v[190:193], v[96:99]
	v_mfma_f32_16x16x32_bf16 v[84:87], v[166:169], v[198:201], v[84:87]
	v_mfma_f32_16x16x32_bf16 v[80:83], v[174:177], v[198:201], v[80:83]
	v_mfma_f32_16x16x32_bf16 v[68:71], v[166:169], v[208:211], v[68:71]
	v_mfma_f32_16x16x32_bf16 v[64:67], v[174:177], v[208:211], v[64:67]
	v_mfma_f32_16x16x32_bf16 v[116:119], v[170:173], v[186:189], v[116:119]
	v_mfma_f32_16x16x32_bf16 v[112:115], v[178:181], v[186:189], v[112:115]
	v_mfma_f32_16x16x32_bf16 v[100:103], v[170:173], v[194:197], v[100:103]
	v_mfma_f32_16x16x32_bf16 v[96:99], v[178:181], v[194:197], v[96:99]
	v_mfma_f32_16x16x32_bf16 v[84:87], v[170:173], v[202:205], v[84:87]
	v_mfma_f32_16x16x32_bf16 v[80:83], v[178:181], v[202:205], v[80:83]
	v_mfma_f32_16x16x32_bf16 v[68:71], v[170:173], v[216:219], v[68:71]
	v_mfma_f32_16x16x32_bf16 v[64:67], v[178:181], v[216:219], v[64:67]
	s_barrier
; #define PG8_STAGE(bufoff, gbase, voff) do { _Pragma("unroll") for (int _i = 0; _i < 2; ++_i) \
;         __builtin_amdgcn_global_load_lds((const unsigned*)((const char*)(gbase) + (voff)[_i]), (LAS unsigned*)(lds + (bufoff) + ldsw + _i * 8192), 16, 0, 0); } while (0)
; #define PG8_LDA(dst, b, h) do { _Pragma("unroll") for (int m = 0; m < 4; ++m) _Pragma("unroll") for (int k = 0; k < 2; ++k) dst[m][k] = *(const LAS bf16x8*)(lds + PG8_SA(b, h) + aoff + m * 2048 + k * 1024); } while (0)
; #define PG8_MMA(ai, bj, At, Bt) do { __builtin_amdgcn_s_setprio(1); _Pragma("unroll") for (int m = 0; m < 4; ++m) _Pragma("unroll") for (int n = 0; n < 2; ++n) _Pragma("unroll") for (int k = 0; k < 2; ++k) \
;         acc[ai][bj][m][n] = __builtin_amdgcn_mfma_f32_16x16x32_bf16(Bt[n][k], At[m][k], acc[ai][bj][m][n], 0, 0, 0); __builtin_amdgcn_s_setprio(0); } while (0)
; #define PG8_WAIT_V(n) asm volatile("s_waitcnt vmcnt(" #n ")" ::: "memory")
; #define PG8_WAIT_L(n) asm volatile("s_waitcnt lgkmcnt(" #n ")" ::: "memory")
; #define PG8_BAR __builtin_amdgcn_s_barrier()
; #define PG8_SCHED __builtin_amdgcn_sched_barrier(0)
; template <class Epi, bool HAS_MID>
; __device__ __forceinline__ void gemm_phase(LAS unsigned char* lds, const Gemm g, const Sched& S, const Epi& E) {
;     ...
;             PG8_LDA(At, 1, 1); PG8_STAGE(PG8_SB(1, 0), b3, voffB); PG8_STAGE(PG8_SB(1, 1), b3 + hstepB, voffB); PG8_STAGE(PG8_SA(1, 0), a3, voffA);
;             PG8_WAIT_V(8); PG8_WAIT_L(0); PG8_BAR; PG8_MMA(1, 0, At, B0); PG8_MMA(1, 1, At, B1); PG8_BAR; PG8_SCHED;
;         }
;         if (wr == 0) PG8_BAR;
	s_add_i32 s30, s30, s89
	v_lshl_add_u64 v[154:155], v[154:155], 0, s[38:39]
	s_mov_b32 m0, s30
	ds_read_b128 v[182:185], v164 offset:49152
	ds_read_b128 v[186:189], v164 offset:50176
	ds_read_b128 v[190:193], v164 offset:51200
	ds_read_b128 v[194:197], v164 offset:52224
	ds_read_b128 v[198:201], v164 offset:53248
	ds_read_b128 v[202:205], v164 offset:54272
	ds_read_b128 v[208:211], v164 offset:55296
	ds_read_b128 v[216:219], v164 offset:56320
	global_load_lds_dwordx4 v[154:155], off
	s_add_i32 m0, s30, 0x2000
	s_add_u32 s64, s76, 0x100080
	v_lshl_add_u64 v[154:155], v[220:221], 0, s[38:39]
	s_addc_u32 s65, s77, 0
	s_add_i32 s30, s36, s89
	global_load_lds_dwordx4 v[154:155], off
	v_lshl_add_u64 v[154:155], s[64:65], 0, v[160:161]
	s_mov_b32 m0, s30
	s_nop 0
	global_load_lds_dwordx4 v[154:155], off
	v_lshl_add_u64 v[154:155], s[64:65], 0, v[136:137]
	s_add_i32 m0, s30, 0x2000
	s_nop 0
	global_load_lds_dwordx4 v[154:155], off
	v_lshl_add_u64 v[154:155], v[222:223], 0, s[38:39]
	s_mov_b32 m0, s58
	s_nop 0
	global_load_lds_dwordx4 v[154:155], off
	v_lshl_add_u64 v[154:155], v[224:225], 0, s[38:39]
	s_mov_b32 m0, s59
	s_nop 0
	global_load_lds_dwordx4 v[154:155], off
	s_waitcnt vmcnt(8)
	s_waitcnt lgkmcnt(0)
	s_barrier
	s_waitcnt lgkmcnt(0)
	v_mfma_f32_16x16x32_bf16 v[60:63], v[128:131], v[182:185], v[60:63]
	v_mfma_f32_16x16x32_bf16 v[56:59], v[146:149], v[182:185], v[56:59]
	v_mfma_f32_16x16x32_bf16 v[44:47], v[128:131], v[190:193], v[44:47]
	v_mfma_f32_16x16x32_bf16 v[40:43], v[146:149], v[190:193], v[40:43]
	v_mfma_f32_16x16x32_bf16 v[28:31], v[128:131], v[198:201], v[28:31]
	v_mfma_f32_16x16x32_bf16 v[24:27], v[146:149], v[198:201], v[24:27]
	v_mfma_f32_16x16x32_bf16 v[12:15], v[128:131], v[208:211], v[12:15]
	v_mfma_f32_16x16x32_bf16 v[8:11], v[146:149], v[208:211], v[8:11]
	v_mfma_f32_16x16x32_bf16 v[60:63], v[142:145], v[186:189], v[60:63]
	v_mfma_f32_16x16x32_bf16 v[56:59], v[150:153], v[186:189], v[56:59]
	v_mfma_f32_16x16x32_bf16 v[44:47], v[142:145], v[194:197], v[44:47]
	v_mfma_f32_16x16x32_bf16 v[40:43], v[150:153], v[194:197], v[40:43]
	v_mfma_f32_16x16x32_bf16 v[28:31], v[142:145], v[202:205], v[28:31]
	v_mfma_f32_16x16x32_bf16 v[24:27], v[150:153], v[202:205], v[24:27]
	v_mfma_f32_16x16x32_bf16 v[12:15], v[142:145], v[216:219], v[12:15]
	v_mfma_f32_16x16x32_bf16 v[8:11], v[150:153], v[216:219], v[8:11]
	v_mfma_f32_16x16x32_bf16 v[52:55], v[166:169], v[182:185], v[52:55]
	v_mfma_f32_16x16x32_bf16 v[48:51], v[174:177], v[182:185], v[48:51]
	v_mfma_f32_16x16x32_bf16 v[36:39], v[166:169], v[190:193], v[36:39]
	v_mfma_f32_16x16x32_bf16 v[32:35], v[174:177], v[190:193], v[32:35]
	v_mfma_f32_16x16x32_bf16 v[20:23], v[166:169], v[198:201], v[20:23]
	v_mfma_f32_16x16x32_bf16 v[16:19], v[174:177], v[198:201], v[16:19]
	v_mfma_f32_16x16x32_bf16 v[4:7], v[166:169], v[208:211], v[4:7]
	v_mfma_f32_16x16x32_bf16 v[0:3], v[174:177], v[208:211], v[0:3]
	v_mfma_f32_16x16x32_bf16 v[52:55], v[170:173], v[186:189], v[52:55]
	v_mfma_f32_16x16x32_bf16 v[48:51], v[178:181], v[186:189], v[48:51]
	v_mfma_f32_16x16x32_bf16 v[36:39], v[170:173], v[194:197], v[36:39]
	v_mfma_f32_16x16x32_bf16 v[32:35], v[178:181], v[194:197], v[32:35]
	v_mfma_f32_16x16x32_bf16 v[20:23], v[170:173], v[202:205], v[20:23]
	v_mfma_f32_16x16x32_bf16 v[16:19], v[178:181], v[202:205], v[16:19]
	v_mfma_f32_16x16x32_bf16 v[4:7], v[170:173], v[216:219], v[4:7]
	v_mfma_f32_16x16x32_bf16 v[0:3], v[178:181], v[216:219], v[0:3]
	s_barrier
	s_add_i32 s51, s51, 2
	s_add_u32 s43, s43, 0x100
	s_addc_u32 s48, s48, 0
	s_add_u32 s74, s74, 0x100
	s_addc_u32 s75, s75, 0
	s_cmp_gt_u32 s51, 29
	s_cbranch_scc0 .LBB0_1562
	s_and_b64 vcc, exec, s[22:23]
	s_cbranch_vccz .LBB0_1565
	s_barrier

; #define PG8_STAGE(bufoff, gbase, voff) do { _Pragma("unroll") for (int _i = 0; _i < 2; ++_i) \
;         __builtin_amdgcn_global_load_lds((const unsigned*)((const char*)(gbase) + (voff)[_i]), (LAS unsigned*)(lds + (bufoff) + ldsw + _i * 8192), 16, 0, 0); } while (0)
; #define PG8_LDA(dst, b, h) do { _Pragma("unroll") for (int m = 0; m < 4; ++m) _Pragma("unroll") for (int k = 0; k < 2; ++k) dst[m][k] = *(const LAS bf16x8*)(lds + PG8_SA(b, h) + aoff + m * 2048 + k * 1024); } while (0)
; #define PG8_LDB(dst, b, h) do { _Pragma("unroll") for (int n = 0; n < 2; ++n) _Pragma("unroll") for (int k = 0; k < 2; ++k) dst[n][k] = *(const LAS bf16x8*)(lds + PG8_SB(b, h) + boff + n * 2048 + k * 1024); } while (0)
; #define PG8_WAIT_V(n) asm volatile("s_waitcnt vmcnt(" #n ")" ::: "memory")
; #define PG8_WAIT_L(n) asm volatile("s_waitcnt lgkmcnt(" #n ")" ::: "memory")
; template <class Epi, bool HAS_MID>
; __device__ __forceinline__ void gemm_phase(LAS unsigned char* lds, const Gemm g, const Sched& S, const Epi& E) {
;     ...
;         for (int t = 0; t < nt; t += 2) {
;             const bool last = (t == nt - 2);
;             const char* a1 = PG8_APT(t + 1);
;             const char* a2 = last ? nA : PG8_APT(t + 2); const char* b2 = last ? nB : cB + (size_t)(t + 2) * kstep;
;             const char* a3 = a2 + kstep; const char* b3 = b2 + kstep;
;             PG8_LDB(B0, 0, 0); PG8_LDB(B1, 0, 1); PG8_SCHED; PG8_LDA(At, 0, 0); PG8_STAGE(PG8_SA(1, 1), a1 + hstepA, voffA);
;             PG8_WAIT_V(8); PG8_WAIT_L(0); PG8_BAR; PG8_MMA(0, 0, At, B0); PG8_MMA(0, 1, At, B1); PG8_BAR; PG8_SCHED;
;             PG8_LDA(At, 0, 1); PG8_STAGE(PG8_SB(0, 0), b2, voffB); PG8_STAGE(PG8_SB(0, 1), b2 + hstepB, voffB); PG8_STAGE(PG8_SA(0, 0), a2, voffA);
;             PG8_WAIT_V(8); PG8_WAIT_L(0); PG8_BAR; PG8_MMA(1, 0, At, B0); PG8_MMA(1, 1, At, B1); PG8_BAR; PG8_SCHED;
;             PG8_LDB(B0, 1, 0); PG8_LDB(B1, 1, 1); PG8_SCHED; PG8_LDA(At, 1, 0); PG8_STAGE(PG8_SA(0, 1), a2 + hstepA, voffA);
;             PG8_WAIT_V(8); PG8_WAIT_L(0); PG8_BAR; PG8_MMA(0, 0, At, B0); PG8_MMA(0, 1, At, B1); PG8_BAR; PG8_SCHED;
;             PG8_LDA(At, 1, 1); PG8_STAGE(PG8_SB(1, 0), b3, voffB); PG8_STAGE(PG8_SB(1, 1), b3 + hstepB, voffB); PG8_STAGE(PG8_SA(1, 0), a3, voffA);
;             PG8_WAIT_V(8); PG8_WAIT_L(0); PG8_BAR; PG8_MMA(1, 0, At, B0); PG8_MMA(1, 1, At, B1); PG8_BAR; PG8_SCHED;
.LBB0_2007:
	s_add_u32 s30, s4, 0xfff80080
	s_addc_u32 s36, s5, -1
	s_add_i32 s37, 0, 0x10000
	s_cmp_eq_u32 s51, s43
	s_cselect_b32 s85, s75, s36
	s_cselect_b32 s84, s74, s30
	s_cselect_b32 s83, s77, s27
	s_cselect_b32 s82, s76, s7
	s_add_i32 s30, 0, 0x14000
	v_add_u32_e32 v140, s37, v215
	v_add_u32_e32 v156, s30, v215
	ds_read_b128 v[96:99], v140
	ds_read_b128 v[100:103], v140 offset:1024
	ds_read_b128 v[136:139], v140 offset:2048
	ds_read_b128 v[140:143], v140 offset:3072
	ds_read_b128 v[144:147], v156
	ds_read_b128 v[148:151], v156 offset:1024
	ds_read_b128 v[152:155], v156 offset:2048
	ds_read_b128 v[156:159], v156 offset:3072
	v_lshl_add_u64 v[230:231], s[4:5], 0, v[188:189]
	s_add_i32 m0, s25, 0xc000
	ds_read_b128 v[190:193], v217
	ds_read_b128 v[194:197], v217 offset:1024
	ds_read_b128 v[198:201], v217 offset:2048
	ds_read_b128 v[202:205], v217 offset:3072
	ds_read_b128 v[208:211], v217 offset:4096
	ds_read_b128 v[218:221], v217 offset:5120
	ds_read_b128 v[222:225], v217 offset:6144
	ds_read_b128 v[226:229], v217 offset:7168
	global_load_lds_dwordx4 v[230:231], off
	v_lshl_add_u64 v[230:231], s[4:5], 0, v[186:187]
	s_add_i32 m0, s25, 0xe000
	s_nop 0
	global_load_lds_dwordx4 v[230:231], off
	s_waitcnt vmcnt(8)
	s_waitcnt lgkmcnt(0)
	s_barrier
	s_waitcnt lgkmcnt(0)
	v_mfma_f32_16x16x32_bf16 v[132:135], v[96:99], v[190:193], v[132:135]
	v_mfma_f32_16x16x32_bf16 v[128:131], v[136:139], v[190:193], v[128:131]
	v_mfma_f32_16x16x32_bf16 v[124:127], v[96:99], v[198:201], v[124:127]
	v_mfma_f32_16x16x32_bf16 v[120:123], v[136:139], v[198:201], v[120:123]
	v_mfma_f32_16x16x32_bf16 v[116:119], v[96:99], v[208:211], v[116:119]
	v_mfma_f32_16x16x32_bf16 v[112:115], v[136:139], v[208:211], v[112:115]
	v_mfma_f32_16x16x32_bf16 v[108:111], v[96:99], v[222:225], v[108:111]
	v_mfma_f32_16x16x32_bf16 v[104:107], v[136:139], v[222:225], v[104:107]
	v_mfma_f32_16x16x32_bf16 v[132:135], v[100:103], v[194:197], v[132:135]
	v_mfma_f32_16x16x32_bf16 v[128:131], v[140:143], v[194:197], v[128:131]
	v_mfma_f32_16x16x32_bf16 v[124:127], v[100:103], v[202:205], v[124:127]
	v_mfma_f32_16x16x32_bf16 v[120:123], v[140:143], v[202:205], v[120:123]
	v_mfma_f32_16x16x32_bf16 v[116:119], v[100:103], v[218:221], v[116:119]
	v_mfma_f32_16x16x32_bf16 v[112:115], v[140:143], v[218:221], v[112:115]
	v_mfma_f32_16x16x32_bf16 v[108:111], v[100:103], v[226:229], v[108:111]
	v_mfma_f32_16x16x32_bf16 v[104:107], v[140:143], v[226:229], v[104:107]
	v_mfma_f32_16x16x32_bf16 v[60:63], v[144:147], v[190:193], v[60:63]
	v_mfma_f32_16x16x32_bf16 v[56:59], v[152:155], v[190:193], v[56:59]
	v_mfma_f32_16x16x32_bf16 v[52:55], v[144:147], v[198:201], v[52:55]
	v_mfma_f32_16x16x32_bf16 v[48:51], v[152:155], v[198:201], v[48:51]
	v_mfma_f32_16x16x32_bf16 v[44:47], v[144:147], v[208:211], v[44:47]
	v_mfma_f32_16x16x32_bf16 v[40:43], v[152:155], v[208:211], v[40:43]
	v_mfma_f32_16x16x32_bf16 v[36:39], v[144:147], v[222:225], v[36:39]
	v_mfma_f32_16x16x32_bf16 v[32:35], v[152:155], v[222:225], v[32:35]
	v_mfma_f32_16x16x32_bf16 v[60:63], v[148:151], v[194:197], v[60:63]
	v_mfma_f32_16x16x32_bf16 v[56:59], v[156:159], v[194:197], v[56:59]
	v_mfma_f32_16x16x32_bf16 v[52:55], v[148:151], v[202:205], v[52:55]
	v_mfma_f32_16x16x32_bf16 v[48:51], v[156:159], v[202:205], v[48:51]
	v_mfma_f32_16x16x32_bf16 v[44:47], v[148:151], v[218:221], v[44:47]
	v_mfma_f32_16x16x32_bf16 v[40:43], v[156:159], v[218:221], v[40:43]
	v_mfma_f32_16x16x32_bf16 v[36:39], v[148:151], v[226:229], v[36:39]
	v_mfma_f32_16x16x32_bf16 v[32:35], v[156:159], v[226:229], v[32:35]
	s_barrier
	s_add_i32 s36, s37, s56
	v_lshl_add_u64 v[230:231], s[82:83], 0, v[160:161]
	s_mov_b32 m0, s36
	ds_read_b128 v[190:193], v217 offset:16384
	ds_read_b128 v[194:197], v217 offset:17408
	ds_read_b128 v[198:201], v217 offset:18432
	ds_read_b128 v[202:205], v217 offset:19456
	ds_read_b128 v[208:211], v217 offset:20480
	ds_read_b128 v[218:221], v217 offset:21504
	ds_read_b128 v[222:225], v217 offset:22528
	ds_read_b128 v[226:229], v217 offset:23552
	global_load_lds_dwordx4 v[230:231], off
	s_add_i32 m0, s36, 0x2000
	s_add_u32 s64, s82, 0x80000
	v_lshl_add_u64 v[232:233], s[82:83], 0, v[168:169]
	s_addc_u32 s65, s83, 0
	s_add_i32 s30, s30, s56
	global_load_lds_dwordx4 v[232:233], off
	v_lshl_add_u64 v[234:235], s[64:65], 0, v[160:161]
	s_mov_b32 m0, s30
	v_lshl_add_u64 v[236:237], s[84:85], 0, v[166:167]
	global_load_lds_dwordx4 v[234:235], off
	v_lshl_add_u64 v[234:235], s[64:65], 0, v[168:169]
	s_add_i32 m0, s30, 0x2000
	s_nop 0
	global_load_lds_dwordx4 v[234:235], off
	v_lshl_add_u64 v[234:235], s[84:85], 0, v[164:165]
	s_mov_b32 m0, s25
	s_nop 0
	global_load_lds_dwordx4 v[234:235], off
	s_mov_b32 m0, s86
	s_nop 0
	global_load_lds_dwordx4 v[236:237], off
	s_waitcnt vmcnt(8)
	s_waitcnt lgkmcnt(0)
	s_barrier
; #define PG8_STAGE(bufoff, gbase, voff) do { _Pragma("unroll") for (int _i = 0; _i < 2; ++_i) \
;         __builtin_amdgcn_global_load_lds((const unsigned*)((const char*)(gbase) + (voff)[_i]), (LAS unsigned*)(lds + (bufoff) + ldsw + _i * 8192), 16, 0, 0); } while (0)
; #define PG8_LDA(dst, b, h) do { _Pragma("unroll") for (int m = 0; m < 4; ++m) _Pragma("unroll") for (int k = 0; k < 2; ++k) dst[m][k] = *(const LAS bf16x8*)(lds + PG8_SA(b, h) + aoff + m * 2048 + k * 1024); } while (0)
; #define PG8_LDB(dst, b, h) do { _Pragma("unroll") for (int n = 0; n < 2; ++n) _Pragma("unroll") for (int k = 0; k < 2; ++k) dst[n][k] = *(const LAS bf16x8*)(lds + PG8_SB(b, h) + boff + n * 2048 + k * 1024); } while (0)
; #define PG8_MMA(ai, bj, At, Bt) do { __builtin_amdgcn_s_setprio(1); _Pragma("unroll") for (int m = 0; m < 4; ++m) _Pragma("unroll") for (int n = 0; n < 2; ++n) _Pragma("unroll") for (int k = 0; k < 2; ++k) \
;         acc[ai][bj][m][n] = __builtin_amdgcn_mfma_f32_16x16x32_bf16(Bt[n][k], At[m][k], acc[ai][bj][m][n], 0, 0, 0); __builtin_amdgcn_s_setprio(0); } while (0)
; #define PG8_WAIT_V(n) asm volatile("s_waitcnt vmcnt(" #n ")" ::: "memory")
; #define PG8_WAIT_L(n) asm volatile("s_waitcnt lgkmcnt(" #n ")" ::: "memory")
; #define PG8_BAR __builtin_amdgcn_s_barrier()
; #define PG8_SCHED __builtin_amdgcn_sched_barrier(0)
; template <class Epi, bool HAS_MID>
; __device__ __forceinline__ void gemm_phase(LAS unsigned char* lds, const Gemm g, const Sched& S, const Epi& E) {
;     ...
;             PG8_WAIT_V(8); PG8_WAIT_L(0); PG8_BAR; PG8_MMA(1, 0, At, B0); PG8_MMA(1, 1, At, B1); PG8_BAR; PG8_SCHED;
;             PG8_LDB(B0, 1, 0); PG8_LDB(B1, 1, 1); PG8_SCHED; PG8_LDA(At, 1, 0); PG8_STAGE(PG8_SA(0, 1), a2 + hstepA, voffA);
;             PG8_WAIT_V(8); PG8_WAIT_L(0); PG8_BAR; PG8_MMA(0, 0, At, B0); PG8_MMA(0, 1, At, B1); PG8_BAR; PG8_SCHED;
;             PG8_LDA(At, 1, 1); PG8_STAGE(PG8_SB(1, 0), b3, voffB); PG8_STAGE(PG8_SB(1, 1), b3 + hstepB, voffB); PG8_STAGE(PG8_SA(1, 0), a3, voffA);
	s_waitcnt lgkmcnt(0)
	v_mfma_f32_16x16x32_bf16 v[92:95], v[96:99], v[190:193], v[92:95]
	v_mfma_f32_16x16x32_bf16 v[88:91], v[136:139], v[190:193], v[88:91]
	v_mfma_f32_16x16x32_bf16 v[84:87], v[96:99], v[198:201], v[84:87]
	v_mfma_f32_16x16x32_bf16 v[80:83], v[136:139], v[198:201], v[80:83]
	v_mfma_f32_16x16x32_bf16 v[76:79], v[96:99], v[208:211], v[76:79]
	v_mfma_f32_16x16x32_bf16 v[72:75], v[136:139], v[208:211], v[72:75]
	v_mfma_f32_16x16x32_bf16 v[68:71], v[96:99], v[222:225], v[68:71]
	v_mfma_f32_16x16x32_bf16 v[64:67], v[136:139], v[222:225], v[64:67]
	v_mfma_f32_16x16x32_bf16 v[92:95], v[100:103], v[194:197], v[92:95]
	v_mfma_f32_16x16x32_bf16 v[88:91], v[140:143], v[194:197], v[88:91]
	v_mfma_f32_16x16x32_bf16 v[84:87], v[100:103], v[202:205], v[84:87]
	v_mfma_f32_16x16x32_bf16 v[80:83], v[140:143], v[202:205], v[80:83]
	v_mfma_f32_16x16x32_bf16 v[76:79], v[100:103], v[218:221], v[76:79]
	v_mfma_f32_16x16x32_bf16 v[72:75], v[140:143], v[218:221], v[72:75]
	v_mfma_f32_16x16x32_bf16 v[68:71], v[100:103], v[226:229], v[68:71]
	v_mfma_f32_16x16x32_bf16 v[64:67], v[140:143], v[226:229], v[64:67]
	v_mfma_f32_16x16x32_bf16 v[28:31], v[144:147], v[190:193], v[28:31]
	v_mfma_f32_16x16x32_bf16 v[24:27], v[152:155], v[190:193], v[24:27]
	v_mfma_f32_16x16x32_bf16 v[20:23], v[144:147], v[198:201], v[20:23]
	v_mfma_f32_16x16x32_bf16 v[16:19], v[152:155], v[198:201], v[16:19]
	v_mfma_f32_16x16x32_bf16 v[12:15], v[144:147], v[208:211], v[12:15]
	v_mfma_f32_16x16x32_bf16 v[8:11], v[152:155], v[208:211], v[8:11]
	v_mfma_f32_16x16x32_bf16 v[4:7], v[144:147], v[222:225], v[4:7]
	v_mfma_f32_16x16x32_bf16 v[0:3], v[152:155], v[222:225], v[0:3]
	v_mfma_f32_16x16x32_bf16 v[28:31], v[148:151], v[194:197], v[28:31]
	v_mfma_f32_16x16x32_bf16 v[24:27], v[156:159], v[194:197], v[24:27]
	v_mfma_f32_16x16x32_bf16 v[20:23], v[148:151], v[202:205], v[20:23]
	v_mfma_f32_16x16x32_bf16 v[16:19], v[156:159], v[202:205], v[16:19]
	v_mfma_f32_16x16x32_bf16 v[12:15], v[148:151], v[218:221], v[12:15]
	v_mfma_f32_16x16x32_bf16 v[8:11], v[156:159], v[218:221], v[8:11]
	v_mfma_f32_16x16x32_bf16 v[4:7], v[148:151], v[226:229], v[4:7]
	v_mfma_f32_16x16x32_bf16 v[0:3], v[156:159], v[226:229], v[0:3]
	s_barrier
	s_add_i32 s30, 0, 0x18000
	s_add_i32 s36, 0, 0x1c000
	v_add_u32_e32 v140, s30, v215
	v_add_u32_e32 v156, s36, v215
	ds_read_b128 v[96:99], v140
	ds_read_b128 v[100:103], v140 offset:1024
	ds_read_b128 v[136:139], v140 offset:2048
	ds_read_b128 v[140:143], v140 offset:3072
	ds_read_b128 v[144:147], v156
	ds_read_b128 v[148:151], v156 offset:1024
	ds_read_b128 v[152:155], v156 offset:2048
	ds_read_b128 v[156:159], v156 offset:3072
	s_add_u32 s64, s84, 0x80000
	s_addc_u32 s65, s85, 0
	s_mov_b32 m0, s87
	v_lshl_add_u64 v[238:239], s[64:65], 0, v[164:165]
	ds_read_b128 v[190:193], v217 offset:32768
	ds_read_b128 v[194:197], v217 offset:33792
	ds_read_b128 v[198:201], v217 offset:34816
	ds_read_b128 v[202:205], v217 offset:35840
	ds_read_b128 v[208:211], v217 offset:36864
	ds_read_b128 v[218:221], v217 offset:37888
	ds_read_b128 v[222:225], v217 offset:38912
	ds_read_b128 v[226:229], v217 offset:39936
	global_load_lds_dwordx4 v[238:239], off
	v_lshl_add_u64 v[238:239], s[64:65], 0, v[166:167]
	s_mov_b32 m0, s88
	s_nop 0
	global_load_lds_dwordx4 v[238:239], off
	s_waitcnt vmcnt(8)
	s_waitcnt lgkmcnt(0)
	s_barrier
	s_waitcnt lgkmcnt(0)
	v_mfma_f32_16x16x32_bf16 v[132:135], v[96:99], v[190:193], v[132:135]
	v_mfma_f32_16x16x32_bf16 v[128:131], v[136:139], v[190:193], v[128:131]
	v_mfma_f32_16x16x32_bf16 v[124:127], v[96:99], v[198:201], v[124:127]
	v_mfma_f32_16x16x32_bf16 v[120:123], v[136:139], v[198:201], v[120:123]
	v_mfma_f32_16x16x32_bf16 v[116:119], v[96:99], v[208:211], v[116:119]
	v_mfma_f32_16x16x32_bf16 v[112:115], v[136:139], v[208:211], v[112:115]
	v_mfma_f32_16x16x32_bf16 v[108:111], v[96:99], v[222:225], v[108:111]
	v_mfma_f32_16x16x32_bf16 v[104:107], v[136:139], v[222:225], v[104:107]
	v_mfma_f32_16x16x32_bf16 v[132:135], v[100:103], v[194:197], v[132:135]
	v_mfma_f32_16x16x32_bf16 v[128:131], v[140:143], v[194:197], v[128:131]
	v_mfma_f32_16x16x32_bf16 v[124:127], v[100:103], v[202:205], v[124:127]
	v_mfma_f32_16x16x32_bf16 v[120:123], v[140:143], v[202:205], v[120:123]
	v_mfma_f32_16x16x32_bf16 v[116:119], v[100:103], v[218:221], v[116:119]
	v_mfma_f32_16x16x32_bf16 v[112:115], v[140:143], v[218:221], v[112:115]
	v_mfma_f32_16x16x32_bf16 v[108:111], v[100:103], v[226:229], v[108:111]
	v_mfma_f32_16x16x32_bf16 v[104:107], v[140:143], v[226:229], v[104:107]
	v_mfma_f32_16x16x32_bf16 v[60:63], v[144:147], v[190:193], v[60:63]
	v_mfma_f32_16x16x32_bf16 v[56:59], v[152:155], v[190:193], v[56:59]
	v_mfma_f32_16x16x32_bf16 v[52:55], v[144:147], v[198:201], v[52:55]
	v_mfma_f32_16x16x32_bf16 v[48:51], v[152:155], v[198:201], v[48:51]
	v_mfma_f32_16x16x32_bf16 v[44:47], v[144:147], v[208:211], v[44:47]
	v_mfma_f32_16x16x32_bf16 v[40:43], v[152:155], v[208:211], v[40:43]
	v_mfma_f32_16x16x32_bf16 v[36:39], v[144:147], v[222:225], v[36:39]
	v_mfma_f32_16x16x32_bf16 v[32:35], v[152:155], v[222:225], v[32:35]
	v_mfma_f32_16x16x32_bf16 v[60:63], v[148:151], v[194:197], v[60:63]
	v_mfma_f32_16x16x32_bf16 v[56:59], v[156:159], v[194:197], v[56:59]
	v_mfma_f32_16x16x32_bf16 v[52:55], v[148:151], v[202:205], v[52:55]
	v_mfma_f32_16x16x32_bf16 v[48:51], v[156:159], v[202:205], v[48:51]
	v_mfma_f32_16x16x32_bf16 v[44:47], v[148:151], v[218:221], v[44:47]
	v_mfma_f32_16x16x32_bf16 v[40:43], v[156:159], v[218:221], v[40:43]
	v_mfma_f32_16x16x32_bf16 v[36:39], v[148:151], v[226:229], v[36:39]
	v_mfma_f32_16x16x32_bf16 v[32:35], v[156:159], v[226:229], v[32:35]
	s_barrier
; #define PG8_STAGE(bufoff, gbase, voff) do { _Pragma("unroll") for (int _i = 0; _i < 2; ++_i) \
;         __builtin_amdgcn_global_load_lds((const unsigned*)((const char*)(gbase) + (voff)[_i]), (LAS unsigned*)(lds + (bufoff) + ldsw + _i * 8192), 16, 0, 0); } while (0)
; #define PG8_LDA(dst, b, h) do { _Pragma("unroll") for (int m = 0; m < 4; ++m) _Pragma("unroll") for (int k = 0; k < 2; ++k) dst[m][k] = *(const LAS bf16x8*)(lds + PG8_SA(b, h) + aoff + m * 2048 + k * 1024); } while (0)
; #define PG8_MMA(ai, bj, At, Bt) do { __builtin_amdgcn_s_setprio(1); _Pragma("unroll") for (int m = 0; m < 4; ++m) _Pragma("unroll") for (int n = 0; n < 2; ++n) _Pragma("unroll") for (int k = 0; k < 2; ++k) \
;         acc[ai][bj][m][n] = __builtin_amdgcn_mfma_f32_16x16x32_bf16(Bt[n][k], At[m][k], acc[ai][bj][m][n], 0, 0, 0); __builtin_amdgcn_s_setprio(0); } while (0)
; #define PG8_WAIT_V(n) asm volatile("s_waitcnt vmcnt(" #n ")" ::: "memory")
; #define PG8_WAIT_L(n) asm volatile("s_waitcnt lgkmcnt(" #n ")" ::: "memory")
; #define PG8_BAR __builtin_amdgcn_s_barrier()
; #define PG8_SCHED __builtin_amdgcn_sched_barrier(0)
; template <class Epi, bool HAS_MID>
; __device__ __forceinline__ void gemm_phase(LAS unsigned char* lds, const Gemm g, const Sched& S, const Epi& E) {
;     ...
;             PG8_LDA(At, 1, 1); PG8_STAGE(PG8_SB(1, 0), b3, voffB); PG8_STAGE(PG8_SB(1, 1), b3 + hstepB, voffB); PG8_STAGE(PG8_SA(1, 0), a3, voffA);
;             PG8_WAIT_V(8); PG8_WAIT_L(0); PG8_BAR; PG8_MMA(1, 0, At, B0); PG8_MMA(1, 1, At, B1); PG8_BAR; PG8_SCHED;
;         }
;         if (wr == 0) PG8_BAR;
	s_add_i32 s30, s30, s56
	v_lshl_add_u64 v[230:231], v[230:231], 0, s[38:39]
	s_mov_b32 m0, s30
	ds_read_b128 v[190:193], v217 offset:49152
	ds_read_b128 v[194:197], v217 offset:50176
	ds_read_b128 v[198:201], v217 offset:51200
	ds_read_b128 v[202:205], v217 offset:52224
	ds_read_b128 v[208:211], v217 offset:53248
	ds_read_b128 v[218:221], v217 offset:54272
	ds_read_b128 v[222:225], v217 offset:55296
	ds_read_b128 v[226:229], v217 offset:56320
	global_load_lds_dwordx4 v[230:231], off
	s_add_i32 m0, s30, 0x2000
	s_add_u32 s64, s82, 0x80080
	v_lshl_add_u64 v[230:231], v[232:233], 0, s[38:39]
	s_addc_u32 s65, s83, 0
	s_add_i32 s30, s36, s56
	global_load_lds_dwordx4 v[230:231], off
	v_lshl_add_u64 v[230:231], s[64:65], 0, v[160:161]
	s_mov_b32 m0, s30
	s_nop 0
	global_load_lds_dwordx4 v[230:231], off
	v_lshl_add_u64 v[230:231], s[64:65], 0, v[168:169]
	s_add_i32 m0, s30, 0x2000
	s_nop 0
	global_load_lds_dwordx4 v[230:231], off
	v_lshl_add_u64 v[230:231], v[234:235], 0, s[38:39]
	s_mov_b32 m0, s48
	s_nop 0
	global_load_lds_dwordx4 v[230:231], off
	v_lshl_add_u64 v[230:231], v[236:237], 0, s[38:39]
	s_mov_b32 m0, s52
	s_nop 0
	global_load_lds_dwordx4 v[230:231], off
	s_waitcnt vmcnt(8)
	s_waitcnt lgkmcnt(0)
	s_barrier
	s_waitcnt lgkmcnt(0)
	v_mfma_f32_16x16x32_bf16 v[92:95], v[96:99], v[190:193], v[92:95]
	v_mfma_f32_16x16x32_bf16 v[88:91], v[136:139], v[190:193], v[88:91]
	v_mfma_f32_16x16x32_bf16 v[84:87], v[96:99], v[198:201], v[84:87]
	v_mfma_f32_16x16x32_bf16 v[80:83], v[136:139], v[198:201], v[80:83]
	v_mfma_f32_16x16x32_bf16 v[76:79], v[96:99], v[208:211], v[76:79]
	v_mfma_f32_16x16x32_bf16 v[72:75], v[136:139], v[208:211], v[72:75]
	v_mfma_f32_16x16x32_bf16 v[68:71], v[96:99], v[222:225], v[68:71]
	v_mfma_f32_16x16x32_bf16 v[64:67], v[136:139], v[222:225], v[64:67]
	v_mfma_f32_16x16x32_bf16 v[92:95], v[100:103], v[194:197], v[92:95]
	v_mfma_f32_16x16x32_bf16 v[88:91], v[140:143], v[194:197], v[88:91]
	v_mfma_f32_16x16x32_bf16 v[84:87], v[100:103], v[202:205], v[84:87]
	v_mfma_f32_16x16x32_bf16 v[80:83], v[140:143], v[202:205], v[80:83]
	v_mfma_f32_16x16x32_bf16 v[76:79], v[100:103], v[218:221], v[76:79]
	v_mfma_f32_16x16x32_bf16 v[72:75], v[140:143], v[218:221], v[72:75]
	v_mfma_f32_16x16x32_bf16 v[68:71], v[100:103], v[226:229], v[68:71]
	v_mfma_f32_16x16x32_bf16 v[64:67], v[140:143], v[226:229], v[64:67]
	v_mfma_f32_16x16x32_bf16 v[28:31], v[144:147], v[190:193], v[28:31]
	v_mfma_f32_16x16x32_bf16 v[24:27], v[152:155], v[190:193], v[24:27]
	v_mfma_f32_16x16x32_bf16 v[20:23], v[144:147], v[198:201], v[20:23]
	v_mfma_f32_16x16x32_bf16 v[16:19], v[152:155], v[198:201], v[16:19]
	v_mfma_f32_16x16x32_bf16 v[12:15], v[144:147], v[208:211], v[12:15]
	v_mfma_f32_16x16x32_bf16 v[8:11], v[152:155], v[208:211], v[8:11]
	v_mfma_f32_16x16x32_bf16 v[4:7], v[144:147], v[222:225], v[4:7]
	v_mfma_f32_16x16x32_bf16 v[0:3], v[152:155], v[222:225], v[0:3]
	v_mfma_f32_16x16x32_bf16 v[28:31], v[148:151], v[194:197], v[28:31]
	v_mfma_f32_16x16x32_bf16 v[24:27], v[156:159], v[194:197], v[24:27]
	v_mfma_f32_16x16x32_bf16 v[20:23], v[148:151], v[202:205], v[20:23]
	v_mfma_f32_16x16x32_bf16 v[16:19], v[156:159], v[202:205], v[16:19]
	v_mfma_f32_16x16x32_bf16 v[12:15], v[148:151], v[218:221], v[12:15]
	v_mfma_f32_16x16x32_bf16 v[8:11], v[156:159], v[218:221], v[8:11]
	v_mfma_f32_16x16x32_bf16 v[4:7], v[148:151], v[226:229], v[4:7]
	v_mfma_f32_16x16x32_bf16 v[0:3], v[156:159], v[226:229], v[0:3]
	s_barrier
	s_add_i32 s30, s43, 2
	s_add_u32 s7, s7, 0x100
	s_addc_u32 s27, s27, 0
	s_add_u32 s4, s4, 0x100
	s_addc_u32 s5, s5, 0
	s_cmp_ge_i32 s43, s51
	s_mov_b32 s43, s30
	s_cbranch_scc0 .LBB0_2007
	s_and_b64 vcc, exec, s[20:21]
	s_cbranch_vccz .LBB0_2010
	s_barrier

; #define PG8_STAGE(bufoff, gbase, voff) do { _Pragma("unroll") for (int _i = 0; _i < 2; ++_i) \
;         __builtin_amdgcn_global_load_lds((const unsigned*)((const char*)(gbase) + (voff)[_i]), (LAS unsigned*)(lds + (bufoff) + ldsw + _i * 8192), 16, 0, 0); } while (0)
; #define PG8_LDA(dst, b, h) do { _Pragma("unroll") for (int m = 0; m < 4; ++m) _Pragma("unroll") for (int k = 0; k < 2; ++k) dst[m][k] = *(const LAS bf16x8*)(lds + PG8_SA(b, h) + aoff + m * 2048 + k * 1024); } while (0)
; #define PG8_LDB(dst, b, h) do { _Pragma("unroll") for (int n = 0; n < 2; ++n) _Pragma("unroll") for (int k = 0; k < 2; ++k) dst[n][k] = *(const LAS bf16x8*)(lds + PG8_SB(b, h) + boff + n * 2048 + k * 1024); } while (0)
; #define PG8_WAIT_V(n) asm volatile("s_waitcnt vmcnt(" #n ")" ::: "memory")
; #define PG8_WAIT_L(n) asm volatile("s_waitcnt lgkmcnt(" #n ")" ::: "memory")
; template <class Epi, bool HAS_MID>
; __device__ __forceinline__ void gemm_phase(LAS unsigned char* lds, const Gemm g, const Sched& S, const Epi& E) {
;     ...
;         for (int t = 0; t < nt; t += 2) {
;             const bool last = (t == nt - 2);
;             const char* a1 = PG8_APT(t + 1);
;             const char* a2 = last ? nA : PG8_APT(t + 2); const char* b2 = last ? nB : cB + (size_t)(t + 2) * kstep;
;             const char* a3 = a2 + kstep; const char* b3 = b2 + kstep;
;             PG8_LDB(B0, 0, 0); PG8_LDB(B1, 0, 1); PG8_SCHED; PG8_LDA(At, 0, 0); PG8_STAGE(PG8_SA(1, 1), a1 + hstepA, voffA);
;             PG8_WAIT_V(8); PG8_WAIT_L(0); PG8_BAR; PG8_MMA(0, 0, At, B0); PG8_MMA(0, 1, At, B1); PG8_BAR; PG8_SCHED;
;             PG8_LDA(At, 0, 1); PG8_STAGE(PG8_SB(0, 0), b2, voffB); PG8_STAGE(PG8_SB(0, 1), b2 + hstepB, voffB); PG8_STAGE(PG8_SA(0, 0), a2, voffA);
;             PG8_WAIT_V(8); PG8_WAIT_L(0); PG8_BAR; PG8_MMA(1, 0, At, B0); PG8_MMA(1, 1, At, B1); PG8_BAR; PG8_SCHED;
;             PG8_LDB(B0, 1, 0); PG8_LDB(B1, 1, 1); PG8_SCHED; PG8_LDA(At, 1, 0); PG8_STAGE(PG8_SA(0, 1), a2 + hstepA, voffA);
;             PG8_WAIT_V(8); PG8_WAIT_L(0); PG8_BAR; PG8_MMA(0, 0, At, B0); PG8_MMA(0, 1, At, B1); PG8_BAR; PG8_SCHED;
;             PG8_LDA(At, 1, 1); PG8_STAGE(PG8_SB(1, 0), b3, voffB); PG8_STAGE(PG8_SB(1, 1), b3 + hstepB, voffB); PG8_STAGE(PG8_SA(1, 0), a3, voffA);
;             PG8_WAIT_V(8); PG8_WAIT_L(0); PG8_BAR; PG8_MMA(1, 0, At, B0); PG8_MMA(1, 1, At, B1); PG8_BAR; PG8_SCHED;
.LBB0_2218:
	s_add_u32 s30, s72, 0xfff80080
	s_addc_u32 s36, s73, -1
	s_add_i32 s37, 0, 0x10000
	s_cmp_eq_u32 s48, 28
	s_cselect_b32 s77, s23, s36
	s_cselect_b32 s76, s35, s30
	v_add_u32_e32 v138, s37, v142
	s_cselect_b32 s75, s21, s43
	s_cselect_b32 s74, s40, s42
	s_add_i32 s30, 0, 0x14000
	ds_read_b128 v[146:149], v138
	ds_read_b128 v[150:153], v138 offset:1024
	ds_read_b128 v[154:157], v138 offset:2048
	ds_read_b128 v[164:167], v138 offset:3072
	v_add_u32_e32 v138, s30, v142
	ds_read_b128 v[168:171], v138
	ds_read_b128 v[172:175], v138 offset:1024
	ds_read_b128 v[176:179], v138 offset:2048
	ds_read_b128 v[180:183], v138 offset:3072
	v_lshl_add_u64 v[138:139], s[72:73], 0, v[136:137]
	s_add_i32 m0, s71, 0xc000
	ds_read_b128 v[184:187], v144
	ds_read_b128 v[188:191], v144 offset:1024
	ds_read_b128 v[192:195], v144 offset:2048
	ds_read_b128 v[196:199], v144 offset:3072
	ds_read_b128 v[200:203], v144 offset:4096
	ds_read_b128 v[208:211], v144 offset:5120
	ds_read_b128 v[216:219], v144 offset:6144
	ds_read_b128 v[220:223], v144 offset:7168
	global_load_lds_dwordx4 v[138:139], off
	v_lshl_add_u64 v[138:139], s[72:73], 0, v[134:135]
	s_add_i32 m0, s71, 0xe000
	s_nop 0
	global_load_lds_dwordx4 v[138:139], off
	s_waitcnt vmcnt(8)
	s_waitcnt lgkmcnt(0)
	s_barrier
	s_waitcnt lgkmcnt(0)
	v_mfma_f32_16x16x32_bf16 v[124:127], v[146:149], v[184:187], v[124:127]
	v_mfma_f32_16x16x32_bf16 v[116:119], v[154:157], v[184:187], v[116:119]
	v_mfma_f32_16x16x32_bf16 v[108:111], v[146:149], v[192:195], v[108:111]
	v_mfma_f32_16x16x32_bf16 v[100:103], v[154:157], v[192:195], v[100:103]
	v_mfma_f32_16x16x32_bf16 v[92:95], v[146:149], v[200:203], v[92:95]
	v_mfma_f32_16x16x32_bf16 v[84:87], v[154:157], v[200:203], v[84:87]
	v_mfma_f32_16x16x32_bf16 v[76:79], v[146:149], v[216:219], v[76:79]
	v_mfma_f32_16x16x32_bf16 v[68:71], v[154:157], v[216:219], v[68:71]
	v_mfma_f32_16x16x32_bf16 v[124:127], v[150:153], v[188:191], v[124:127]
	v_mfma_f32_16x16x32_bf16 v[116:119], v[164:167], v[188:191], v[116:119]
	v_mfma_f32_16x16x32_bf16 v[108:111], v[150:153], v[196:199], v[108:111]
	v_mfma_f32_16x16x32_bf16 v[100:103], v[164:167], v[196:199], v[100:103]
	v_mfma_f32_16x16x32_bf16 v[92:95], v[150:153], v[208:211], v[92:95]
	v_mfma_f32_16x16x32_bf16 v[84:87], v[164:167], v[208:211], v[84:87]
	v_mfma_f32_16x16x32_bf16 v[76:79], v[150:153], v[220:223], v[76:79]
	v_mfma_f32_16x16x32_bf16 v[68:71], v[164:167], v[220:223], v[68:71]
	v_mfma_f32_16x16x32_bf16 v[120:123], v[168:171], v[184:187], v[120:123]
	v_mfma_f32_16x16x32_bf16 v[112:115], v[176:179], v[184:187], v[112:115]
	v_mfma_f32_16x16x32_bf16 v[104:107], v[168:171], v[192:195], v[104:107]
	v_mfma_f32_16x16x32_bf16 v[96:99], v[176:179], v[192:195], v[96:99]
	v_mfma_f32_16x16x32_bf16 v[88:91], v[168:171], v[200:203], v[88:91]
	v_mfma_f32_16x16x32_bf16 v[80:83], v[176:179], v[200:203], v[80:83]
	v_mfma_f32_16x16x32_bf16 v[72:75], v[168:171], v[216:219], v[72:75]
	v_mfma_f32_16x16x32_bf16 v[64:67], v[176:179], v[216:219], v[64:67]
	v_mfma_f32_16x16x32_bf16 v[120:123], v[172:175], v[188:191], v[120:123]
	v_mfma_f32_16x16x32_bf16 v[112:115], v[180:183], v[188:191], v[112:115]
	v_mfma_f32_16x16x32_bf16 v[104:107], v[172:175], v[196:199], v[104:107]
	v_mfma_f32_16x16x32_bf16 v[96:99], v[180:183], v[196:199], v[96:99]
	v_mfma_f32_16x16x32_bf16 v[88:91], v[172:175], v[208:211], v[88:91]
	v_mfma_f32_16x16x32_bf16 v[80:83], v[180:183], v[208:211], v[80:83]
	v_mfma_f32_16x16x32_bf16 v[72:75], v[172:175], v[220:223], v[72:75]
	v_mfma_f32_16x16x32_bf16 v[64:67], v[180:183], v[220:223], v[64:67]
	s_barrier
	s_add_i32 s36, s37, s81
	v_lshl_add_u64 v[138:139], s[74:75], 0, v[160:161]
	s_mov_b32 m0, s36
	ds_read_b128 v[184:187], v144 offset:16384
	ds_read_b128 v[188:191], v144 offset:17408
	ds_read_b128 v[192:195], v144 offset:18432
	ds_read_b128 v[196:199], v144 offset:19456
	ds_read_b128 v[200:203], v144 offset:20480
	ds_read_b128 v[208:211], v144 offset:21504
	ds_read_b128 v[216:219], v144 offset:22528
	ds_read_b128 v[220:223], v144 offset:23552
	global_load_lds_dwordx4 v[138:139], off
	s_add_i32 m0, s36, 0x2000
	s_add_u32 s64, s74, 0x80000
	v_lshl_add_u64 v[158:159], s[74:75], 0, v[132:133]
	s_addc_u32 s65, s75, 0
	s_add_i32 s30, s30, s81
	global_load_lds_dwordx4 v[158:159], off
	v_lshl_add_u64 v[204:205], s[64:65], 0, v[160:161]
	s_mov_b32 m0, s30
	v_lshl_add_u64 v[224:225], s[76:77], 0, v[130:131]
	global_load_lds_dwordx4 v[204:205], off
	v_lshl_add_u64 v[204:205], s[64:65], 0, v[132:133]
	s_add_i32 m0, s30, 0x2000
	s_nop 0
	global_load_lds_dwordx4 v[204:205], off
	v_lshl_add_u64 v[204:205], s[76:77], 0, v[128:129]
	s_mov_b32 m0, s71
	s_nop 0
	global_load_lds_dwordx4 v[204:205], off
	s_mov_b32 m0, s82
	s_nop 0
	global_load_lds_dwordx4 v[224:225], off
	s_waitcnt vmcnt(8)
	s_waitcnt lgkmcnt(0)
	s_barrier
; #define PG8_STAGE(bufoff, gbase, voff) do { _Pragma("unroll") for (int _i = 0; _i < 2; ++_i) \
;         __builtin_amdgcn_global_load_lds((const unsigned*)((const char*)(gbase) + (voff)[_i]), (LAS unsigned*)(lds + (bufoff) + ldsw + _i * 8192), 16, 0, 0); } while (0)
; #define PG8_LDA(dst, b, h) do { _Pragma("unroll") for (int m = 0; m < 4; ++m) _Pragma("unroll") for (int k = 0; k < 2; ++k) dst[m][k] = *(const LAS bf16x8*)(lds + PG8_SA(b, h) + aoff + m * 2048 + k * 1024); } while (0)
; #define PG8_LDB(dst, b, h) do { _Pragma("unroll") for (int n = 0; n < 2; ++n) _Pragma("unroll") for (int k = 0; k < 2; ++k) dst[n][k] = *(const LAS bf16x8*)(lds + PG8_SB(b, h) + boff + n * 2048 + k * 1024); } while (0)
; #define PG8_MMA(ai, bj, At, Bt) do { __builtin_amdgcn_s_setprio(1); _Pragma("unroll") for (int m = 0; m < 4; ++m) _Pragma("unroll") for (int n = 0; n < 2; ++n) _Pragma("unroll") for (int k = 0; k < 2; ++k) \
;         acc[ai][bj][m][n] = __builtin_amdgcn_mfma_f32_16x16x32_bf16(Bt[n][k], At[m][k], acc[ai][bj][m][n], 0, 0, 0); __builtin_amdgcn_s_setprio(0); } while (0)
; #define PG8_WAIT_V(n) asm volatile("s_waitcnt vmcnt(" #n ")" ::: "memory")
; #define PG8_WAIT_L(n) asm volatile("s_waitcnt lgkmcnt(" #n ")" ::: "memory")
; #define PG8_BAR __builtin_amdgcn_s_barrier()
; #define PG8_SCHED __builtin_amdgcn_sched_barrier(0)
; template <class Epi, bool HAS_MID>
; __device__ __forceinline__ void gemm_phase(LAS unsigned char* lds, const Gemm g, const Sched& S, const Epi& E) {
;     ...
;             PG8_WAIT_V(8); PG8_WAIT_L(0); PG8_BAR; PG8_MMA(1, 0, At, B0); PG8_MMA(1, 1, At, B1); PG8_BAR; PG8_SCHED;
;             PG8_LDB(B0, 1, 0); PG8_LDB(B1, 1, 1); PG8_SCHED; PG8_LDA(At, 1, 0); PG8_STAGE(PG8_SA(0, 1), a2 + hstepA, voffA);
;             PG8_WAIT_V(8); PG8_WAIT_L(0); PG8_BAR; PG8_MMA(0, 0, At, B0); PG8_MMA(0, 1, At, B1); PG8_BAR; PG8_SCHED;
;             PG8_LDA(At, 1, 1); PG8_STAGE(PG8_SB(1, 0), b3, voffB); PG8_STAGE(PG8_SB(1, 1), b3 + hstepB, voffB); PG8_STAGE(PG8_SA(1, 0), a3, voffA);
	s_waitcnt lgkmcnt(0)
	v_mfma_f32_16x16x32_bf16 v[60:63], v[146:149], v[184:187], v[60:63]
	v_mfma_f32_16x16x32_bf16 v[52:55], v[154:157], v[184:187], v[52:55]
	v_mfma_f32_16x16x32_bf16 v[44:47], v[146:149], v[192:195], v[44:47]
	v_mfma_f32_16x16x32_bf16 v[36:39], v[154:157], v[192:195], v[36:39]
	v_mfma_f32_16x16x32_bf16 v[28:31], v[146:149], v[200:203], v[28:31]
	v_mfma_f32_16x16x32_bf16 v[20:23], v[154:157], v[200:203], v[20:23]
	v_mfma_f32_16x16x32_bf16 v[12:15], v[146:149], v[216:219], v[12:15]
	v_mfma_f32_16x16x32_bf16 v[4:7], v[154:157], v[216:219], v[4:7]
	v_mfma_f32_16x16x32_bf16 v[60:63], v[150:153], v[188:191], v[60:63]
	v_mfma_f32_16x16x32_bf16 v[52:55], v[164:167], v[188:191], v[52:55]
	v_mfma_f32_16x16x32_bf16 v[44:47], v[150:153], v[196:199], v[44:47]
	v_mfma_f32_16x16x32_bf16 v[36:39], v[164:167], v[196:199], v[36:39]
	v_mfma_f32_16x16x32_bf16 v[28:31], v[150:153], v[208:211], v[28:31]
	v_mfma_f32_16x16x32_bf16 v[20:23], v[164:167], v[208:211], v[20:23]
	v_mfma_f32_16x16x32_bf16 v[12:15], v[150:153], v[220:223], v[12:15]
	v_mfma_f32_16x16x32_bf16 v[4:7], v[164:167], v[220:223], v[4:7]
	v_mfma_f32_16x16x32_bf16 v[56:59], v[168:171], v[184:187], v[56:59]
	v_mfma_f32_16x16x32_bf16 v[48:51], v[176:179], v[184:187], v[48:51]
	v_mfma_f32_16x16x32_bf16 v[40:43], v[168:171], v[192:195], v[40:43]
	v_mfma_f32_16x16x32_bf16 v[32:35], v[176:179], v[192:195], v[32:35]
	v_mfma_f32_16x16x32_bf16 v[24:27], v[168:171], v[200:203], v[24:27]
	v_mfma_f32_16x16x32_bf16 v[16:19], v[176:179], v[200:203], v[16:19]
	v_mfma_f32_16x16x32_bf16 v[8:11], v[168:171], v[216:219], v[8:11]
	v_mfma_f32_16x16x32_bf16 v[0:3], v[176:179], v[216:219], v[0:3]
	v_mfma_f32_16x16x32_bf16 v[56:59], v[172:175], v[188:191], v[56:59]
	v_mfma_f32_16x16x32_bf16 v[48:51], v[180:183], v[188:191], v[48:51]
	v_mfma_f32_16x16x32_bf16 v[40:43], v[172:175], v[196:199], v[40:43]
	v_mfma_f32_16x16x32_bf16 v[32:35], v[180:183], v[196:199], v[32:35]
	v_mfma_f32_16x16x32_bf16 v[24:27], v[172:175], v[208:211], v[24:27]
	v_mfma_f32_16x16x32_bf16 v[16:19], v[180:183], v[208:211], v[16:19]
	v_mfma_f32_16x16x32_bf16 v[8:11], v[172:175], v[220:223], v[8:11]
	v_mfma_f32_16x16x32_bf16 v[0:3], v[180:183], v[220:223], v[0:3]
	s_barrier
	s_add_i32 s30, 0, 0x18000
	v_add_u32_e32 v145, s30, v142
	s_add_i32 s36, 0, 0x1c000
	ds_read_b128 v[146:149], v145
	ds_read_b128 v[150:153], v145 offset:1024
	ds_read_b128 v[154:157], v145 offset:2048
	ds_read_b128 v[164:167], v145 offset:3072
	v_add_u32_e32 v145, s36, v142
	ds_read_b128 v[168:171], v145
	ds_read_b128 v[172:175], v145 offset:1024
	ds_read_b128 v[176:179], v145 offset:2048
	ds_read_b128 v[180:183], v145 offset:3072
	s_add_u32 s64, s76, 0x80000
	s_addc_u32 s65, s77, 0
	s_mov_b32 m0, s83
	v_lshl_add_u64 v[226:227], s[64:65], 0, v[128:129]
	ds_read_b128 v[184:187], v144 offset:32768
	ds_read_b128 v[188:191], v144 offset:33792
	ds_read_b128 v[192:195], v144 offset:34816
	ds_read_b128 v[196:199], v144 offset:35840
	ds_read_b128 v[200:203], v144 offset:36864
	ds_read_b128 v[208:211], v144 offset:37888
	ds_read_b128 v[216:219], v144 offset:38912
	ds_read_b128 v[220:223], v144 offset:39936
	global_load_lds_dwordx4 v[226:227], off
	v_lshl_add_u64 v[226:227], s[64:65], 0, v[130:131]
	s_mov_b32 m0, s84
	s_nop 0
	global_load_lds_dwordx4 v[226:227], off
	s_waitcnt vmcnt(8)
	s_waitcnt lgkmcnt(0)
	s_barrier
	s_waitcnt lgkmcnt(0)
	v_mfma_f32_16x16x32_bf16 v[124:127], v[146:149], v[184:187], v[124:127]
	v_mfma_f32_16x16x32_bf16 v[116:119], v[154:157], v[184:187], v[116:119]
	v_mfma_f32_16x16x32_bf16 v[108:111], v[146:149], v[192:195], v[108:111]
	v_mfma_f32_16x16x32_bf16 v[100:103], v[154:157], v[192:195], v[100:103]
	v_mfma_f32_16x16x32_bf16 v[92:95], v[146:149], v[200:203], v[92:95]
	v_mfma_f32_16x16x32_bf16 v[84:87], v[154:157], v[200:203], v[84:87]
	v_mfma_f32_16x16x32_bf16 v[76:79], v[146:149], v[216:219], v[76:79]
	v_mfma_f32_16x16x32_bf16 v[68:71], v[154:157], v[216:219], v[68:71]
	v_mfma_f32_16x16x32_bf16 v[124:127], v[150:153], v[188:191], v[124:127]
	v_mfma_f32_16x16x32_bf16 v[116:119], v[164:167], v[188:191], v[116:119]
	v_mfma_f32_16x16x32_bf16 v[108:111], v[150:153], v[196:199], v[108:111]
	v_mfma_f32_16x16x32_bf16 v[100:103], v[164:167], v[196:199], v[100:103]
	v_mfma_f32_16x16x32_bf16 v[92:95], v[150:153], v[208:211], v[92:95]
	v_mfma_f32_16x16x32_bf16 v[84:87], v[164:167], v[208:211], v[84:87]
	v_mfma_f32_16x16x32_bf16 v[76:79], v[150:153], v[220:223], v[76:79]
	v_mfma_f32_16x16x32_bf16 v[68:71], v[164:167], v[220:223], v[68:71]
	v_mfma_f32_16x16x32_bf16 v[120:123], v[168:171], v[184:187], v[120:123]
	v_mfma_f32_16x16x32_bf16 v[112:115], v[176:179], v[184:187], v[112:115]
	v_mfma_f32_16x16x32_bf16 v[104:107], v[168:171], v[192:195], v[104:107]
	v_mfma_f32_16x16x32_bf16 v[96:99], v[176:179], v[192:195], v[96:99]
	v_mfma_f32_16x16x32_bf16 v[88:91], v[168:171], v[200:203], v[88:91]
	v_mfma_f32_16x16x32_bf16 v[80:83], v[176:179], v[200:203], v[80:83]
	v_mfma_f32_16x16x32_bf16 v[72:75], v[168:171], v[216:219], v[72:75]
	v_mfma_f32_16x16x32_bf16 v[64:67], v[176:179], v[216:219], v[64:67]
	v_mfma_f32_16x16x32_bf16 v[120:123], v[172:175], v[188:191], v[120:123]
	v_mfma_f32_16x16x32_bf16 v[112:115], v[180:183], v[188:191], v[112:115]
	v_mfma_f32_16x16x32_bf16 v[104:107], v[172:175], v[196:199], v[104:107]
	v_mfma_f32_16x16x32_bf16 v[96:99], v[180:183], v[196:199], v[96:99]
	v_mfma_f32_16x16x32_bf16 v[88:91], v[172:175], v[208:211], v[88:91]
	v_mfma_f32_16x16x32_bf16 v[80:83], v[180:183], v[208:211], v[80:83]
	v_mfma_f32_16x16x32_bf16 v[72:75], v[172:175], v[220:223], v[72:75]
	v_mfma_f32_16x16x32_bf16 v[64:67], v[180:183], v[220:223], v[64:67]
	s_barrier
; #define PG8_STAGE(bufoff, gbase, voff) do { _Pragma("unroll") for (int _i = 0; _i < 2; ++_i) \
;         __builtin_amdgcn_global_load_lds((const unsigned*)((const char*)(gbase) + (voff)[_i]), (LAS unsigned*)(lds + (bufoff) + ldsw + _i * 8192), 16, 0, 0); } while (0)
; #define PG8_LDA(dst, b, h) do { _Pragma("unroll") for (int m = 0; m < 4; ++m) _Pragma("unroll") for (int k = 0; k < 2; ++k) dst[m][k] = *(const LAS bf16x8*)(lds + PG8_SA(b, h) + aoff + m * 2048 + k * 1024); } while (0)
; #define PG8_MMA(ai, bj, At, Bt) do { __builtin_amdgcn_s_setprio(1); _Pragma("unroll") for (int m = 0; m < 4; ++m) _Pragma("unroll") for (int n = 0; n < 2; ++n) _Pragma("unroll") for (int k = 0; k < 2; ++k) \
;         acc[ai][bj][m][n] = __builtin_amdgcn_mfma_f32_16x16x32_bf16(Bt[n][k], At[m][k], acc[ai][bj][m][n], 0, 0, 0); __builtin_amdgcn_s_setprio(0); } while (0)
; #define PG8_WAIT_V(n) asm volatile("s_waitcnt vmcnt(" #n ")" ::: "memory")
; #define PG8_WAIT_L(n) asm volatile("s_waitcnt lgkmcnt(" #n ")" ::: "memory")
; #define PG8_BAR __builtin_amdgcn_s_barrier()
; #define PG8_SCHED __builtin_amdgcn_sched_barrier(0)
; template <class Epi, bool HAS_MID>
; __device__ __forceinline__ void gemm_phase(LAS unsigned char* lds, const Gemm g, const Sched& S, const Epi& E) {
;     ...
;             PG8_LDA(At, 1, 1); PG8_STAGE(PG8_SB(1, 0), b3, voffB); PG8_STAGE(PG8_SB(1, 1), b3 + hstepB, voffB); PG8_STAGE(PG8_SA(1, 0), a3, voffA);
;             PG8_WAIT_V(8); PG8_WAIT_L(0); PG8_BAR; PG8_MMA(1, 0, At, B0); PG8_MMA(1, 1, At, B1); PG8_BAR; PG8_SCHED;
;         }
;         if (wr == 0) PG8_BAR;
	s_add_i32 s30, s30, s81
	v_lshl_add_u64 v[138:139], v[138:139], 0, s[38:39]
	s_mov_b32 m0, s30
	ds_read_b128 v[184:187], v144 offset:49152
	ds_read_b128 v[188:191], v144 offset:50176
	ds_read_b128 v[192:195], v144 offset:51200
	ds_read_b128 v[196:199], v144 offset:52224
	ds_read_b128 v[200:203], v144 offset:53248
	ds_read_b128 v[208:211], v144 offset:54272
	ds_read_b128 v[216:219], v144 offset:55296
	ds_read_b128 v[220:223], v144 offset:56320
	global_load_lds_dwordx4 v[138:139], off
	s_add_i32 m0, s30, 0x2000
	s_add_u32 s64, s74, 0x80080
	v_lshl_add_u64 v[138:139], v[158:159], 0, s[38:39]
	s_addc_u32 s65, s75, 0
	s_add_i32 s30, s36, s81
	global_load_lds_dwordx4 v[138:139], off
	v_lshl_add_u64 v[138:139], s[64:65], 0, v[160:161]
	s_mov_b32 m0, s30
	s_nop 0
	global_load_lds_dwordx4 v[138:139], off
	v_lshl_add_u64 v[138:139], s[64:65], 0, v[132:133]
	s_add_i32 m0, s30, 0x2000
	s_nop 0
	global_load_lds_dwordx4 v[138:139], off
	v_lshl_add_u64 v[138:139], v[204:205], 0, s[38:39]
	s_mov_b32 m0, s85
	s_nop 0
	global_load_lds_dwordx4 v[138:139], off
	v_lshl_add_u64 v[138:139], v[224:225], 0, s[38:39]
	s_mov_b32 m0, s86
	s_nop 0
	global_load_lds_dwordx4 v[138:139], off
	s_waitcnt vmcnt(8)
	s_waitcnt lgkmcnt(0)
	s_barrier
	s_waitcnt lgkmcnt(0)
	v_mfma_f32_16x16x32_bf16 v[60:63], v[146:149], v[184:187], v[60:63]
	v_mfma_f32_16x16x32_bf16 v[52:55], v[154:157], v[184:187], v[52:55]
	v_mfma_f32_16x16x32_bf16 v[44:47], v[146:149], v[192:195], v[44:47]
	v_mfma_f32_16x16x32_bf16 v[36:39], v[154:157], v[192:195], v[36:39]
	v_mfma_f32_16x16x32_bf16 v[28:31], v[146:149], v[200:203], v[28:31]
	v_mfma_f32_16x16x32_bf16 v[20:23], v[154:157], v[200:203], v[20:23]
	v_mfma_f32_16x16x32_bf16 v[12:15], v[146:149], v[216:219], v[12:15]
	v_mfma_f32_16x16x32_bf16 v[4:7], v[154:157], v[216:219], v[4:7]
	v_mfma_f32_16x16x32_bf16 v[60:63], v[150:153], v[188:191], v[60:63]
	v_mfma_f32_16x16x32_bf16 v[52:55], v[164:167], v[188:191], v[52:55]
	v_mfma_f32_16x16x32_bf16 v[44:47], v[150:153], v[196:199], v[44:47]
	v_mfma_f32_16x16x32_bf16 v[36:39], v[164:167], v[196:199], v[36:39]
	v_mfma_f32_16x16x32_bf16 v[28:31], v[150:153], v[208:211], v[28:31]
	v_mfma_f32_16x16x32_bf16 v[20:23], v[164:167], v[208:211], v[20:23]
	v_mfma_f32_16x16x32_bf16 v[12:15], v[150:153], v[220:223], v[12:15]
	v_mfma_f32_16x16x32_bf16 v[4:7], v[164:167], v[220:223], v[4:7]
	v_mfma_f32_16x16x32_bf16 v[56:59], v[168:171], v[184:187], v[56:59]
	v_mfma_f32_16x16x32_bf16 v[48:51], v[176:179], v[184:187], v[48:51]
	v_mfma_f32_16x16x32_bf16 v[40:43], v[168:171], v[192:195], v[40:43]
	v_mfma_f32_16x16x32_bf16 v[32:35], v[176:179], v[192:195], v[32:35]
	v_mfma_f32_16x16x32_bf16 v[24:27], v[168:171], v[200:203], v[24:27]
	v_mfma_f32_16x16x32_bf16 v[16:19], v[176:179], v[200:203], v[16:19]
	v_mfma_f32_16x16x32_bf16 v[8:11], v[168:171], v[216:219], v[8:11]
	v_mfma_f32_16x16x32_bf16 v[0:3], v[176:179], v[216:219], v[0:3]
	v_mfma_f32_16x16x32_bf16 v[56:59], v[172:175], v[188:191], v[56:59]
	v_mfma_f32_16x16x32_bf16 v[48:51], v[180:183], v[188:191], v[48:51]
	v_mfma_f32_16x16x32_bf16 v[40:43], v[172:175], v[196:199], v[40:43]
	v_mfma_f32_16x16x32_bf16 v[32:35], v[180:183], v[196:199], v[32:35]
	v_mfma_f32_16x16x32_bf16 v[24:27], v[172:175], v[208:211], v[24:27]
	v_mfma_f32_16x16x32_bf16 v[16:19], v[180:183], v[208:211], v[16:19]
	v_mfma_f32_16x16x32_bf16 v[8:11], v[172:175], v[220:223], v[8:11]
	v_mfma_f32_16x16x32_bf16 v[0:3], v[180:183], v[220:223], v[0:3]
	s_barrier
	s_add_i32 s48, s48, 2
	s_add_u32 s42, s42, 0x100
	s_addc_u32 s43, s43, 0
	s_add_u32 s72, s72, 0x100
	s_addc_u32 s73, s73, 0
	s_cmp_gt_u32 s48, 29
	s_cbranch_scc0 .LBB0_2218
	s_and_b64 vcc, exec, s[18:19]
	s_cbranch_vccz .LBB0_2221
	s_barrier

; #define PG8_STAGE(bufoff, gbase, voff) do { _Pragma("unroll") for (int _i = 0; _i < 2; ++_i) \
;         __builtin_amdgcn_global_load_lds((const unsigned*)((const char*)(gbase) + (voff)[_i]), (LAS unsigned*)(lds + (bufoff) + ldsw + _i * 8192), 16, 0, 0); } while (0)
; #define PG8_LDA(dst, b, h) do { _Pragma("unroll") for (int m = 0; m < 4; ++m) _Pragma("unroll") for (int k = 0; k < 2; ++k) dst[m][k] = *(const LAS bf16x8*)(lds + PG8_SA(b, h) + aoff + m * 2048 + k * 1024); } while (0)
; #define PG8_LDB(dst, b, h) do { _Pragma("unroll") for (int n = 0; n < 2; ++n) _Pragma("unroll") for (int k = 0; k < 2; ++k) dst[n][k] = *(const LAS bf16x8*)(lds + PG8_SB(b, h) + boff + n * 2048 + k * 1024); } while (0)
; #define PG8_WAIT_V(n) asm volatile("s_waitcnt vmcnt(" #n ")" ::: "memory")
; #define PG8_WAIT_L(n) asm volatile("s_waitcnt lgkmcnt(" #n ")" ::: "memory")
; template <class Epi, bool HAS_MID>
; __device__ __forceinline__ void gemm_phase(LAS unsigned char* lds, const Gemm g, const Sched& S, const Epi& E) {
;     ...
;         for (int t = 0; t < nt; t += 2) {
;             const bool last = (t == nt - 2);
;             const char* a1 = PG8_APT(t + 1);
;             const char* a2 = last ? nA : PG8_APT(t + 2); const char* b2 = last ? nB : cB + (size_t)(t + 2) * kstep;
;             const char* a3 = a2 + kstep; const char* b3 = b2 + kstep;
;             PG8_LDB(B0, 0, 0); PG8_LDB(B1, 0, 1); PG8_SCHED; PG8_LDA(At, 0, 0); PG8_STAGE(PG8_SA(1, 1), a1 + hstepA, voffA);
;             PG8_WAIT_V(8); PG8_WAIT_L(0); PG8_BAR; PG8_MMA(0, 0, At, B0); PG8_MMA(0, 1, At, B1); PG8_BAR; PG8_SCHED;
;             PG8_LDA(At, 0, 1); PG8_STAGE(PG8_SB(0, 0), b2, voffB); PG8_STAGE(PG8_SB(0, 1), b2 + hstepB, voffB); PG8_STAGE(PG8_SA(0, 0), a2, voffA);
;             PG8_WAIT_V(8); PG8_WAIT_L(0); PG8_BAR; PG8_MMA(1, 0, At, B0); PG8_MMA(1, 1, At, B1); PG8_BAR; PG8_SCHED;
;             PG8_LDB(B0, 1, 0); PG8_LDB(B1, 1, 1); PG8_SCHED; PG8_LDA(At, 1, 0); PG8_STAGE(PG8_SA(0, 1), a2 + hstepA, voffA);
;             PG8_WAIT_V(8); PG8_WAIT_L(0); PG8_BAR; PG8_MMA(0, 0, At, B0); PG8_MMA(0, 1, At, B1); PG8_BAR; PG8_SCHED;
;             PG8_LDA(At, 1, 1); PG8_STAGE(PG8_SB(1, 0), b3, voffB); PG8_STAGE(PG8_SB(1, 1), b3 + hstepB, voffB); PG8_STAGE(PG8_SA(1, 0), a3, voffA);
;             PG8_WAIT_V(8); PG8_WAIT_L(0); PG8_BAR; PG8_MMA(1, 0, At, B0); PG8_MMA(1, 1, At, B1); PG8_BAR; PG8_SCHED;
.LBB0_3020:
	s_add_u32 s4, s74, 0x100
	s_addc_u32 s5, s75, 0
	s_add_i32 s30, 0, 0x10000
	s_cmp_eq_u32 s84, s94
	s_cselect_b32 s79, s69, s5
	s_cselect_b32 s78, s68, s4
	s_cselect_b32 s77, s71, s89
	s_cselect_b32 s76, s70, s27
	s_add_i32 s36, 0, 0x14000
	v_add_u32_e32 v170, s30, v187
	v_add_u32_e32 v190, s36, v187
	ds_read_b128 v[128:131], v170
	ds_read_b128 v[132:135], v170 offset:1024
	ds_read_b128 v[136:139], v170 offset:2048
	ds_read_b128 v[170:173], v170 offset:3072
	ds_read_b128 v[174:177], v190
	ds_read_b128 v[178:181], v190 offset:1024
	ds_read_b128 v[182:185], v190 offset:2048
	ds_read_b128 v[190:193], v190 offset:3072
	v_lshl_add_u64 v[232:233], s[74:75], 0, v[168:169]
	s_add_i32 m0, s23, 0xc000
	ds_read_b128 v[194:197], v189
	ds_read_b128 v[198:201], v189 offset:1024
	ds_read_b128 v[202:205], v189 offset:2048
	ds_read_b128 v[208:211], v189 offset:3072
	ds_read_b128 v[216:219], v189 offset:4096
	ds_read_b128 v[220:223], v189 offset:5120
	ds_read_b128 v[224:227], v189 offset:6144
	ds_read_b128 v[228:231], v189 offset:7168
	global_load_lds_dwordx4 v[232:233], off
	v_lshl_add_u64 v[232:233], s[74:75], 0, v[166:167]
	s_add_i32 m0, s23, 0xe000
	s_nop 0
	global_load_lds_dwordx4 v[232:233], off
	s_waitcnt vmcnt(8)
	s_waitcnt lgkmcnt(0)
	s_barrier
	s_waitcnt lgkmcnt(0)
	v_mfma_f32_16x16x32_bf16 v[124:127], v[128:131], v[194:197], v[124:127]
	v_mfma_f32_16x16x32_bf16 v[120:123], v[136:139], v[194:197], v[120:123]
	v_mfma_f32_16x16x32_bf16 v[116:119], v[128:131], v[202:205], v[116:119]
	v_mfma_f32_16x16x32_bf16 v[112:115], v[136:139], v[202:205], v[112:115]
	v_mfma_f32_16x16x32_bf16 v[108:111], v[128:131], v[216:219], v[108:111]
	v_mfma_f32_16x16x32_bf16 v[104:107], v[136:139], v[216:219], v[104:107]
	v_mfma_f32_16x16x32_bf16 v[100:103], v[128:131], v[224:227], v[100:103]
	v_mfma_f32_16x16x32_bf16 v[96:99], v[136:139], v[224:227], v[96:99]
	v_mfma_f32_16x16x32_bf16 v[124:127], v[132:135], v[198:201], v[124:127]
	v_mfma_f32_16x16x32_bf16 v[120:123], v[170:173], v[198:201], v[120:123]
	v_mfma_f32_16x16x32_bf16 v[116:119], v[132:135], v[208:211], v[116:119]
	v_mfma_f32_16x16x32_bf16 v[112:115], v[170:173], v[208:211], v[112:115]
	v_mfma_f32_16x16x32_bf16 v[108:111], v[132:135], v[220:223], v[108:111]
	v_mfma_f32_16x16x32_bf16 v[104:107], v[170:173], v[220:223], v[104:107]
	v_mfma_f32_16x16x32_bf16 v[100:103], v[132:135], v[228:231], v[100:103]
	v_mfma_f32_16x16x32_bf16 v[96:99], v[170:173], v[228:231], v[96:99]
	v_mfma_f32_16x16x32_bf16 v[60:63], v[174:177], v[194:197], v[60:63]
	v_mfma_f32_16x16x32_bf16 v[56:59], v[182:185], v[194:197], v[56:59]
	v_mfma_f32_16x16x32_bf16 v[52:55], v[174:177], v[202:205], v[52:55]
	v_mfma_f32_16x16x32_bf16 v[48:51], v[182:185], v[202:205], v[48:51]
	v_mfma_f32_16x16x32_bf16 v[44:47], v[174:177], v[216:219], v[44:47]
	v_mfma_f32_16x16x32_bf16 v[40:43], v[182:185], v[216:219], v[40:43]
	v_mfma_f32_16x16x32_bf16 v[36:39], v[174:177], v[224:227], v[36:39]
	v_mfma_f32_16x16x32_bf16 v[32:35], v[182:185], v[224:227], v[32:35]
	v_mfma_f32_16x16x32_bf16 v[60:63], v[178:181], v[198:201], v[60:63]
	v_mfma_f32_16x16x32_bf16 v[56:59], v[190:193], v[198:201], v[56:59]
	v_mfma_f32_16x16x32_bf16 v[52:55], v[178:181], v[208:211], v[52:55]
	v_mfma_f32_16x16x32_bf16 v[48:51], v[190:193], v[208:211], v[48:51]
	v_mfma_f32_16x16x32_bf16 v[44:47], v[178:181], v[220:223], v[44:47]
	v_mfma_f32_16x16x32_bf16 v[40:43], v[190:193], v[220:223], v[40:43]
	v_mfma_f32_16x16x32_bf16 v[36:39], v[178:181], v[228:231], v[36:39]
	v_mfma_f32_16x16x32_bf16 v[32:35], v[190:193], v[228:231], v[32:35]
	s_barrier
	s_add_i32 s30, s30, s52
	v_lshl_add_u64 v[232:233], s[76:77], 0, v[160:161]
	s_mov_b32 m0, s30
	ds_read_b128 v[194:197], v189 offset:16384
	ds_read_b128 v[198:201], v189 offset:17408
	ds_read_b128 v[202:205], v189 offset:18432
	ds_read_b128 v[208:211], v189 offset:19456
	ds_read_b128 v[216:219], v189 offset:20480
	ds_read_b128 v[220:223], v189 offset:21504
	ds_read_b128 v[224:227], v189 offset:22528
	ds_read_b128 v[228:231], v189 offset:23552
	global_load_lds_dwordx4 v[232:233], off
	s_add_i32 m0, s30, 0x2000
	s_add_u32 s64, s76, 0x160000
	v_lshl_add_u64 v[234:235], s[76:77], 0, v[144:145]
	s_addc_u32 s65, s77, 0
	s_add_i32 s30, s36, s52
	global_load_lds_dwordx4 v[234:235], off
	v_lshl_add_u64 v[236:237], s[64:65], 0, v[160:161]
	s_mov_b32 m0, s30
	v_lshl_add_u64 v[238:239], s[78:79], 0, v[142:143]
	global_load_lds_dwordx4 v[236:237], off
	v_lshl_add_u64 v[236:237], s[64:65], 0, v[144:145]
	s_add_i32 m0, s30, 0x2000
	s_nop 0
	global_load_lds_dwordx4 v[236:237], off
	v_lshl_add_u64 v[236:237], s[78:79], 0, v[140:141]
	s_mov_b32 m0, s23
	s_nop 0
	global_load_lds_dwordx4 v[236:237], off
	s_mov_b32 m0, s56
	s_nop 0
	global_load_lds_dwordx4 v[238:239], off
	s_waitcnt vmcnt(8)
	s_waitcnt lgkmcnt(0)
	s_barrier
; #define PG8_STAGE(bufoff, gbase, voff) do { _Pragma("unroll") for (int _i = 0; _i < 2; ++_i) \
;         __builtin_amdgcn_global_load_lds((const unsigned*)((const char*)(gbase) + (voff)[_i]), (LAS unsigned*)(lds + (bufoff) + ldsw + _i * 8192), 16, 0, 0); } while (0)
; #define PG8_LDA(dst, b, h) do { _Pragma("unroll") for (int m = 0; m < 4; ++m) _Pragma("unroll") for (int k = 0; k < 2; ++k) dst[m][k] = *(const LAS bf16x8*)(lds + PG8_SA(b, h) + aoff + m * 2048 + k * 1024); } while (0)
; #define PG8_LDB(dst, b, h) do { _Pragma("unroll") for (int n = 0; n < 2; ++n) _Pragma("unroll") for (int k = 0; k < 2; ++k) dst[n][k] = *(const LAS bf16x8*)(lds + PG8_SB(b, h) + boff + n * 2048 + k * 1024); } while (0)
; #define PG8_MMA(ai, bj, At, Bt) do { __builtin_amdgcn_s_setprio(1); _Pragma("unroll") for (int m = 0; m < 4; ++m) _Pragma("unroll") for (int n = 0; n < 2; ++n) _Pragma("unroll") for (int k = 0; k < 2; ++k) \
;         acc[ai][bj][m][n] = __builtin_amdgcn_mfma_f32_16x16x32_bf16(Bt[n][k], At[m][k], acc[ai][bj][m][n], 0, 0, 0); __builtin_amdgcn_s_setprio(0); } while (0)
; #define PG8_WAIT_V(n) asm volatile("s_waitcnt vmcnt(" #n ")" ::: "memory")
; #define PG8_WAIT_L(n) asm volatile("s_waitcnt lgkmcnt(" #n ")" ::: "memory")
; #define PG8_BAR __builtin_amdgcn_s_barrier()
; #define PG8_SCHED __builtin_amdgcn_sched_barrier(0)
; template <class Epi, bool HAS_MID>
; __device__ __forceinline__ void gemm_phase(LAS unsigned char* lds, const Gemm g, const Sched& S, const Epi& E) {
;     ...
;             PG8_WAIT_V(8); PG8_WAIT_L(0); PG8_BAR; PG8_MMA(1, 0, At, B0); PG8_MMA(1, 1, At, B1); PG8_BAR; PG8_SCHED;
;             PG8_LDB(B0, 1, 0); PG8_LDB(B1, 1, 1); PG8_SCHED; PG8_LDA(At, 1, 0); PG8_STAGE(PG8_SA(0, 1), a2 + hstepA, voffA);
;             PG8_WAIT_V(8); PG8_WAIT_L(0); PG8_BAR; PG8_MMA(0, 0, At, B0); PG8_MMA(0, 1, At, B1); PG8_BAR; PG8_SCHED;
;             PG8_LDA(At, 1, 1); PG8_STAGE(PG8_SB(1, 0), b3, voffB); PG8_STAGE(PG8_SB(1, 1), b3 + hstepB, voffB); PG8_STAGE(PG8_SA(1, 0), a3, voffA);
	s_waitcnt lgkmcnt(0)
	v_mfma_f32_16x16x32_bf16 v[92:95], v[128:131], v[194:197], v[92:95]
	v_mfma_f32_16x16x32_bf16 v[88:91], v[136:139], v[194:197], v[88:91]
	v_mfma_f32_16x16x32_bf16 v[84:87], v[128:131], v[202:205], v[84:87]
	v_mfma_f32_16x16x32_bf16 v[80:83], v[136:139], v[202:205], v[80:83]
	v_mfma_f32_16x16x32_bf16 v[76:79], v[128:131], v[216:219], v[76:79]
	v_mfma_f32_16x16x32_bf16 v[72:75], v[136:139], v[216:219], v[72:75]
	v_mfma_f32_16x16x32_bf16 v[68:71], v[128:131], v[224:227], v[68:71]
	v_mfma_f32_16x16x32_bf16 v[64:67], v[136:139], v[224:227], v[64:67]
	v_mfma_f32_16x16x32_bf16 v[92:95], v[132:135], v[198:201], v[92:95]
	v_mfma_f32_16x16x32_bf16 v[88:91], v[170:173], v[198:201], v[88:91]
	v_mfma_f32_16x16x32_bf16 v[84:87], v[132:135], v[208:211], v[84:87]
	v_mfma_f32_16x16x32_bf16 v[80:83], v[170:173], v[208:211], v[80:83]
	v_mfma_f32_16x16x32_bf16 v[76:79], v[132:135], v[220:223], v[76:79]
	v_mfma_f32_16x16x32_bf16 v[72:75], v[170:173], v[220:223], v[72:75]
	v_mfma_f32_16x16x32_bf16 v[68:71], v[132:135], v[228:231], v[68:71]
	v_mfma_f32_16x16x32_bf16 v[64:67], v[170:173], v[228:231], v[64:67]
	v_mfma_f32_16x16x32_bf16 v[28:31], v[174:177], v[194:197], v[28:31]
	v_mfma_f32_16x16x32_bf16 v[24:27], v[182:185], v[194:197], v[24:27]
	v_mfma_f32_16x16x32_bf16 v[20:23], v[174:177], v[202:205], v[20:23]
	v_mfma_f32_16x16x32_bf16 v[16:19], v[182:185], v[202:205], v[16:19]
	v_mfma_f32_16x16x32_bf16 v[12:15], v[174:177], v[216:219], v[12:15]
	v_mfma_f32_16x16x32_bf16 v[8:11], v[182:185], v[216:219], v[8:11]
	v_mfma_f32_16x16x32_bf16 v[4:7], v[174:177], v[224:227], v[4:7]
	v_mfma_f32_16x16x32_bf16 v[0:3], v[182:185], v[224:227], v[0:3]
	v_mfma_f32_16x16x32_bf16 v[28:31], v[178:181], v[198:201], v[28:31]
	v_mfma_f32_16x16x32_bf16 v[24:27], v[190:193], v[198:201], v[24:27]
	v_mfma_f32_16x16x32_bf16 v[20:23], v[178:181], v[208:211], v[20:23]
	v_mfma_f32_16x16x32_bf16 v[16:19], v[190:193], v[208:211], v[16:19]
	v_mfma_f32_16x16x32_bf16 v[12:15], v[178:181], v[220:223], v[12:15]
	v_mfma_f32_16x16x32_bf16 v[8:11], v[190:193], v[220:223], v[8:11]
	v_mfma_f32_16x16x32_bf16 v[4:7], v[178:181], v[228:231], v[4:7]
	v_mfma_f32_16x16x32_bf16 v[0:3], v[190:193], v[228:231], v[0:3]
	s_barrier
	s_add_i32 s30, 0, 0x18000
	s_add_i32 s36, 0, 0x1c000
	v_add_u32_e32 v170, s30, v187
	v_add_u32_e32 v190, s36, v187
	ds_read_b128 v[128:131], v170
	ds_read_b128 v[132:135], v170 offset:1024
	ds_read_b128 v[136:139], v170 offset:2048
	ds_read_b128 v[170:173], v170 offset:3072
	ds_read_b128 v[174:177], v190
	ds_read_b128 v[178:181], v190 offset:1024
	ds_read_b128 v[182:185], v190 offset:2048
	ds_read_b128 v[190:193], v190 offset:3072
	s_add_u32 s64, s78, 0x160000
	s_addc_u32 s65, s79, 0
	s_mov_b32 m0, s57
	v_lshl_add_u64 v[240:241], s[64:65], 0, v[140:141]
	ds_read_b128 v[194:197], v189 offset:32768
	ds_read_b128 v[198:201], v189 offset:33792
	ds_read_b128 v[202:205], v189 offset:34816
	ds_read_b128 v[208:211], v189 offset:35840
	ds_read_b128 v[216:219], v189 offset:36864
	ds_read_b128 v[220:223], v189 offset:37888
	ds_read_b128 v[224:227], v189 offset:38912
	ds_read_b128 v[228:231], v189 offset:39936
	global_load_lds_dwordx4 v[240:241], off
	v_lshl_add_u64 v[240:241], s[64:65], 0, v[142:143]
	s_mov_b32 m0, s58
	s_nop 0
	global_load_lds_dwordx4 v[240:241], off
	s_waitcnt vmcnt(8)
	s_waitcnt lgkmcnt(0)
	s_barrier
	s_waitcnt lgkmcnt(0)
	v_mfma_f32_16x16x32_bf16 v[124:127], v[128:131], v[194:197], v[124:127]
	v_mfma_f32_16x16x32_bf16 v[120:123], v[136:139], v[194:197], v[120:123]
	v_mfma_f32_16x16x32_bf16 v[116:119], v[128:131], v[202:205], v[116:119]
	v_mfma_f32_16x16x32_bf16 v[112:115], v[136:139], v[202:205], v[112:115]
	v_mfma_f32_16x16x32_bf16 v[108:111], v[128:131], v[216:219], v[108:111]
	v_mfma_f32_16x16x32_bf16 v[104:107], v[136:139], v[216:219], v[104:107]
	v_mfma_f32_16x16x32_bf16 v[100:103], v[128:131], v[224:227], v[100:103]
	v_mfma_f32_16x16x32_bf16 v[96:99], v[136:139], v[224:227], v[96:99]
	v_mfma_f32_16x16x32_bf16 v[124:127], v[132:135], v[198:201], v[124:127]
	v_mfma_f32_16x16x32_bf16 v[120:123], v[170:173], v[198:201], v[120:123]
	v_mfma_f32_16x16x32_bf16 v[116:119], v[132:135], v[208:211], v[116:119]
	v_mfma_f32_16x16x32_bf16 v[112:115], v[170:173], v[208:211], v[112:115]
	v_mfma_f32_16x16x32_bf16 v[108:111], v[132:135], v[220:223], v[108:111]
	v_mfma_f32_16x16x32_bf16 v[104:107], v[170:173], v[220:223], v[104:107]
	v_mfma_f32_16x16x32_bf16 v[100:103], v[132:135], v[228:231], v[100:103]
	v_mfma_f32_16x16x32_bf16 v[96:99], v[170:173], v[228:231], v[96:99]
	v_mfma_f32_16x16x32_bf16 v[60:63], v[174:177], v[194:197], v[60:63]
	v_mfma_f32_16x16x32_bf16 v[56:59], v[182:185], v[194:197], v[56:59]
	v_mfma_f32_16x16x32_bf16 v[52:55], v[174:177], v[202:205], v[52:55]
	v_mfma_f32_16x16x32_bf16 v[48:51], v[182:185], v[202:205], v[48:51]
	v_mfma_f32_16x16x32_bf16 v[44:47], v[174:177], v[216:219], v[44:47]
	v_mfma_f32_16x16x32_bf16 v[40:43], v[182:185], v[216:219], v[40:43]
	v_mfma_f32_16x16x32_bf16 v[36:39], v[174:177], v[224:227], v[36:39]
	v_mfma_f32_16x16x32_bf16 v[32:35], v[182:185], v[224:227], v[32:35]
	v_mfma_f32_16x16x32_bf16 v[60:63], v[178:181], v[198:201], v[60:63]
	v_mfma_f32_16x16x32_bf16 v[56:59], v[190:193], v[198:201], v[56:59]
	v_mfma_f32_16x16x32_bf16 v[52:55], v[178:181], v[208:211], v[52:55]
	v_mfma_f32_16x16x32_bf16 v[48:51], v[190:193], v[208:211], v[48:51]
	v_mfma_f32_16x16x32_bf16 v[44:47], v[178:181], v[220:223], v[44:47]
	v_mfma_f32_16x16x32_bf16 v[40:43], v[190:193], v[220:223], v[40:43]
	v_mfma_f32_16x16x32_bf16 v[36:39], v[178:181], v[228:231], v[36:39]
	v_mfma_f32_16x16x32_bf16 v[32:35], v[190:193], v[228:231], v[32:35]
	s_barrier
; #define PG8_STAGE(bufoff, gbase, voff) do { _Pragma("unroll") for (int _i = 0; _i < 2; ++_i) \
;         __builtin_amdgcn_global_load_lds((const unsigned*)((const char*)(gbase) + (voff)[_i]), (LAS unsigned*)(lds + (bufoff) + ldsw + _i * 8192), 16, 0, 0); } while (0)
; #define PG8_LDA(dst, b, h) do { _Pragma("unroll") for (int m = 0; m < 4; ++m) _Pragma("unroll") for (int k = 0; k < 2; ++k) dst[m][k] = *(const LAS bf16x8*)(lds + PG8_SA(b, h) + aoff + m * 2048 + k * 1024); } while (0)
; #define PG8_MMA(ai, bj, At, Bt) do { __builtin_amdgcn_s_setprio(1); _Pragma("unroll") for (int m = 0; m < 4; ++m) _Pragma("unroll") for (int n = 0; n < 2; ++n) _Pragma("unroll") for (int k = 0; k < 2; ++k) \
;         acc[ai][bj][m][n] = __builtin_amdgcn_mfma_f32_16x16x32_bf16(Bt[n][k], At[m][k], acc[ai][bj][m][n], 0, 0, 0); __builtin_amdgcn_s_setprio(0); } while (0)
; #define PG8_WAIT_V(n) asm volatile("s_waitcnt vmcnt(" #n ")" ::: "memory")
; #define PG8_WAIT_L(n) asm volatile("s_waitcnt lgkmcnt(" #n ")" ::: "memory")
; #define PG8_BAR __builtin_amdgcn_s_barrier()
; #define PG8_SCHED __builtin_amdgcn_sched_barrier(0)
; template <class Epi, bool HAS_MID>
; __device__ __forceinline__ void gemm_phase(LAS unsigned char* lds, const Gemm g, const Sched& S, const Epi& E) {
;     ...
;             PG8_LDA(At, 1, 1); PG8_STAGE(PG8_SB(1, 0), b3, voffB); PG8_STAGE(PG8_SB(1, 1), b3 + hstepB, voffB); PG8_STAGE(PG8_SA(1, 0), a3, voffA);
;             PG8_WAIT_V(8); PG8_WAIT_L(0); PG8_BAR; PG8_MMA(1, 0, At, B0); PG8_MMA(1, 1, At, B1); PG8_BAR; PG8_SCHED;
;         }
;         if (wr == 0) PG8_BAR;
	s_add_i32 s30, s30, s52
	v_lshl_add_u64 v[232:233], v[232:233], 0, s[38:39]
	s_mov_b32 m0, s30
	ds_read_b128 v[194:197], v189 offset:49152
	ds_read_b128 v[198:201], v189 offset:50176
	ds_read_b128 v[202:205], v189 offset:51200
	ds_read_b128 v[208:211], v189 offset:52224
	ds_read_b128 v[216:219], v189 offset:53248
	ds_read_b128 v[220:223], v189 offset:54272
	ds_read_b128 v[224:227], v189 offset:55296
	ds_read_b128 v[228:231], v189 offset:56320
	global_load_lds_dwordx4 v[232:233], off
	s_add_i32 m0, s30, 0x2000
	s_add_u32 s64, s76, 0x160080
	v_lshl_add_u64 v[232:233], v[234:235], 0, s[38:39]
	s_addc_u32 s65, s77, 0
	s_add_i32 s30, s36, s52
	global_load_lds_dwordx4 v[232:233], off
	v_lshl_add_u64 v[232:233], s[64:65], 0, v[160:161]
	s_mov_b32 m0, s30
	s_nop 0
	global_load_lds_dwordx4 v[232:233], off
	v_lshl_add_u64 v[232:233], s[64:65], 0, v[144:145]
	s_add_i32 m0, s30, 0x2000
	s_nop 0
	global_load_lds_dwordx4 v[232:233], off
	v_lshl_add_u64 v[232:233], v[236:237], 0, s[38:39]
	s_mov_b32 m0, s61
	s_nop 0
	global_load_lds_dwordx4 v[232:233], off
	v_lshl_add_u64 v[232:233], v[238:239], 0, s[38:39]
	s_mov_b32 m0, s80
	s_nop 0
	global_load_lds_dwordx4 v[232:233], off
	s_waitcnt vmcnt(8)
	s_waitcnt lgkmcnt(0)
	s_barrier
	s_waitcnt lgkmcnt(0)
	v_mfma_f32_16x16x32_bf16 v[92:95], v[128:131], v[194:197], v[92:95]
	v_mfma_f32_16x16x32_bf16 v[88:91], v[136:139], v[194:197], v[88:91]
	v_mfma_f32_16x16x32_bf16 v[84:87], v[128:131], v[202:205], v[84:87]
	v_mfma_f32_16x16x32_bf16 v[80:83], v[136:139], v[202:205], v[80:83]
	v_mfma_f32_16x16x32_bf16 v[76:79], v[128:131], v[216:219], v[76:79]
	v_mfma_f32_16x16x32_bf16 v[72:75], v[136:139], v[216:219], v[72:75]
	v_mfma_f32_16x16x32_bf16 v[68:71], v[128:131], v[224:227], v[68:71]
	v_mfma_f32_16x16x32_bf16 v[64:67], v[136:139], v[224:227], v[64:67]
	v_mfma_f32_16x16x32_bf16 v[92:95], v[132:135], v[198:201], v[92:95]
	v_mfma_f32_16x16x32_bf16 v[88:91], v[170:173], v[198:201], v[88:91]
	v_mfma_f32_16x16x32_bf16 v[84:87], v[132:135], v[208:211], v[84:87]
	v_mfma_f32_16x16x32_bf16 v[80:83], v[170:173], v[208:211], v[80:83]
	v_mfma_f32_16x16x32_bf16 v[76:79], v[132:135], v[220:223], v[76:79]
	v_mfma_f32_16x16x32_bf16 v[72:75], v[170:173], v[220:223], v[72:75]
	v_mfma_f32_16x16x32_bf16 v[68:71], v[132:135], v[228:231], v[68:71]
	v_mfma_f32_16x16x32_bf16 v[64:67], v[170:173], v[228:231], v[64:67]
	v_mfma_f32_16x16x32_bf16 v[28:31], v[174:177], v[194:197], v[28:31]
	v_mfma_f32_16x16x32_bf16 v[24:27], v[182:185], v[194:197], v[24:27]
	v_mfma_f32_16x16x32_bf16 v[20:23], v[174:177], v[202:205], v[20:23]
	v_mfma_f32_16x16x32_bf16 v[16:19], v[182:185], v[202:205], v[16:19]
	v_mfma_f32_16x16x32_bf16 v[12:15], v[174:177], v[216:219], v[12:15]
	v_mfma_f32_16x16x32_bf16 v[8:11], v[182:185], v[216:219], v[8:11]
	v_mfma_f32_16x16x32_bf16 v[4:7], v[174:177], v[224:227], v[4:7]
	v_mfma_f32_16x16x32_bf16 v[0:3], v[182:185], v[224:227], v[0:3]
	v_mfma_f32_16x16x32_bf16 v[28:31], v[178:181], v[198:201], v[28:31]
	v_mfma_f32_16x16x32_bf16 v[24:27], v[190:193], v[198:201], v[24:27]
	v_mfma_f32_16x16x32_bf16 v[20:23], v[178:181], v[208:211], v[20:23]
	v_mfma_f32_16x16x32_bf16 v[16:19], v[190:193], v[208:211], v[16:19]
	v_mfma_f32_16x16x32_bf16 v[12:15], v[178:181], v[220:223], v[12:15]
	v_mfma_f32_16x16x32_bf16 v[8:11], v[190:193], v[220:223], v[8:11]
	v_mfma_f32_16x16x32_bf16 v[4:7], v[178:181], v[228:231], v[4:7]
	v_mfma_f32_16x16x32_bf16 v[0:3], v[190:193], v[228:231], v[0:3]
	s_barrier
	s_add_i32 s30, s94, 2
	s_add_u32 s27, s27, 0x100
	s_addc_u32 s89, s89, 0
	s_cmp_ge_i32 s94, s84
	s_mov_b64 s[74:75], s[4:5]
	s_mov_b32 s94, s30
	s_cbranch_scc0 .LBB0_3020
	s_and_b64 vcc, exec, s[20:21]
	s_cbranch_vccz .LBB0_3023
	s_barrier
